# speedup vs baseline: 1.0107x; 1.0020x over previous
; __device__ __forceinline__ int tid_fresh() { int t = (int)threadIdx.x; asm volatile("" : "+v"(t)); return t; }
; __device__ __forceinline__ void conv_phase(const bf16_t* Z, bf16_t* UA, const float* cw, const float* cb, int nrows, int rowoff) {
;     const int gtid = blockIdx.x * 512 + tid_fresh(), NT = gridDim.x * 512; const int total = (nrows / 16) * 352;
;     for (int idx = gtid; idx < total; idx += NT) {
;         const int cgp = idx % 352, rb = idx / 352, c0 = cgp * 8, r0 = rb * 16, grow0 = rowoff + r0;
;         const int seg = grow0 < MLAT ? SEQ : CTXL; const bool has_left = (grow0 & (seg - 1)) != 0, has_right = ((grow0 + 16) & (seg - 1)) != 0;
;         float wa[3][8], wg[3][8], ba[8], bg[8];
; #pragma unroll
;         for (int j = 0; j < 3; ++j)
; #pragma unroll
;             for (int h = 0; h < 2; ++h) { const f32x4 x = *(const f32x4*)(cw + j * FFN2 + c0 + 4 * h), y = *(const f32x4*)(cw + j * FFN2 + FFN + c0 + 4 * h);
; #pragma unroll
;                 for (int e = 0; e < 4; ++e) { wa[j][4 * h + e] = x[e]; wg[j][4 * h + e] = y[e]; } }
; #pragma unroll
;         for (int h = 0; h < 2; ++h) { const f32x4 x = *(const f32x4*)(cb + c0 + 4 * h), y = *(const f32x4*)(cb + FFN + c0 + 4 * h);
; #pragma unroll
;             for (int e = 0; e < 4; ++e) { ba[4 * h + e] = x[e]; bg[4 * h + e] = y[e]; } }
;         const bf16_t* zp = Z + (size_t)r0 * FFN2 + c0; const u32x4 zero = (u32x4){0u, 0u, 0u, 0u};
;         u32x4 pa = zero, pg = zero; if (has_left) { pa = *(const u32x4*)(zp - FFN2); pg = *(const u32x4*)(zp - FFN2 + FFN); }
;         u32x4 ca = *(const u32x4*)(zp), cgv = *(const u32x4*)(zp + FFN);
; #pragma unroll 4
;         for (int rr = 0; rr < 16; ++rr) {
;             u32x4 na = zero, ng = zero; if (rr < 15 || has_right) { na = *(const u32x4*)(zp + (size_t)(rr + 1) * FFN2); ng = *(const u32x4*)(zp + (size_t)(rr + 1) * FFN2 + FFN); }
.LBB0_459:
	s_or_b64 exec, exec, s[2:3]
	v_mov_b32_e32 v1, v204
	v_readlane_b32 s2, v255, 17
	s_lshr_b32 s12, s45, 4
	s_waitcnt lgkmcnt(0)
	s_barrier
	s_mulk_i32 s12, 0x160
	s_xor_b64 s[88:89], s[40:41], -1
	s_lshr_b32 s13, s45, 4
	v_readlane_b32 s2, v254, 21
	v_readlane_b32 s3, v254, 22
	v_readlane_b32 s98, v255, 17
	s_load_dwordx2 s[38:39], s[2:3], 0x98
	s_load_dwordx2 s[40:41], s[2:3], 0xa0
	s_add_u32 s36, s54, 0x23a00000
	s_addc_u32 s37, s55, 0
	v_mov_b32_e32 v180, 0xbfb8aa3b
	v_mov_b32_e32 v181, 0xbfb8aa3b
	v_mov_b32_e32 v144, 1.0
	v_mov_b32_e32 v145, 1.0
	v_add_u32_e32 v1, s98, v204
	s_mov_b32 s99, 0x2e8ba2e9
	v_mul_hi_u32 v2, v1, s99
	v_lshrrev_b32_e32 v2, 6, v2
	v_mul_u32_u24_e32 v3, 0x160, v2
	v_sub_u32_e32 v3, v1, v3
	v_lshlrev_b32_e32 v4, 5, v3
	v_mul_u32_u24_e32 v5, 180224, v2
	v_lshl_add_u32 v5, v3, 4, v5
	v_mul_u32_u24_e32 v6, 90112, v2
	v_lshl_add_u32 v6, v3, 4, v6
	s_lshr_b32 s99, s43, 4
	v_add_u32_e32 v7, s99, v2
	s_waitcnt lgkmcnt(0)
	s_sub_u32 s2, s64, 0x4000
	s_subb_u32 s3, s65, 0
	s_mov_b32 s98, 0
	s_mov_b32 s99, 0xffff0000
	global_load_dwordx4 v[152:155], v4, s[38:39]
	global_load_dwordx4 v[156:159], v4, s[38:39] offset:16
	v_add_u32_e32 v10, 11264, v4
	global_load_dwordx4 v[212:215], v10, s[38:39]
	global_load_dwordx4 v[216:219], v10, s[38:39] offset:16
	v_add_u32_e32 v11, 22528, v4
	global_load_dwordx4 v[160:163], v11, s[38:39]
	global_load_dwordx4 v[164:167], v11, s[38:39] offset:16
	v_add_u32_e32 v10, 33792, v4
	global_load_dwordx4 v[220:223], v10, s[38:39]
	global_load_dwordx4 v[224:227], v10, s[38:39] offset:16
	v_add_u32_e32 v11, 45056, v4
	global_load_dwordx4 v[168:171], v11, s[38:39]
	global_load_dwordx4 v[172:175], v11, s[38:39] offset:16
	v_add_u32_e32 v10, 56320, v4
	global_load_dwordx4 v[228:231], v10, s[38:39]
	global_load_dwordx4 v[232:235], v10, s[38:39] offset:16
	global_load_dwordx4 v[236:239], v4, s[40:41]
	global_load_dwordx4 v[240:243], v4, s[40:41] offset:16
	v_add_u32_e32 v11, 11264, v4
	global_load_dwordx4 v[244:247], v11, s[40:41]
	global_load_dwordx4 v[248:251], v11, s[40:41] offset:16
	v_add_u32_e32 v10, 7936, v5
	global_load_dwordx4 v[64:67], v10, s[2:3] offset:-2816 nt
	global_load_dwordx4 v[68:71], v10, s[2:3] offset:2816 nt
	global_load_dword v252, v4, s[40:41]
	v_add_u32_e32 v11, 19200, v5
	global_load_dwordx4 v[72:75], v11, s[2:3] offset:-2816 nt
	global_load_dwordx4 v[76:79], v11, s[2:3] offset:2816 nt
	global_load_dword v252, v4, s[40:41]
	v_add_u32_e32 v10, 30464, v5
	global_load_dwordx4 v[80:83], v10, s[2:3] offset:-2816 nt
	global_load_dwordx4 v[84:87], v10, s[2:3] offset:2816 nt
	global_load_dword v252, v4, s[40:41]
	v_add_u32_e32 v11, 41728, v5
	global_load_dwordx4 v[88:91], v11, s[2:3] offset:-2816 nt
	global_load_dwordx4 v[92:95], v11, s[2:3] offset:2816 nt
	global_load_dword v252, v4, s[40:41]
	v_add_u32_e32 v10, 52992, v5
	global_load_dwordx4 v[96:99], v10, s[2:3] offset:-2816 nt
	global_load_dwordx4 v[100:103], v10, s[2:3] offset:2816 nt
	global_load_dword v252, v4, s[40:41]
	v_add_u32_e32 v11, 64256, v5
	global_load_dwordx4 v[104:107], v11, s[2:3] offset:-2816 nt
	global_load_dwordx4 v[108:111], v11, s[2:3] offset:2816 nt
	global_load_dword v252, v4, s[40:41]
	v_add_u32_e32 v10, 75520, v5
	global_load_dwordx4 v[112:115], v10, s[2:3] offset:-2816 nt
	global_load_dwordx4 v[116:119], v10, s[2:3] offset:2816 nt
	global_load_dword v252, v4, s[40:41]
	v_add_u32_e32 v11, 86784, v5
	global_load_dwordx4 v[120:123], v11, s[2:3] offset:-2816 nt
	global_load_dwordx4 v[124:127], v11, s[2:3] offset:2816 nt
	global_load_dword v252, v4, s[40:41]
	v_add_u32_e32 v10, 98048, v5
	global_load_dwordx4 v[128:131], v10, s[2:3] offset:-2816 nt
	global_load_dwordx4 v[132:135], v10, s[2:3] offset:2816 nt
	global_load_dword v252, v4, s[40:41]
.Lconv_item_l0:
	v_cmp_gt_u32_e32 vcc, s13, v2
	s_nop 4
	s_cbranch_vccz .Lconv_done_l0
	v_mov_b32_e32 v9, 0x1ff
	v_cmp_gt_u32_e32 vcc, 0x1000, v7
	s_nop 1
	v_cndmask_b32_e32 v8, 15, v9, vcc
	v_and_b32_e32 v9, v7, v8
	v_cmp_ne_u32_e64 s[60:61], 0, v9
	v_add_u32_e32 v9, 1, v7
	v_and_b32_e32 v9, v9, v8
	v_cmp_ne_u32_e64 s[100:101], 0, v9
	s_waitcnt vmcnt(25)
	v_cndmask_b32_e64 v64, 0, v64, s[60:61]
	v_cndmask_b32_e64 v65, 0, v65, s[60:61]
	v_cndmask_b32_e64 v66, 0, v66, s[60:61]
	v_cndmask_b32_e64 v67, 0, v67, s[60:61]
	v_cndmask_b32_e64 v68, 0, v68, s[60:61]
	v_cndmask_b32_e64 v69, 0, v69, s[60:61]
	v_cndmask_b32_e64 v70, 0, v70, s[60:61]
	v_cndmask_b32_e64 v71, 0, v71, s[60:61]
	v_lshlrev_b32_e32 v16, 16, v64
	v_and_b32_e32 v17, s99, v64
	v_lshlrev_b32_e32 v18, 16, v65
	v_and_b32_e32 v19, s99, v65
	v_lshlrev_b32_e32 v20, 16, v66
	v_and_b32_e32 v21, s99, v66
	v_lshlrev_b32_e32 v22, 16, v67
	v_and_b32_e32 v23, s99, v67
	v_lshlrev_b32_e32 v24, 16, v68
	v_and_b32_e32 v25, s99, v68
	v_lshlrev_b32_e32 v26, 16, v69
	v_and_b32_e32 v27, s99, v69
	v_lshlrev_b32_e32 v28, 16, v70
	v_and_b32_e32 v29, s99, v70
	v_lshlrev_b32_e32 v30, 16, v71
	v_and_b32_e32 v31, s99, v71
	v_add_u32_e32 v11, 109312, v5
	global_load_dwordx4 v[64:67], v11, s[2:3] offset:-2816 nt
	global_load_dwordx4 v[68:71], v11, s[2:3] offset:2816 nt
	s_waitcnt vmcnt(24)
	v_lshlrev_b32_e32 v32, 16, v72
	v_and_b32_e32 v33, s99, v72
	v_lshlrev_b32_e32 v34, 16, v73
	v_and_b32_e32 v35, s99, v73
	v_lshlrev_b32_e32 v36, 16, v74
	v_and_b32_e32 v37, s99, v74
	v_lshlrev_b32_e32 v38, 16, v75
	v_and_b32_e32 v39, s99, v75
	v_lshlrev_b32_e32 v40, 16, v76
	v_and_b32_e32 v41, s99, v76
	v_lshlrev_b32_e32 v42, 16, v77
	v_and_b32_e32 v43, s99, v77
	v_lshlrev_b32_e32 v44, 16, v78
	v_and_b32_e32 v45, s99, v78
	v_lshlrev_b32_e32 v46, 16, v79
	v_and_b32_e32 v47, s99, v79
	v_add_u32_e32 v10, 120576, v5
	global_load_dwordx4 v[72:75], v10, s[2:3] offset:-2816 nt
	global_load_dwordx4 v[76:79], v10, s[2:3] offset:2816 nt
	s_waitcnt vmcnt(23)
; __device__ __forceinline__ unsigned cvt_pk_bf16(float lo, float hi) { unsigned r; asm volatile("v_cvt_pk_bf16_f32 %0, %1, %2" : "=v"(r) : "v"(lo), "v"(hi)); return r; }
; __device__ __forceinline__ float silu_f(float x) { return x * __builtin_amdgcn_rcpf(1.0f + __builtin_amdgcn_exp2f(-LOG2E * x)); }
; __device__ __forceinline__ float bflo(unsigned w) { return __uint_as_float(w << 16); }
; __device__ __forceinline__ float bfhi(unsigned w) { return __uint_as_float(w & 0xffff0000u); }
; __device__ __forceinline__ void conv_phase(const bf16_t* Z, bf16_t* UA, const float* cw, const float* cb, int nrows, int rowoff) {
;     ...
;         for (int rr = 0; rr < 16; ++rr) {
;             u32x4 na = zero, ng = zero; if (rr < 15 || has_right) { na = *(const u32x4*)(zp + (size_t)(rr + 1) * FFN2); ng = *(const u32x4*)(zp + (size_t)(rr + 1) * FFN2 + FFN); }
;             u32x4 o;
; #pragma unroll
;             for (int e2 = 0; e2 < 4; ++e2) {
;                 const float a0 = bflo(pa[e2]) * wa[0][2 * e2] + bflo(ca[e2]) * wa[1][2 * e2] + bflo(na[e2]) * wa[2][2 * e2] + ba[2 * e2];
;                 const float a1 = bfhi(pa[e2]) * wa[0][2 * e2 + 1] + bfhi(ca[e2]) * wa[1][2 * e2 + 1] + bfhi(na[e2]) * wa[2][2 * e2 + 1] + ba[2 * e2 + 1];
;                 const float g0 = bflo(pg[e2]) * wg[0][2 * e2] + bflo(cgv[e2]) * wg[1][2 * e2] + bflo(ng[e2]) * wg[2][2 * e2] + bg[2 * e2];
;                 const float g1 = bfhi(pg[e2]) * wg[0][2 * e2 + 1] + bfhi(cgv[e2]) * wg[1][2 * e2 + 1] + bfhi(ng[e2]) * wg[2][2 * e2 + 1] + bg[2 * e2 + 1];
;                 o[e2] = cvt_pk_bf16(silu_f(a0) * g0, silu_f(a1) * g1); }
;             *(u32x4*)(UA + (size_t)(r0 + rr) * FFN + c0) = o;
;             pa = ca; pg = cgv; ca = na; cgv = ng;
	v_lshlrev_b32_e32 v48, 16, v80
	v_and_b32_e32 v49, s99, v80
	v_lshlrev_b32_e32 v50, 16, v81
	v_and_b32_e32 v51, s99, v81
	v_lshlrev_b32_e32 v52, 16, v82
	v_and_b32_e32 v53, s99, v82
	v_lshlrev_b32_e32 v54, 16, v83
	v_and_b32_e32 v55, s99, v83
	v_lshlrev_b32_e32 v56, 16, v84
	v_and_b32_e32 v57, s99, v84
	v_lshlrev_b32_e32 v58, 16, v85
	v_and_b32_e32 v59, s99, v85
	v_lshlrev_b32_e32 v60, 16, v86
	v_and_b32_e32 v61, s99, v86
	v_lshlrev_b32_e32 v62, 16, v87
	v_and_b32_e32 v63, s99, v87
	v_add_u32_e32 v11, 131840, v5
	global_load_dwordx4 v[80:83], v11, s[2:3] offset:-2816 nt
	global_load_dwordx4 v[84:87], v11, s[2:3] offset:2816 nt
	v_pk_fma_f32 v[136:137], v[16:17], v[152:153], v[236:237]
	v_pk_fma_f32 v[196:197], v[24:25], v[212:213], v[244:245]
	v_pk_fma_f32 v[138:139], v[18:19], v[154:155], v[238:239]
	v_pk_fma_f32 v[198:199], v[26:27], v[214:215], v[246:247]
	v_pk_fma_f32 v[140:141], v[20:21], v[156:157], v[240:241]
	v_pk_fma_f32 v[200:201], v[28:29], v[216:217], v[248:249]
	v_pk_fma_f32 v[142:143], v[22:23], v[158:159], v[242:243]
	v_pk_fma_f32 v[202:203], v[30:31], v[218:219], v[250:251]
	v_pk_fma_f32 v[136:137], v[32:33], v[160:161], v[136:137]
	v_pk_fma_f32 v[196:197], v[40:41], v[220:221], v[196:197]
	v_pk_fma_f32 v[138:139], v[34:35], v[162:163], v[138:139]
	v_pk_fma_f32 v[198:199], v[42:43], v[222:223], v[198:199]
	v_pk_fma_f32 v[140:141], v[36:37], v[164:165], v[140:141]
	v_pk_fma_f32 v[200:201], v[44:45], v[224:225], v[200:201]
	v_pk_fma_f32 v[142:143], v[38:39], v[166:167], v[142:143]
	v_pk_fma_f32 v[202:203], v[46:47], v[226:227], v[202:203]
	v_pk_fma_f32 v[136:137], v[48:49], v[168:169], v[136:137]
	v_pk_fma_f32 v[196:197], v[56:57], v[228:229], v[196:197]
	v_pk_fma_f32 v[138:139], v[50:51], v[170:171], v[138:139]
	v_pk_fma_f32 v[198:199], v[58:59], v[230:231], v[198:199]
	v_pk_fma_f32 v[140:141], v[52:53], v[172:173], v[140:141]
	v_pk_fma_f32 v[200:201], v[60:61], v[232:233], v[200:201]
	v_pk_fma_f32 v[142:143], v[54:55], v[174:175], v[142:143]
	v_pk_fma_f32 v[202:203], v[62:63], v[234:235], v[202:203]
	v_pk_mul_f32 v[184:185], v[136:137], v[180:181]
	v_pk_mul_f32 v[186:187], v[138:139], v[180:181]
	v_pk_mul_f32 v[188:189], v[140:141], v[180:181]
	v_pk_mul_f32 v[190:191], v[142:143], v[180:181]
	v_exp_f32_e32 v184, v184
	v_exp_f32_e32 v185, v185
	v_exp_f32_e32 v186, v186
	v_exp_f32_e32 v187, v187
	v_exp_f32_e32 v188, v188
	v_exp_f32_e32 v189, v189
	v_exp_f32_e32 v190, v190
	v_exp_f32_e32 v191, v191
	s_nop 0
	v_pk_add_f32 v[184:185], v[184:185], v[144:145]
	v_pk_add_f32 v[186:187], v[186:187], v[144:145]
	v_pk_add_f32 v[188:189], v[188:189], v[144:145]
	v_pk_add_f32 v[190:191], v[190:191], v[144:145]
	v_rcp_f32_e32 v184, v184
	v_rcp_f32_e32 v185, v185
	v_rcp_f32_e32 v186, v186
	v_rcp_f32_e32 v187, v187
	v_rcp_f32_e32 v188, v188
	v_rcp_f32_e32 v189, v189
	v_rcp_f32_e32 v190, v190
	v_rcp_f32_e32 v191, v191
	s_nop 0
	v_pk_mul_f32 v[136:137], v[136:137], v[184:185]
	v_pk_mul_f32 v[138:139], v[138:139], v[186:187]
	v_pk_mul_f32 v[140:141], v[140:141], v[188:189]
	v_pk_mul_f32 v[142:143], v[142:143], v[190:191]
	v_pk_mul_f32 v[136:137], v[136:137], v[196:197]
	v_pk_mul_f32 v[138:139], v[138:139], v[198:199]
	v_pk_mul_f32 v[140:141], v[140:141], v[200:201]
	v_pk_mul_f32 v[142:143], v[142:143], v[202:203]
	v_cvt_pk_bf16_f32 v12, v136, v137
	v_cvt_pk_bf16_f32 v13, v138, v139
	v_cvt_pk_bf16_f32 v14, v140, v141
	v_cvt_pk_bf16_f32 v15, v142, v143
	global_store_dwordx4 v6, v[12:15], s[36:37]
	v_add_u32_e32 v6, 5632, v6
	s_waitcnt vmcnt(23)
	v_lshlrev_b32_e32 v16, 16, v88
	v_and_b32_e32 v17, s99, v88
	v_lshlrev_b32_e32 v18, 16, v89
	v_and_b32_e32 v19, s99, v89
	v_lshlrev_b32_e32 v20, 16, v90
	v_and_b32_e32 v21, s99, v90
	v_lshlrev_b32_e32 v22, 16, v91
	v_and_b32_e32 v23, s99, v91
	v_lshlrev_b32_e32 v24, 16, v92
	v_and_b32_e32 v25, s99, v92
	v_lshlrev_b32_e32 v26, 16, v93
	v_and_b32_e32 v27, s99, v93
	v_lshlrev_b32_e32 v28, 16, v94
	v_and_b32_e32 v29, s99, v94
	v_lshlrev_b32_e32 v30, 16, v95
	v_and_b32_e32 v31, s99, v95
	v_add_u32_e32 v10, 143104, v5
	global_load_dwordx4 v[88:91], v10, s[2:3] offset:-2816 nt
	global_load_dwordx4 v[92:95], v10, s[2:3] offset:2816 nt
	v_pk_fma_f32 v[136:137], v[32:33], v[152:153], v[236:237]
	v_pk_fma_f32 v[196:197], v[40:41], v[212:213], v[244:245]
	v_pk_fma_f32 v[138:139], v[34:35], v[154:155], v[238:239]
	v_pk_fma_f32 v[198:199], v[42:43], v[214:215], v[246:247]
	v_pk_fma_f32 v[140:141], v[36:37], v[156:157], v[240:241]
	v_pk_fma_f32 v[200:201], v[44:45], v[216:217], v[248:249]
	v_pk_fma_f32 v[142:143], v[38:39], v[158:159], v[242:243]
	v_pk_fma_f32 v[202:203], v[46:47], v[218:219], v[250:251]
	v_pk_fma_f32 v[136:137], v[48:49], v[160:161], v[136:137]
	v_pk_fma_f32 v[196:197], v[56:57], v[220:221], v[196:197]
	v_pk_fma_f32 v[138:139], v[50:51], v[162:163], v[138:139]
	v_pk_fma_f32 v[198:199], v[58:59], v[222:223], v[198:199]
	v_pk_fma_f32 v[140:141], v[52:53], v[164:165], v[140:141]
	v_pk_fma_f32 v[200:201], v[60:61], v[224:225], v[200:201]
	v_pk_fma_f32 v[142:143], v[54:55], v[166:167], v[142:143]
	v_pk_fma_f32 v[202:203], v[62:63], v[226:227], v[202:203]
	v_pk_fma_f32 v[136:137], v[16:17], v[168:169], v[136:137]
	v_pk_fma_f32 v[196:197], v[24:25], v[228:229], v[196:197]
	v_pk_fma_f32 v[138:139], v[18:19], v[170:171], v[138:139]
	v_pk_fma_f32 v[198:199], v[26:27], v[230:231], v[198:199]
	v_pk_fma_f32 v[140:141], v[20:21], v[172:173], v[140:141]
	v_pk_fma_f32 v[200:201], v[28:29], v[232:233], v[200:201]
	v_pk_fma_f32 v[142:143], v[22:23], v[174:175], v[142:143]
	v_pk_fma_f32 v[202:203], v[30:31], v[234:235], v[202:203]
	v_pk_mul_f32 v[184:185], v[136:137], v[180:181]
	v_pk_mul_f32 v[186:187], v[138:139], v[180:181]
	v_pk_mul_f32 v[188:189], v[140:141], v[180:181]
	v_pk_mul_f32 v[190:191], v[142:143], v[180:181]
	v_exp_f32_e32 v184, v184
	v_exp_f32_e32 v185, v185
	v_exp_f32_e32 v186, v186
	v_exp_f32_e32 v187, v187
	v_exp_f32_e32 v188, v188
	v_exp_f32_e32 v189, v189
	v_exp_f32_e32 v190, v190
	v_exp_f32_e32 v191, v191
	s_nop 0
	v_pk_add_f32 v[184:185], v[184:185], v[144:145]
	v_pk_add_f32 v[186:187], v[186:187], v[144:145]
	v_pk_add_f32 v[188:189], v[188:189], v[144:145]
	v_pk_add_f32 v[190:191], v[190:191], v[144:145]
	v_rcp_f32_e32 v184, v184
	v_rcp_f32_e32 v185, v185
	v_rcp_f32_e32 v186, v186
	v_rcp_f32_e32 v187, v187
	v_rcp_f32_e32 v188, v188
	v_rcp_f32_e32 v189, v189
	v_rcp_f32_e32 v190, v190
	v_rcp_f32_e32 v191, v191
	s_nop 0
	v_pk_mul_f32 v[136:137], v[136:137], v[184:185]
	v_pk_mul_f32 v[138:139], v[138:139], v[186:187]
	v_pk_mul_f32 v[140:141], v[140:141], v[188:189]
	v_pk_mul_f32 v[142:143], v[142:143], v[190:191]
	v_pk_mul_f32 v[136:137], v[136:137], v[196:197]
	v_pk_mul_f32 v[138:139], v[138:139], v[198:199]
	v_pk_mul_f32 v[140:141], v[140:141], v[200:201]
	v_pk_mul_f32 v[142:143], v[142:143], v[202:203]
	v_cvt_pk_bf16_f32 v12, v136, v137
	v_cvt_pk_bf16_f32 v13, v138, v139
	v_cvt_pk_bf16_f32 v14, v140, v141
	v_cvt_pk_bf16_f32 v15, v142, v143
	global_store_dwordx4 v6, v[12:15], s[36:37]
	v_add_u32_e32 v6, 5632, v6
	s_waitcnt vmcnt(23)
; __device__ __forceinline__ unsigned cvt_pk_bf16(float lo, float hi) { unsigned r; asm volatile("v_cvt_pk_bf16_f32 %0, %1, %2" : "=v"(r) : "v"(lo), "v"(hi)); return r; }
; __device__ __forceinline__ float silu_f(float x) { return x * __builtin_amdgcn_rcpf(1.0f + __builtin_amdgcn_exp2f(-LOG2E * x)); }
; __device__ __forceinline__ float bflo(unsigned w) { return __uint_as_float(w << 16); }
; __device__ __forceinline__ float bfhi(unsigned w) { return __uint_as_float(w & 0xffff0000u); }
; __device__ __forceinline__ void conv_phase(const bf16_t* Z, bf16_t* UA, const float* cw, const float* cb, int nrows, int rowoff) {
;     ...
;         for (int rr = 0; rr < 16; ++rr) {
;             u32x4 na = zero, ng = zero; if (rr < 15 || has_right) { na = *(const u32x4*)(zp + (size_t)(rr + 1) * FFN2); ng = *(const u32x4*)(zp + (size_t)(rr + 1) * FFN2 + FFN); }
;             u32x4 o;
; #pragma unroll
;             for (int e2 = 0; e2 < 4; ++e2) {
;                 const float a0 = bflo(pa[e2]) * wa[0][2 * e2] + bflo(ca[e2]) * wa[1][2 * e2] + bflo(na[e2]) * wa[2][2 * e2] + ba[2 * e2];
;                 const float a1 = bfhi(pa[e2]) * wa[0][2 * e2 + 1] + bfhi(ca[e2]) * wa[1][2 * e2 + 1] + bfhi(na[e2]) * wa[2][2 * e2 + 1] + ba[2 * e2 + 1];
;                 const float g0 = bflo(pg[e2]) * wg[0][2 * e2] + bflo(cgv[e2]) * wg[1][2 * e2] + bflo(ng[e2]) * wg[2][2 * e2] + bg[2 * e2];
;                 const float g1 = bfhi(pg[e2]) * wg[0][2 * e2 + 1] + bfhi(cgv[e2]) * wg[1][2 * e2 + 1] + bfhi(ng[e2]) * wg[2][2 * e2 + 1] + bg[2 * e2 + 1];
;                 o[e2] = cvt_pk_bf16(silu_f(a0) * g0, silu_f(a1) * g1); }
;             *(u32x4*)(UA + (size_t)(r0 + rr) * FFN + c0) = o;
;             pa = ca; pg = cgv; ca = na; cgv = ng;
	v_lshlrev_b32_e32 v32, 16, v96
	v_and_b32_e32 v33, s99, v96
	v_lshlrev_b32_e32 v34, 16, v97
	v_and_b32_e32 v35, s99, v97
	v_lshlrev_b32_e32 v36, 16, v98
	v_and_b32_e32 v37, s99, v98
	v_lshlrev_b32_e32 v38, 16, v99
	v_and_b32_e32 v39, s99, v99
	v_lshlrev_b32_e32 v40, 16, v100
	v_and_b32_e32 v41, s99, v100
	v_lshlrev_b32_e32 v42, 16, v101
	v_and_b32_e32 v43, s99, v101
	v_lshlrev_b32_e32 v44, 16, v102
	v_and_b32_e32 v45, s99, v102
	v_lshlrev_b32_e32 v46, 16, v103
	v_and_b32_e32 v47, s99, v103
	v_add_u32_e32 v11, 154368, v5
	global_load_dwordx4 v[96:99], v11, s[2:3] offset:-2816 nt
	global_load_dwordx4 v[100:103], v11, s[2:3] offset:2816 nt
	v_pk_fma_f32 v[136:137], v[48:49], v[152:153], v[236:237]
	v_pk_fma_f32 v[196:197], v[56:57], v[212:213], v[244:245]
	v_pk_fma_f32 v[138:139], v[50:51], v[154:155], v[238:239]
	v_pk_fma_f32 v[198:199], v[58:59], v[214:215], v[246:247]
	v_pk_fma_f32 v[140:141], v[52:53], v[156:157], v[240:241]
	v_pk_fma_f32 v[200:201], v[60:61], v[216:217], v[248:249]
	v_pk_fma_f32 v[142:143], v[54:55], v[158:159], v[242:243]
	v_pk_fma_f32 v[202:203], v[62:63], v[218:219], v[250:251]
	v_pk_fma_f32 v[136:137], v[16:17], v[160:161], v[136:137]
	v_pk_fma_f32 v[196:197], v[24:25], v[220:221], v[196:197]
	v_pk_fma_f32 v[138:139], v[18:19], v[162:163], v[138:139]
	v_pk_fma_f32 v[198:199], v[26:27], v[222:223], v[198:199]
	v_pk_fma_f32 v[140:141], v[20:21], v[164:165], v[140:141]
	v_pk_fma_f32 v[200:201], v[28:29], v[224:225], v[200:201]
	v_pk_fma_f32 v[142:143], v[22:23], v[166:167], v[142:143]
	v_pk_fma_f32 v[202:203], v[30:31], v[226:227], v[202:203]
	v_pk_fma_f32 v[136:137], v[32:33], v[168:169], v[136:137]
	v_pk_fma_f32 v[196:197], v[40:41], v[228:229], v[196:197]
	v_pk_fma_f32 v[138:139], v[34:35], v[170:171], v[138:139]
	v_pk_fma_f32 v[198:199], v[42:43], v[230:231], v[198:199]
	v_pk_fma_f32 v[140:141], v[36:37], v[172:173], v[140:141]
	v_pk_fma_f32 v[200:201], v[44:45], v[232:233], v[200:201]
	v_pk_fma_f32 v[142:143], v[38:39], v[174:175], v[142:143]
	v_pk_fma_f32 v[202:203], v[46:47], v[234:235], v[202:203]
	v_pk_mul_f32 v[184:185], v[136:137], v[180:181]
	v_pk_mul_f32 v[186:187], v[138:139], v[180:181]
	v_pk_mul_f32 v[188:189], v[140:141], v[180:181]
	v_pk_mul_f32 v[190:191], v[142:143], v[180:181]
	v_exp_f32_e32 v184, v184
	v_exp_f32_e32 v185, v185
	v_exp_f32_e32 v186, v186
	v_exp_f32_e32 v187, v187
	v_exp_f32_e32 v188, v188
	v_exp_f32_e32 v189, v189
	v_exp_f32_e32 v190, v190
	v_exp_f32_e32 v191, v191
	s_nop 0
	v_pk_add_f32 v[184:185], v[184:185], v[144:145]
	v_pk_add_f32 v[186:187], v[186:187], v[144:145]
	v_pk_add_f32 v[188:189], v[188:189], v[144:145]
	v_pk_add_f32 v[190:191], v[190:191], v[144:145]
	v_rcp_f32_e32 v184, v184
	v_rcp_f32_e32 v185, v185
	v_rcp_f32_e32 v186, v186
	v_rcp_f32_e32 v187, v187
	v_rcp_f32_e32 v188, v188
	v_rcp_f32_e32 v189, v189
	v_rcp_f32_e32 v190, v190
	v_rcp_f32_e32 v191, v191
	s_nop 0
	v_pk_mul_f32 v[136:137], v[136:137], v[184:185]
	v_pk_mul_f32 v[138:139], v[138:139], v[186:187]
	v_pk_mul_f32 v[140:141], v[140:141], v[188:189]
	v_pk_mul_f32 v[142:143], v[142:143], v[190:191]
	v_pk_mul_f32 v[136:137], v[136:137], v[196:197]
	v_pk_mul_f32 v[138:139], v[138:139], v[198:199]
	v_pk_mul_f32 v[140:141], v[140:141], v[200:201]
	v_pk_mul_f32 v[142:143], v[142:143], v[202:203]
	v_cvt_pk_bf16_f32 v12, v136, v137
	v_cvt_pk_bf16_f32 v13, v138, v139
	v_cvt_pk_bf16_f32 v14, v140, v141
	v_cvt_pk_bf16_f32 v15, v142, v143
	global_store_dwordx4 v6, v[12:15], s[36:37]
	v_add_u32_e32 v6, 5632, v6
	s_waitcnt vmcnt(23)
	v_lshlrev_b32_e32 v48, 16, v104
	v_and_b32_e32 v49, s99, v104
	v_lshlrev_b32_e32 v50, 16, v105
	v_and_b32_e32 v51, s99, v105
	v_lshlrev_b32_e32 v52, 16, v106
	v_and_b32_e32 v53, s99, v106
	v_lshlrev_b32_e32 v54, 16, v107
	v_and_b32_e32 v55, s99, v107
	v_lshlrev_b32_e32 v56, 16, v108
	v_and_b32_e32 v57, s99, v108
	v_lshlrev_b32_e32 v58, 16, v109
	v_and_b32_e32 v59, s99, v109
	v_lshlrev_b32_e32 v60, 16, v110
	v_and_b32_e32 v61, s99, v110
	v_lshlrev_b32_e32 v62, 16, v111
	v_and_b32_e32 v63, s99, v111
	v_add_u32_e32 v10, 165632, v5
	global_load_dwordx4 v[104:107], v10, s[2:3] offset:-2816 nt
	global_load_dwordx4 v[108:111], v10, s[2:3] offset:2816 nt
	v_pk_fma_f32 v[136:137], v[16:17], v[152:153], v[236:237]
	v_pk_fma_f32 v[196:197], v[24:25], v[212:213], v[244:245]
	v_pk_fma_f32 v[138:139], v[18:19], v[154:155], v[238:239]
	v_pk_fma_f32 v[198:199], v[26:27], v[214:215], v[246:247]
	v_pk_fma_f32 v[140:141], v[20:21], v[156:157], v[240:241]
	v_pk_fma_f32 v[200:201], v[28:29], v[216:217], v[248:249]
	v_pk_fma_f32 v[142:143], v[22:23], v[158:159], v[242:243]
	v_pk_fma_f32 v[202:203], v[30:31], v[218:219], v[250:251]
	v_pk_fma_f32 v[136:137], v[32:33], v[160:161], v[136:137]
	v_pk_fma_f32 v[196:197], v[40:41], v[220:221], v[196:197]
	v_pk_fma_f32 v[138:139], v[34:35], v[162:163], v[138:139]
	v_pk_fma_f32 v[198:199], v[42:43], v[222:223], v[198:199]
	v_pk_fma_f32 v[140:141], v[36:37], v[164:165], v[140:141]
	v_pk_fma_f32 v[200:201], v[44:45], v[224:225], v[200:201]
	v_pk_fma_f32 v[142:143], v[38:39], v[166:167], v[142:143]
	v_pk_fma_f32 v[202:203], v[46:47], v[226:227], v[202:203]
	v_pk_fma_f32 v[136:137], v[48:49], v[168:169], v[136:137]
	v_pk_fma_f32 v[196:197], v[56:57], v[228:229], v[196:197]
	v_pk_fma_f32 v[138:139], v[50:51], v[170:171], v[138:139]
	v_pk_fma_f32 v[198:199], v[58:59], v[230:231], v[198:199]
	v_pk_fma_f32 v[140:141], v[52:53], v[172:173], v[140:141]
	v_pk_fma_f32 v[200:201], v[60:61], v[232:233], v[200:201]
	v_pk_fma_f32 v[142:143], v[54:55], v[174:175], v[142:143]
	v_pk_fma_f32 v[202:203], v[62:63], v[234:235], v[202:203]
	v_pk_mul_f32 v[184:185], v[136:137], v[180:181]
	v_pk_mul_f32 v[186:187], v[138:139], v[180:181]
	v_pk_mul_f32 v[188:189], v[140:141], v[180:181]
	v_pk_mul_f32 v[190:191], v[142:143], v[180:181]
	v_exp_f32_e32 v184, v184
	v_exp_f32_e32 v185, v185
	v_exp_f32_e32 v186, v186
	v_exp_f32_e32 v187, v187
	v_exp_f32_e32 v188, v188
	v_exp_f32_e32 v189, v189
	v_exp_f32_e32 v190, v190
	v_exp_f32_e32 v191, v191
	s_nop 0
	v_pk_add_f32 v[184:185], v[184:185], v[144:145]
	v_pk_add_f32 v[186:187], v[186:187], v[144:145]
	v_pk_add_f32 v[188:189], v[188:189], v[144:145]
	v_pk_add_f32 v[190:191], v[190:191], v[144:145]
	v_rcp_f32_e32 v184, v184
	v_rcp_f32_e32 v185, v185
	v_rcp_f32_e32 v186, v186
	v_rcp_f32_e32 v187, v187
	v_rcp_f32_e32 v188, v188
	v_rcp_f32_e32 v189, v189
	v_rcp_f32_e32 v190, v190
	v_rcp_f32_e32 v191, v191
	s_nop 0
	v_pk_mul_f32 v[136:137], v[136:137], v[184:185]
	v_pk_mul_f32 v[138:139], v[138:139], v[186:187]
	v_pk_mul_f32 v[140:141], v[140:141], v[188:189]
	v_pk_mul_f32 v[142:143], v[142:143], v[190:191]
	v_pk_mul_f32 v[136:137], v[136:137], v[196:197]
	v_pk_mul_f32 v[138:139], v[138:139], v[198:199]
	v_pk_mul_f32 v[140:141], v[140:141], v[200:201]
	v_pk_mul_f32 v[142:143], v[142:143], v[202:203]
	v_cvt_pk_bf16_f32 v12, v136, v137
	v_cvt_pk_bf16_f32 v13, v138, v139
	v_cvt_pk_bf16_f32 v14, v140, v141
	v_cvt_pk_bf16_f32 v15, v142, v143
	global_store_dwordx4 v6, v[12:15], s[36:37]
	v_add_u32_e32 v6, 5632, v6
	s_waitcnt vmcnt(23)
; __device__ __forceinline__ unsigned cvt_pk_bf16(float lo, float hi) { unsigned r; asm volatile("v_cvt_pk_bf16_f32 %0, %1, %2" : "=v"(r) : "v"(lo), "v"(hi)); return r; }
; __device__ __forceinline__ float silu_f(float x) { return x * __builtin_amdgcn_rcpf(1.0f + __builtin_amdgcn_exp2f(-LOG2E * x)); }
; __device__ __forceinline__ float bflo(unsigned w) { return __uint_as_float(w << 16); }
; __device__ __forceinline__ float bfhi(unsigned w) { return __uint_as_float(w & 0xffff0000u); }
; __device__ __forceinline__ void conv_phase(const bf16_t* Z, bf16_t* UA, const float* cw, const float* cb, int nrows, int rowoff) {
;     ...
;         for (int rr = 0; rr < 16; ++rr) {
;             u32x4 na = zero, ng = zero; if (rr < 15 || has_right) { na = *(const u32x4*)(zp + (size_t)(rr + 1) * FFN2); ng = *(const u32x4*)(zp + (size_t)(rr + 1) * FFN2 + FFN); }
;             u32x4 o;
; #pragma unroll
;             for (int e2 = 0; e2 < 4; ++e2) {
;                 const float a0 = bflo(pa[e2]) * wa[0][2 * e2] + bflo(ca[e2]) * wa[1][2 * e2] + bflo(na[e2]) * wa[2][2 * e2] + ba[2 * e2];
;                 const float a1 = bfhi(pa[e2]) * wa[0][2 * e2 + 1] + bfhi(ca[e2]) * wa[1][2 * e2 + 1] + bfhi(na[e2]) * wa[2][2 * e2 + 1] + ba[2 * e2 + 1];
;                 const float g0 = bflo(pg[e2]) * wg[0][2 * e2] + bflo(cgv[e2]) * wg[1][2 * e2] + bflo(ng[e2]) * wg[2][2 * e2] + bg[2 * e2];
;                 const float g1 = bfhi(pg[e2]) * wg[0][2 * e2 + 1] + bfhi(cgv[e2]) * wg[1][2 * e2 + 1] + bfhi(ng[e2]) * wg[2][2 * e2 + 1] + bg[2 * e2 + 1];
;                 o[e2] = cvt_pk_bf16(silu_f(a0) * g0, silu_f(a1) * g1); }
;             *(u32x4*)(UA + (size_t)(r0 + rr) * FFN + c0) = o;
;             pa = ca; pg = cgv; ca = na; cgv = ng;
	v_lshlrev_b32_e32 v16, 16, v112
	v_and_b32_e32 v17, s99, v112
	v_lshlrev_b32_e32 v18, 16, v113
	v_and_b32_e32 v19, s99, v113
	v_lshlrev_b32_e32 v20, 16, v114
	v_and_b32_e32 v21, s99, v114
	v_lshlrev_b32_e32 v22, 16, v115
	v_and_b32_e32 v23, s99, v115
	v_lshlrev_b32_e32 v24, 16, v116
	v_and_b32_e32 v25, s99, v116
	v_lshlrev_b32_e32 v26, 16, v117
	v_and_b32_e32 v27, s99, v117
	v_lshlrev_b32_e32 v28, 16, v118
	v_and_b32_e32 v29, s99, v118
	v_lshlrev_b32_e32 v30, 16, v119
	v_and_b32_e32 v31, s99, v119
	v_add_u32_e32 v11, 176896, v5
	global_load_dwordx4 v[112:115], v11, s[2:3] offset:-2816 nt
	global_load_dwordx4 v[116:119], v11, s[2:3] offset:2816 nt
	v_pk_fma_f32 v[136:137], v[32:33], v[152:153], v[236:237]
	v_pk_fma_f32 v[196:197], v[40:41], v[212:213], v[244:245]
	v_pk_fma_f32 v[138:139], v[34:35], v[154:155], v[238:239]
	v_pk_fma_f32 v[198:199], v[42:43], v[214:215], v[246:247]
	v_pk_fma_f32 v[140:141], v[36:37], v[156:157], v[240:241]
	v_pk_fma_f32 v[200:201], v[44:45], v[216:217], v[248:249]
	v_pk_fma_f32 v[142:143], v[38:39], v[158:159], v[242:243]
	v_pk_fma_f32 v[202:203], v[46:47], v[218:219], v[250:251]
	v_pk_fma_f32 v[136:137], v[48:49], v[160:161], v[136:137]
	v_pk_fma_f32 v[196:197], v[56:57], v[220:221], v[196:197]
	v_pk_fma_f32 v[138:139], v[50:51], v[162:163], v[138:139]
	v_pk_fma_f32 v[198:199], v[58:59], v[222:223], v[198:199]
	v_pk_fma_f32 v[140:141], v[52:53], v[164:165], v[140:141]
	v_pk_fma_f32 v[200:201], v[60:61], v[224:225], v[200:201]
	v_pk_fma_f32 v[142:143], v[54:55], v[166:167], v[142:143]
	v_pk_fma_f32 v[202:203], v[62:63], v[226:227], v[202:203]
	v_pk_fma_f32 v[136:137], v[16:17], v[168:169], v[136:137]
	v_pk_fma_f32 v[196:197], v[24:25], v[228:229], v[196:197]
	v_pk_fma_f32 v[138:139], v[18:19], v[170:171], v[138:139]
	v_pk_fma_f32 v[198:199], v[26:27], v[230:231], v[198:199]
	v_pk_fma_f32 v[140:141], v[20:21], v[172:173], v[140:141]
	v_pk_fma_f32 v[200:201], v[28:29], v[232:233], v[200:201]
	v_pk_fma_f32 v[142:143], v[22:23], v[174:175], v[142:143]
	v_pk_fma_f32 v[202:203], v[30:31], v[234:235], v[202:203]
	v_pk_mul_f32 v[184:185], v[136:137], v[180:181]
	v_pk_mul_f32 v[186:187], v[138:139], v[180:181]
	v_pk_mul_f32 v[188:189], v[140:141], v[180:181]
	v_pk_mul_f32 v[190:191], v[142:143], v[180:181]
	v_exp_f32_e32 v184, v184
	v_exp_f32_e32 v185, v185
	v_exp_f32_e32 v186, v186
	v_exp_f32_e32 v187, v187
	v_exp_f32_e32 v188, v188
	v_exp_f32_e32 v189, v189
	v_exp_f32_e32 v190, v190
	v_exp_f32_e32 v191, v191
	s_nop 0
	v_pk_add_f32 v[184:185], v[184:185], v[144:145]
	v_pk_add_f32 v[186:187], v[186:187], v[144:145]
	v_pk_add_f32 v[188:189], v[188:189], v[144:145]
	v_pk_add_f32 v[190:191], v[190:191], v[144:145]
	v_rcp_f32_e32 v184, v184
	v_rcp_f32_e32 v185, v185
	v_rcp_f32_e32 v186, v186
	v_rcp_f32_e32 v187, v187
	v_rcp_f32_e32 v188, v188
	v_rcp_f32_e32 v189, v189
	v_rcp_f32_e32 v190, v190
	v_rcp_f32_e32 v191, v191
	s_nop 0
	v_pk_mul_f32 v[136:137], v[136:137], v[184:185]
	v_pk_mul_f32 v[138:139], v[138:139], v[186:187]
	v_pk_mul_f32 v[140:141], v[140:141], v[188:189]
	v_pk_mul_f32 v[142:143], v[142:143], v[190:191]
	v_pk_mul_f32 v[136:137], v[136:137], v[196:197]
	v_pk_mul_f32 v[138:139], v[138:139], v[198:199]
	v_pk_mul_f32 v[140:141], v[140:141], v[200:201]
	v_pk_mul_f32 v[142:143], v[142:143], v[202:203]
	v_cvt_pk_bf16_f32 v12, v136, v137
	v_cvt_pk_bf16_f32 v13, v138, v139
	v_cvt_pk_bf16_f32 v14, v140, v141
	v_cvt_pk_bf16_f32 v15, v142, v143
	global_store_dwordx4 v6, v[12:15], s[36:37]
	v_add_u32_e32 v6, 5632, v6
	s_waitcnt vmcnt(23)
	v_lshlrev_b32_e32 v32, 16, v120
	v_and_b32_e32 v33, s99, v120
	v_lshlrev_b32_e32 v34, 16, v121
	v_and_b32_e32 v35, s99, v121
	v_lshlrev_b32_e32 v36, 16, v122
	v_and_b32_e32 v37, s99, v122
	v_lshlrev_b32_e32 v38, 16, v123
	v_and_b32_e32 v39, s99, v123
	v_lshlrev_b32_e32 v40, 16, v124
	v_and_b32_e32 v41, s99, v124
	v_lshlrev_b32_e32 v42, 16, v125
	v_and_b32_e32 v43, s99, v125
	v_lshlrev_b32_e32 v44, 16, v126
	v_and_b32_e32 v45, s99, v126
	v_lshlrev_b32_e32 v46, 16, v127
	v_and_b32_e32 v47, s99, v127
	v_add_u32_e32 v10, 188160, v5
	global_load_dwordx4 v[120:123], v10, s[2:3] offset:-2816 nt
	global_load_dwordx4 v[124:127], v10, s[2:3] offset:2816 nt
	v_pk_fma_f32 v[136:137], v[48:49], v[152:153], v[236:237]
	v_pk_fma_f32 v[196:197], v[56:57], v[212:213], v[244:245]
	v_pk_fma_f32 v[138:139], v[50:51], v[154:155], v[238:239]
	v_pk_fma_f32 v[198:199], v[58:59], v[214:215], v[246:247]
	v_pk_fma_f32 v[140:141], v[52:53], v[156:157], v[240:241]
	v_pk_fma_f32 v[200:201], v[60:61], v[216:217], v[248:249]
	v_pk_fma_f32 v[142:143], v[54:55], v[158:159], v[242:243]
	v_pk_fma_f32 v[202:203], v[62:63], v[218:219], v[250:251]
	v_pk_fma_f32 v[136:137], v[16:17], v[160:161], v[136:137]
	v_pk_fma_f32 v[196:197], v[24:25], v[220:221], v[196:197]
	v_pk_fma_f32 v[138:139], v[18:19], v[162:163], v[138:139]
	v_pk_fma_f32 v[198:199], v[26:27], v[222:223], v[198:199]
	v_pk_fma_f32 v[140:141], v[20:21], v[164:165], v[140:141]
	v_pk_fma_f32 v[200:201], v[28:29], v[224:225], v[200:201]
	v_pk_fma_f32 v[142:143], v[22:23], v[166:167], v[142:143]
	v_pk_fma_f32 v[202:203], v[30:31], v[226:227], v[202:203]
	v_pk_fma_f32 v[136:137], v[32:33], v[168:169], v[136:137]
	v_pk_fma_f32 v[196:197], v[40:41], v[228:229], v[196:197]
	v_pk_fma_f32 v[138:139], v[34:35], v[170:171], v[138:139]
	v_pk_fma_f32 v[198:199], v[42:43], v[230:231], v[198:199]
	v_pk_fma_f32 v[140:141], v[36:37], v[172:173], v[140:141]
	v_pk_fma_f32 v[200:201], v[44:45], v[232:233], v[200:201]
	v_pk_fma_f32 v[142:143], v[38:39], v[174:175], v[142:143]
	v_pk_fma_f32 v[202:203], v[46:47], v[234:235], v[202:203]
	v_pk_mul_f32 v[184:185], v[136:137], v[180:181]
	v_pk_mul_f32 v[186:187], v[138:139], v[180:181]
	v_pk_mul_f32 v[188:189], v[140:141], v[180:181]
	v_pk_mul_f32 v[190:191], v[142:143], v[180:181]
	v_exp_f32_e32 v184, v184
	v_exp_f32_e32 v185, v185
	v_exp_f32_e32 v186, v186
	v_exp_f32_e32 v187, v187
	v_exp_f32_e32 v188, v188
	v_exp_f32_e32 v189, v189
	v_exp_f32_e32 v190, v190
	v_exp_f32_e32 v191, v191
	s_nop 0
	v_pk_add_f32 v[184:185], v[184:185], v[144:145]
	v_pk_add_f32 v[186:187], v[186:187], v[144:145]
	v_pk_add_f32 v[188:189], v[188:189], v[144:145]
	v_pk_add_f32 v[190:191], v[190:191], v[144:145]
	v_rcp_f32_e32 v184, v184
	v_rcp_f32_e32 v185, v185
	v_rcp_f32_e32 v186, v186
	v_rcp_f32_e32 v187, v187
	v_rcp_f32_e32 v188, v188
	v_rcp_f32_e32 v189, v189
	v_rcp_f32_e32 v190, v190
	v_rcp_f32_e32 v191, v191
	s_nop 0
	v_pk_mul_f32 v[136:137], v[136:137], v[184:185]
	v_pk_mul_f32 v[138:139], v[138:139], v[186:187]
	v_pk_mul_f32 v[140:141], v[140:141], v[188:189]
	v_pk_mul_f32 v[142:143], v[142:143], v[190:191]
	v_pk_mul_f32 v[136:137], v[136:137], v[196:197]
	v_pk_mul_f32 v[138:139], v[138:139], v[198:199]
	v_pk_mul_f32 v[140:141], v[140:141], v[200:201]
	v_pk_mul_f32 v[142:143], v[142:143], v[202:203]
	v_cvt_pk_bf16_f32 v12, v136, v137
	v_cvt_pk_bf16_f32 v13, v138, v139
	v_cvt_pk_bf16_f32 v14, v140, v141
	v_cvt_pk_bf16_f32 v15, v142, v143
	global_store_dwordx4 v6, v[12:15], s[36:37]
	v_add_u32_e32 v6, 5632, v6
	s_waitcnt vmcnt(23)
; __device__ __forceinline__ unsigned cvt_pk_bf16(float lo, float hi) { unsigned r; asm volatile("v_cvt_pk_bf16_f32 %0, %1, %2" : "=v"(r) : "v"(lo), "v"(hi)); return r; }
; __device__ __forceinline__ float silu_f(float x) { return x * __builtin_amdgcn_rcpf(1.0f + __builtin_amdgcn_exp2f(-LOG2E * x)); }
; __device__ __forceinline__ float bflo(unsigned w) { return __uint_as_float(w << 16); }
; __device__ __forceinline__ float bfhi(unsigned w) { return __uint_as_float(w & 0xffff0000u); }
; __device__ __forceinline__ void conv_phase(const bf16_t* Z, bf16_t* UA, const float* cw, const float* cb, int nrows, int rowoff) {
;     ...
;     for (int idx = gtid; idx < total; idx += NT) {
;         const int cgp = idx % 352, rb = idx / 352, c0 = cgp * 8, r0 = rb * 16, grow0 = rowoff + r0;
;     ...
;         for (int rr = 0; rr < 16; ++rr) {
;             u32x4 na = zero, ng = zero; if (rr < 15 || has_right) { na = *(const u32x4*)(zp + (size_t)(rr + 1) * FFN2); ng = *(const u32x4*)(zp + (size_t)(rr + 1) * FFN2 + FFN); }
;             u32x4 o;
; #pragma unroll
;             for (int e2 = 0; e2 < 4; ++e2) {
;                 const float a0 = bflo(pa[e2]) * wa[0][2 * e2] + bflo(ca[e2]) * wa[1][2 * e2] + bflo(na[e2]) * wa[2][2 * e2] + ba[2 * e2];
;                 const float a1 = bfhi(pa[e2]) * wa[0][2 * e2 + 1] + bfhi(ca[e2]) * wa[1][2 * e2 + 1] + bfhi(na[e2]) * wa[2][2 * e2 + 1] + ba[2 * e2 + 1];
;                 const float g0 = bflo(pg[e2]) * wg[0][2 * e2] + bflo(cgv[e2]) * wg[1][2 * e2] + bflo(ng[e2]) * wg[2][2 * e2] + bg[2 * e2];
;                 const float g1 = bfhi(pg[e2]) * wg[0][2 * e2 + 1] + bfhi(cgv[e2]) * wg[1][2 * e2 + 1] + bfhi(ng[e2]) * wg[2][2 * e2 + 1] + bg[2 * e2 + 1];
;                 o[e2] = cvt_pk_bf16(silu_f(a0) * g0, silu_f(a1) * g1); }
;             *(u32x4*)(UA + (size_t)(r0 + rr) * FFN + c0) = o;
;             pa = ca; pg = cgv; ca = na; cgv = ng;
	v_lshlrev_b32_e32 v48, 16, v128
	v_and_b32_e32 v49, s99, v128
	v_lshlrev_b32_e32 v50, 16, v129
	v_and_b32_e32 v51, s99, v129
	v_lshlrev_b32_e32 v52, 16, v130
	v_and_b32_e32 v53, s99, v130
	v_lshlrev_b32_e32 v54, 16, v131
	v_and_b32_e32 v55, s99, v131
	v_lshlrev_b32_e32 v56, 16, v132
	v_and_b32_e32 v57, s99, v132
	v_lshlrev_b32_e32 v58, 16, v133
	v_and_b32_e32 v59, s99, v133
	v_lshlrev_b32_e32 v60, 16, v134
	v_and_b32_e32 v61, s99, v134
	v_lshlrev_b32_e32 v62, 16, v135
	v_and_b32_e32 v63, s99, v135
	v_add_u32_e32 v11, 199424, v5
	global_load_dwordx4 v[128:131], v11, s[2:3] offset:-2816 nt
	global_load_dwordx4 v[132:135], v11, s[2:3] offset:2816 nt
	v_pk_fma_f32 v[136:137], v[16:17], v[152:153], v[236:237]
	v_pk_fma_f32 v[196:197], v[24:25], v[212:213], v[244:245]
	v_pk_fma_f32 v[138:139], v[18:19], v[154:155], v[238:239]
	v_pk_fma_f32 v[198:199], v[26:27], v[214:215], v[246:247]
	v_pk_fma_f32 v[140:141], v[20:21], v[156:157], v[240:241]
	v_pk_fma_f32 v[200:201], v[28:29], v[216:217], v[248:249]
	v_pk_fma_f32 v[142:143], v[22:23], v[158:159], v[242:243]
	v_pk_fma_f32 v[202:203], v[30:31], v[218:219], v[250:251]
	v_pk_fma_f32 v[136:137], v[32:33], v[160:161], v[136:137]
	v_pk_fma_f32 v[196:197], v[40:41], v[220:221], v[196:197]
	v_pk_fma_f32 v[138:139], v[34:35], v[162:163], v[138:139]
	v_pk_fma_f32 v[198:199], v[42:43], v[222:223], v[198:199]
	v_pk_fma_f32 v[140:141], v[36:37], v[164:165], v[140:141]
	v_pk_fma_f32 v[200:201], v[44:45], v[224:225], v[200:201]
	v_pk_fma_f32 v[142:143], v[38:39], v[166:167], v[142:143]
	v_pk_fma_f32 v[202:203], v[46:47], v[226:227], v[202:203]
	v_pk_fma_f32 v[136:137], v[48:49], v[168:169], v[136:137]
	v_pk_fma_f32 v[196:197], v[56:57], v[228:229], v[196:197]
	v_pk_fma_f32 v[138:139], v[50:51], v[170:171], v[138:139]
	v_pk_fma_f32 v[198:199], v[58:59], v[230:231], v[198:199]
	v_pk_fma_f32 v[140:141], v[52:53], v[172:173], v[140:141]
	v_pk_fma_f32 v[200:201], v[60:61], v[232:233], v[200:201]
	v_pk_fma_f32 v[142:143], v[54:55], v[174:175], v[142:143]
	v_pk_fma_f32 v[202:203], v[62:63], v[234:235], v[202:203]
	v_pk_mul_f32 v[184:185], v[136:137], v[180:181]
	v_pk_mul_f32 v[186:187], v[138:139], v[180:181]
	v_pk_mul_f32 v[188:189], v[140:141], v[180:181]
	v_pk_mul_f32 v[190:191], v[142:143], v[180:181]
	v_exp_f32_e32 v184, v184
	v_exp_f32_e32 v185, v185
	v_exp_f32_e32 v186, v186
	v_exp_f32_e32 v187, v187
	v_exp_f32_e32 v188, v188
	v_exp_f32_e32 v189, v189
	v_exp_f32_e32 v190, v190
	v_exp_f32_e32 v191, v191
	s_nop 0
	v_pk_add_f32 v[184:185], v[184:185], v[144:145]
	v_pk_add_f32 v[186:187], v[186:187], v[144:145]
	v_pk_add_f32 v[188:189], v[188:189], v[144:145]
	v_pk_add_f32 v[190:191], v[190:191], v[144:145]
	v_rcp_f32_e32 v184, v184
	v_rcp_f32_e32 v185, v185
	v_rcp_f32_e32 v186, v186
	v_rcp_f32_e32 v187, v187
	v_rcp_f32_e32 v188, v188
	v_rcp_f32_e32 v189, v189
	v_rcp_f32_e32 v190, v190
	v_rcp_f32_e32 v191, v191
	s_nop 0
	v_pk_mul_f32 v[136:137], v[136:137], v[184:185]
	v_pk_mul_f32 v[138:139], v[138:139], v[186:187]
	v_pk_mul_f32 v[140:141], v[140:141], v[188:189]
	v_pk_mul_f32 v[142:143], v[142:143], v[190:191]
	v_pk_mul_f32 v[136:137], v[136:137], v[196:197]
	v_pk_mul_f32 v[138:139], v[138:139], v[198:199]
	v_pk_mul_f32 v[140:141], v[140:141], v[200:201]
	v_pk_mul_f32 v[142:143], v[142:143], v[202:203]
	v_cvt_pk_bf16_f32 v12, v136, v137
	v_cvt_pk_bf16_f32 v13, v138, v139
	v_cvt_pk_bf16_f32 v14, v140, v141
	v_cvt_pk_bf16_f32 v15, v142, v143
	global_store_dwordx4 v6, v[12:15], s[36:37]
	v_add_u32_e32 v6, 5632, v6
	s_waitcnt vmcnt(23)
	v_lshlrev_b32_e32 v16, 16, v64
	v_and_b32_e32 v17, s99, v64
	v_lshlrev_b32_e32 v18, 16, v65
	v_and_b32_e32 v19, s99, v65
	v_lshlrev_b32_e32 v20, 16, v66
	v_and_b32_e32 v21, s99, v66
	v_lshlrev_b32_e32 v22, 16, v67
	v_and_b32_e32 v23, s99, v67
	v_lshlrev_b32_e32 v24, 16, v68
	v_and_b32_e32 v25, s99, v68
	v_lshlrev_b32_e32 v26, 16, v69
	v_and_b32_e32 v27, s99, v69
	v_lshlrev_b32_e32 v28, 16, v70
	v_and_b32_e32 v29, s99, v70
	v_lshlrev_b32_e32 v30, 16, v71
	v_and_b32_e32 v31, s99, v71
	v_add_u32_e32 v10, 67051264, v5
	global_load_dwordx4 v[64:67], v10, s[2:3] offset:-2816 nt
	global_load_dwordx4 v[68:71], v10, s[2:3] offset:2816 nt
	v_pk_fma_f32 v[136:137], v[32:33], v[152:153], v[236:237]
	v_pk_fma_f32 v[196:197], v[40:41], v[212:213], v[244:245]
	v_pk_fma_f32 v[138:139], v[34:35], v[154:155], v[238:239]
	v_pk_fma_f32 v[198:199], v[42:43], v[214:215], v[246:247]
	v_pk_fma_f32 v[140:141], v[36:37], v[156:157], v[240:241]
	v_pk_fma_f32 v[200:201], v[44:45], v[216:217], v[248:249]
	v_pk_fma_f32 v[142:143], v[38:39], v[158:159], v[242:243]
	v_pk_fma_f32 v[202:203], v[46:47], v[218:219], v[250:251]
	v_pk_fma_f32 v[136:137], v[48:49], v[160:161], v[136:137]
	v_pk_fma_f32 v[196:197], v[56:57], v[220:221], v[196:197]
	v_pk_fma_f32 v[138:139], v[50:51], v[162:163], v[138:139]
	v_pk_fma_f32 v[198:199], v[58:59], v[222:223], v[198:199]
	v_pk_fma_f32 v[140:141], v[52:53], v[164:165], v[140:141]
	v_pk_fma_f32 v[200:201], v[60:61], v[224:225], v[200:201]
	v_pk_fma_f32 v[142:143], v[54:55], v[166:167], v[142:143]
	v_pk_fma_f32 v[202:203], v[62:63], v[226:227], v[202:203]
	v_pk_fma_f32 v[136:137], v[16:17], v[168:169], v[136:137]
	v_pk_fma_f32 v[196:197], v[24:25], v[228:229], v[196:197]
	v_pk_fma_f32 v[138:139], v[18:19], v[170:171], v[138:139]
	v_pk_fma_f32 v[198:199], v[26:27], v[230:231], v[198:199]
	v_pk_fma_f32 v[140:141], v[20:21], v[172:173], v[140:141]
	v_pk_fma_f32 v[200:201], v[28:29], v[232:233], v[200:201]
	v_pk_fma_f32 v[142:143], v[22:23], v[174:175], v[142:143]
	v_pk_fma_f32 v[202:203], v[30:31], v[234:235], v[202:203]
	v_pk_mul_f32 v[184:185], v[136:137], v[180:181]
	v_pk_mul_f32 v[186:187], v[138:139], v[180:181]
	v_pk_mul_f32 v[188:189], v[140:141], v[180:181]
	v_pk_mul_f32 v[190:191], v[142:143], v[180:181]
	v_exp_f32_e32 v184, v184
	v_exp_f32_e32 v185, v185
	v_exp_f32_e32 v186, v186
	v_exp_f32_e32 v187, v187
	v_exp_f32_e32 v188, v188
	v_exp_f32_e32 v189, v189
	v_exp_f32_e32 v190, v190
	v_exp_f32_e32 v191, v191
	s_nop 0
	v_pk_add_f32 v[184:185], v[184:185], v[144:145]
	v_pk_add_f32 v[186:187], v[186:187], v[144:145]
	v_pk_add_f32 v[188:189], v[188:189], v[144:145]
	v_pk_add_f32 v[190:191], v[190:191], v[144:145]
	v_rcp_f32_e32 v184, v184
	v_rcp_f32_e32 v185, v185
	v_rcp_f32_e32 v186, v186
	v_rcp_f32_e32 v187, v187
	v_rcp_f32_e32 v188, v188
	v_rcp_f32_e32 v189, v189
	v_rcp_f32_e32 v190, v190
	v_rcp_f32_e32 v191, v191
	s_nop 0
	v_pk_mul_f32 v[136:137], v[136:137], v[184:185]
	v_pk_mul_f32 v[138:139], v[138:139], v[186:187]
	v_pk_mul_f32 v[140:141], v[140:141], v[188:189]
	v_pk_mul_f32 v[142:143], v[142:143], v[190:191]
	v_pk_mul_f32 v[136:137], v[136:137], v[196:197]
	v_pk_mul_f32 v[138:139], v[138:139], v[198:199]
	v_pk_mul_f32 v[140:141], v[140:141], v[200:201]
	v_pk_mul_f32 v[142:143], v[142:143], v[202:203]
	v_cvt_pk_bf16_f32 v12, v136, v137
	v_cvt_pk_bf16_f32 v13, v138, v139
	v_cvt_pk_bf16_f32 v14, v140, v141
	v_cvt_pk_bf16_f32 v15, v142, v143
	global_store_dwordx4 v6, v[12:15], s[36:37]
	v_add_u32_e32 v6, 5632, v6
	s_waitcnt vmcnt(24)
; __device__ __forceinline__ unsigned cvt_pk_bf16(float lo, float hi) { unsigned r; asm volatile("v_cvt_pk_bf16_f32 %0, %1, %2" : "=v"(r) : "v"(lo), "v"(hi)); return r; }
; __device__ __forceinline__ float silu_f(float x) { return x * __builtin_amdgcn_rcpf(1.0f + __builtin_amdgcn_exp2f(-LOG2E * x)); }
; __device__ __forceinline__ float bflo(unsigned w) { return __uint_as_float(w << 16); }
; __device__ __forceinline__ float bfhi(unsigned w) { return __uint_as_float(w & 0xffff0000u); }
; __device__ __forceinline__ void conv_phase(const bf16_t* Z, bf16_t* UA, const float* cw, const float* cb, int nrows, int rowoff) {
;     ...
;         for (int rr = 0; rr < 16; ++rr) {
;             u32x4 na = zero, ng = zero; if (rr < 15 || has_right) { na = *(const u32x4*)(zp + (size_t)(rr + 1) * FFN2); ng = *(const u32x4*)(zp + (size_t)(rr + 1) * FFN2 + FFN); }
;             u32x4 o;
; #pragma unroll
;             for (int e2 = 0; e2 < 4; ++e2) {
;                 const float a0 = bflo(pa[e2]) * wa[0][2 * e2] + bflo(ca[e2]) * wa[1][2 * e2] + bflo(na[e2]) * wa[2][2 * e2] + ba[2 * e2];
;                 const float a1 = bfhi(pa[e2]) * wa[0][2 * e2 + 1] + bfhi(ca[e2]) * wa[1][2 * e2 + 1] + bfhi(na[e2]) * wa[2][2 * e2 + 1] + ba[2 * e2 + 1];
;                 const float g0 = bflo(pg[e2]) * wg[0][2 * e2] + bflo(cgv[e2]) * wg[1][2 * e2] + bflo(ng[e2]) * wg[2][2 * e2] + bg[2 * e2];
;                 const float g1 = bfhi(pg[e2]) * wg[0][2 * e2 + 1] + bfhi(cgv[e2]) * wg[1][2 * e2 + 1] + bfhi(ng[e2]) * wg[2][2 * e2 + 1] + bg[2 * e2 + 1];
;                 o[e2] = cvt_pk_bf16(silu_f(a0) * g0, silu_f(a1) * g1); }
;             *(u32x4*)(UA + (size_t)(r0 + rr) * FFN + c0) = o;
;             pa = ca; pg = cgv; ca = na; cgv = ng;
	v_lshlrev_b32_e32 v32, 16, v72
	v_and_b32_e32 v33, s99, v72
	v_lshlrev_b32_e32 v34, 16, v73
	v_and_b32_e32 v35, s99, v73
	v_lshlrev_b32_e32 v36, 16, v74
	v_and_b32_e32 v37, s99, v74
	v_lshlrev_b32_e32 v38, 16, v75
	v_and_b32_e32 v39, s99, v75
	v_lshlrev_b32_e32 v40, 16, v76
	v_and_b32_e32 v41, s99, v76
	v_lshlrev_b32_e32 v42, 16, v77
	v_and_b32_e32 v43, s99, v77
	v_lshlrev_b32_e32 v44, 16, v78
	v_and_b32_e32 v45, s99, v78
	v_lshlrev_b32_e32 v46, 16, v79
	v_and_b32_e32 v47, s99, v79
	v_add_u32_e32 v11, 67062528, v5
	global_load_dwordx4 v[72:75], v11, s[2:3] offset:-2816 nt
	global_load_dwordx4 v[76:79], v11, s[2:3] offset:2816 nt
	v_pk_fma_f32 v[136:137], v[48:49], v[152:153], v[236:237]
	v_pk_fma_f32 v[196:197], v[56:57], v[212:213], v[244:245]
	v_pk_fma_f32 v[138:139], v[50:51], v[154:155], v[238:239]
	v_pk_fma_f32 v[198:199], v[58:59], v[214:215], v[246:247]
	v_pk_fma_f32 v[140:141], v[52:53], v[156:157], v[240:241]
	v_pk_fma_f32 v[200:201], v[60:61], v[216:217], v[248:249]
	v_pk_fma_f32 v[142:143], v[54:55], v[158:159], v[242:243]
	v_pk_fma_f32 v[202:203], v[62:63], v[218:219], v[250:251]
	v_pk_fma_f32 v[136:137], v[16:17], v[160:161], v[136:137]
	v_pk_fma_f32 v[196:197], v[24:25], v[220:221], v[196:197]
	v_pk_fma_f32 v[138:139], v[18:19], v[162:163], v[138:139]
	v_pk_fma_f32 v[198:199], v[26:27], v[222:223], v[198:199]
	v_pk_fma_f32 v[140:141], v[20:21], v[164:165], v[140:141]
	v_pk_fma_f32 v[200:201], v[28:29], v[224:225], v[200:201]
	v_pk_fma_f32 v[142:143], v[22:23], v[166:167], v[142:143]
	v_pk_fma_f32 v[202:203], v[30:31], v[226:227], v[202:203]
	v_pk_fma_f32 v[136:137], v[32:33], v[168:169], v[136:137]
	v_pk_fma_f32 v[196:197], v[40:41], v[228:229], v[196:197]
	v_pk_fma_f32 v[138:139], v[34:35], v[170:171], v[138:139]
	v_pk_fma_f32 v[198:199], v[42:43], v[230:231], v[198:199]
	v_pk_fma_f32 v[140:141], v[36:37], v[172:173], v[140:141]
	v_pk_fma_f32 v[200:201], v[44:45], v[232:233], v[200:201]
	v_pk_fma_f32 v[142:143], v[38:39], v[174:175], v[142:143]
	v_pk_fma_f32 v[202:203], v[46:47], v[234:235], v[202:203]
	v_pk_mul_f32 v[184:185], v[136:137], v[180:181]
	v_pk_mul_f32 v[186:187], v[138:139], v[180:181]
	v_pk_mul_f32 v[188:189], v[140:141], v[180:181]
	v_pk_mul_f32 v[190:191], v[142:143], v[180:181]
	v_exp_f32_e32 v184, v184
	v_exp_f32_e32 v185, v185
	v_exp_f32_e32 v186, v186
	v_exp_f32_e32 v187, v187
	v_exp_f32_e32 v188, v188
	v_exp_f32_e32 v189, v189
	v_exp_f32_e32 v190, v190
	v_exp_f32_e32 v191, v191
	s_nop 0
	v_pk_add_f32 v[184:185], v[184:185], v[144:145]
	v_pk_add_f32 v[186:187], v[186:187], v[144:145]
	v_pk_add_f32 v[188:189], v[188:189], v[144:145]
	v_pk_add_f32 v[190:191], v[190:191], v[144:145]
	v_rcp_f32_e32 v184, v184
	v_rcp_f32_e32 v185, v185
	v_rcp_f32_e32 v186, v186
	v_rcp_f32_e32 v187, v187
	v_rcp_f32_e32 v188, v188
	v_rcp_f32_e32 v189, v189
	v_rcp_f32_e32 v190, v190
	v_rcp_f32_e32 v191, v191
	s_nop 0
	v_pk_mul_f32 v[136:137], v[136:137], v[184:185]
	v_pk_mul_f32 v[138:139], v[138:139], v[186:187]
	v_pk_mul_f32 v[140:141], v[140:141], v[188:189]
	v_pk_mul_f32 v[142:143], v[142:143], v[190:191]
	v_pk_mul_f32 v[136:137], v[136:137], v[196:197]
	v_pk_mul_f32 v[138:139], v[138:139], v[198:199]
	v_pk_mul_f32 v[140:141], v[140:141], v[200:201]
	v_pk_mul_f32 v[142:143], v[142:143], v[202:203]
	v_cvt_pk_bf16_f32 v12, v136, v137
	v_cvt_pk_bf16_f32 v13, v138, v139
	v_cvt_pk_bf16_f32 v14, v140, v141
	v_cvt_pk_bf16_f32 v15, v142, v143
	global_store_dwordx4 v6, v[12:15], s[36:37]
	v_add_u32_e32 v6, 5632, v6
	s_waitcnt vmcnt(25)
	v_lshlrev_b32_e32 v48, 16, v80
	v_and_b32_e32 v49, s99, v80
	v_lshlrev_b32_e32 v50, 16, v81
	v_and_b32_e32 v51, s99, v81
	v_lshlrev_b32_e32 v52, 16, v82
	v_and_b32_e32 v53, s99, v82
	v_lshlrev_b32_e32 v54, 16, v83
	v_and_b32_e32 v55, s99, v83
	v_lshlrev_b32_e32 v56, 16, v84
	v_and_b32_e32 v57, s99, v84
	v_lshlrev_b32_e32 v58, 16, v85
	v_and_b32_e32 v59, s99, v85
	v_lshlrev_b32_e32 v60, 16, v86
	v_and_b32_e32 v61, s99, v86
	v_lshlrev_b32_e32 v62, 16, v87
	v_and_b32_e32 v63, s99, v87
	v_add_u32_e32 v10, 67073792, v5
	global_load_dwordx4 v[80:83], v10, s[2:3] offset:-2816 nt
	global_load_dwordx4 v[84:87], v10, s[2:3] offset:2816 nt
	v_pk_fma_f32 v[136:137], v[16:17], v[152:153], v[236:237]
	v_pk_fma_f32 v[196:197], v[24:25], v[212:213], v[244:245]
	v_pk_fma_f32 v[138:139], v[18:19], v[154:155], v[238:239]
	v_pk_fma_f32 v[198:199], v[26:27], v[214:215], v[246:247]
	v_pk_fma_f32 v[140:141], v[20:21], v[156:157], v[240:241]
	v_pk_fma_f32 v[200:201], v[28:29], v[216:217], v[248:249]
	v_pk_fma_f32 v[142:143], v[22:23], v[158:159], v[242:243]
	v_pk_fma_f32 v[202:203], v[30:31], v[218:219], v[250:251]
	v_pk_fma_f32 v[136:137], v[32:33], v[160:161], v[136:137]
	v_pk_fma_f32 v[196:197], v[40:41], v[220:221], v[196:197]
	v_pk_fma_f32 v[138:139], v[34:35], v[162:163], v[138:139]
	v_pk_fma_f32 v[198:199], v[42:43], v[222:223], v[198:199]
	v_pk_fma_f32 v[140:141], v[36:37], v[164:165], v[140:141]
	v_pk_fma_f32 v[200:201], v[44:45], v[224:225], v[200:201]
	v_pk_fma_f32 v[142:143], v[38:39], v[166:167], v[142:143]
	v_pk_fma_f32 v[202:203], v[46:47], v[226:227], v[202:203]
	v_pk_fma_f32 v[136:137], v[48:49], v[168:169], v[136:137]
	v_pk_fma_f32 v[196:197], v[56:57], v[228:229], v[196:197]
	v_pk_fma_f32 v[138:139], v[50:51], v[170:171], v[138:139]
	v_pk_fma_f32 v[198:199], v[58:59], v[230:231], v[198:199]
	v_pk_fma_f32 v[140:141], v[52:53], v[172:173], v[140:141]
	v_pk_fma_f32 v[200:201], v[60:61], v[232:233], v[200:201]
	v_pk_fma_f32 v[142:143], v[54:55], v[174:175], v[142:143]
	v_pk_fma_f32 v[202:203], v[62:63], v[234:235], v[202:203]
	v_pk_mul_f32 v[184:185], v[136:137], v[180:181]
	v_pk_mul_f32 v[186:187], v[138:139], v[180:181]
	v_pk_mul_f32 v[188:189], v[140:141], v[180:181]
	v_pk_mul_f32 v[190:191], v[142:143], v[180:181]
	v_exp_f32_e32 v184, v184
	v_exp_f32_e32 v185, v185
	v_exp_f32_e32 v186, v186
	v_exp_f32_e32 v187, v187
	v_exp_f32_e32 v188, v188
	v_exp_f32_e32 v189, v189
	v_exp_f32_e32 v190, v190
	v_exp_f32_e32 v191, v191
	s_nop 0
	v_pk_add_f32 v[184:185], v[184:185], v[144:145]
	v_pk_add_f32 v[186:187], v[186:187], v[144:145]
	v_pk_add_f32 v[188:189], v[188:189], v[144:145]
	v_pk_add_f32 v[190:191], v[190:191], v[144:145]
	v_rcp_f32_e32 v184, v184
	v_rcp_f32_e32 v185, v185
	v_rcp_f32_e32 v186, v186
	v_rcp_f32_e32 v187, v187
	v_rcp_f32_e32 v188, v188
	v_rcp_f32_e32 v189, v189
	v_rcp_f32_e32 v190, v190
	v_rcp_f32_e32 v191, v191
	s_nop 0
	v_pk_mul_f32 v[136:137], v[136:137], v[184:185]
	v_pk_mul_f32 v[138:139], v[138:139], v[186:187]
	v_pk_mul_f32 v[140:141], v[140:141], v[188:189]
	v_pk_mul_f32 v[142:143], v[142:143], v[190:191]
	v_pk_mul_f32 v[136:137], v[136:137], v[196:197]
	v_pk_mul_f32 v[138:139], v[138:139], v[198:199]
	v_pk_mul_f32 v[140:141], v[140:141], v[200:201]
	v_pk_mul_f32 v[142:143], v[142:143], v[202:203]
	v_cvt_pk_bf16_f32 v12, v136, v137
	v_cvt_pk_bf16_f32 v13, v138, v139
	v_cvt_pk_bf16_f32 v14, v140, v141
	v_cvt_pk_bf16_f32 v15, v142, v143
	global_store_dwordx4 v6, v[12:15], s[36:37]
	v_add_u32_e32 v6, 5632, v6
	s_waitcnt vmcnt(25)
; __device__ __forceinline__ unsigned cvt_pk_bf16(float lo, float hi) { unsigned r; asm volatile("v_cvt_pk_bf16_f32 %0, %1, %2" : "=v"(r) : "v"(lo), "v"(hi)); return r; }
; __device__ __forceinline__ float silu_f(float x) { return x * __builtin_amdgcn_rcpf(1.0f + __builtin_amdgcn_exp2f(-LOG2E * x)); }
; __device__ __forceinline__ float bflo(unsigned w) { return __uint_as_float(w << 16); }
; __device__ __forceinline__ float bfhi(unsigned w) { return __uint_as_float(w & 0xffff0000u); }
; __device__ __forceinline__ void conv_phase(const bf16_t* Z, bf16_t* UA, const float* cw, const float* cb, int nrows, int rowoff) {
;     ...
;         for (int rr = 0; rr < 16; ++rr) {
;             u32x4 na = zero, ng = zero; if (rr < 15 || has_right) { na = *(const u32x4*)(zp + (size_t)(rr + 1) * FFN2); ng = *(const u32x4*)(zp + (size_t)(rr + 1) * FFN2 + FFN); }
;             u32x4 o;
; #pragma unroll
;             for (int e2 = 0; e2 < 4; ++e2) {
;                 const float a0 = bflo(pa[e2]) * wa[0][2 * e2] + bflo(ca[e2]) * wa[1][2 * e2] + bflo(na[e2]) * wa[2][2 * e2] + ba[2 * e2];
;                 const float a1 = bfhi(pa[e2]) * wa[0][2 * e2 + 1] + bfhi(ca[e2]) * wa[1][2 * e2 + 1] + bfhi(na[e2]) * wa[2][2 * e2 + 1] + ba[2 * e2 + 1];
;                 const float g0 = bflo(pg[e2]) * wg[0][2 * e2] + bflo(cgv[e2]) * wg[1][2 * e2] + bflo(ng[e2]) * wg[2][2 * e2] + bg[2 * e2];
;                 const float g1 = bfhi(pg[e2]) * wg[0][2 * e2 + 1] + bfhi(cgv[e2]) * wg[1][2 * e2 + 1] + bfhi(ng[e2]) * wg[2][2 * e2 + 1] + bg[2 * e2 + 1];
;                 o[e2] = cvt_pk_bf16(silu_f(a0) * g0, silu_f(a1) * g1); }
;             *(u32x4*)(UA + (size_t)(r0 + rr) * FFN + c0) = o;
;             pa = ca; pg = cgv; ca = na; cgv = ng;
	v_lshlrev_b32_e32 v16, 16, v88
	v_and_b32_e32 v17, s99, v88
	v_lshlrev_b32_e32 v18, 16, v89
	v_and_b32_e32 v19, s99, v89
	v_lshlrev_b32_e32 v20, 16, v90
	v_and_b32_e32 v21, s99, v90
	v_lshlrev_b32_e32 v22, 16, v91
	v_and_b32_e32 v23, s99, v91
	v_lshlrev_b32_e32 v24, 16, v92
	v_and_b32_e32 v25, s99, v92
	v_lshlrev_b32_e32 v26, 16, v93
	v_and_b32_e32 v27, s99, v93
	v_lshlrev_b32_e32 v28, 16, v94
	v_and_b32_e32 v29, s99, v94
	v_lshlrev_b32_e32 v30, 16, v95
	v_and_b32_e32 v31, s99, v95
	v_add_u32_e32 v11, 67085056, v5
	global_load_dwordx4 v[88:91], v11, s[2:3] offset:-2816 nt
	global_load_dwordx4 v[92:95], v11, s[2:3] offset:2816 nt
	v_pk_fma_f32 v[136:137], v[32:33], v[152:153], v[236:237]
	v_pk_fma_f32 v[196:197], v[40:41], v[212:213], v[244:245]
	v_pk_fma_f32 v[138:139], v[34:35], v[154:155], v[238:239]
	v_pk_fma_f32 v[198:199], v[42:43], v[214:215], v[246:247]
	v_pk_fma_f32 v[140:141], v[36:37], v[156:157], v[240:241]
	v_pk_fma_f32 v[200:201], v[44:45], v[216:217], v[248:249]
	v_pk_fma_f32 v[142:143], v[38:39], v[158:159], v[242:243]
	v_pk_fma_f32 v[202:203], v[46:47], v[218:219], v[250:251]
	v_pk_fma_f32 v[136:137], v[48:49], v[160:161], v[136:137]
	v_pk_fma_f32 v[196:197], v[56:57], v[220:221], v[196:197]
	v_pk_fma_f32 v[138:139], v[50:51], v[162:163], v[138:139]
	v_pk_fma_f32 v[198:199], v[58:59], v[222:223], v[198:199]
	v_pk_fma_f32 v[140:141], v[52:53], v[164:165], v[140:141]
	v_pk_fma_f32 v[200:201], v[60:61], v[224:225], v[200:201]
	v_pk_fma_f32 v[142:143], v[54:55], v[166:167], v[142:143]
	v_pk_fma_f32 v[202:203], v[62:63], v[226:227], v[202:203]
	v_pk_fma_f32 v[136:137], v[16:17], v[168:169], v[136:137]
	v_pk_fma_f32 v[196:197], v[24:25], v[228:229], v[196:197]
	v_pk_fma_f32 v[138:139], v[18:19], v[170:171], v[138:139]
	v_pk_fma_f32 v[198:199], v[26:27], v[230:231], v[198:199]
	v_pk_fma_f32 v[140:141], v[20:21], v[172:173], v[140:141]
	v_pk_fma_f32 v[200:201], v[28:29], v[232:233], v[200:201]
	v_pk_fma_f32 v[142:143], v[22:23], v[174:175], v[142:143]
	v_pk_fma_f32 v[202:203], v[30:31], v[234:235], v[202:203]
	v_pk_mul_f32 v[184:185], v[136:137], v[180:181]
	v_pk_mul_f32 v[186:187], v[138:139], v[180:181]
	v_pk_mul_f32 v[188:189], v[140:141], v[180:181]
	v_pk_mul_f32 v[190:191], v[142:143], v[180:181]
	v_exp_f32_e32 v184, v184
	v_exp_f32_e32 v185, v185
	v_exp_f32_e32 v186, v186
	v_exp_f32_e32 v187, v187
	v_exp_f32_e32 v188, v188
	v_exp_f32_e32 v189, v189
	v_exp_f32_e32 v190, v190
	v_exp_f32_e32 v191, v191
	s_nop 0
	v_pk_add_f32 v[184:185], v[184:185], v[144:145]
	v_pk_add_f32 v[186:187], v[186:187], v[144:145]
	v_pk_add_f32 v[188:189], v[188:189], v[144:145]
	v_pk_add_f32 v[190:191], v[190:191], v[144:145]
	v_rcp_f32_e32 v184, v184
	v_rcp_f32_e32 v185, v185
	v_rcp_f32_e32 v186, v186
	v_rcp_f32_e32 v187, v187
	v_rcp_f32_e32 v188, v188
	v_rcp_f32_e32 v189, v189
	v_rcp_f32_e32 v190, v190
	v_rcp_f32_e32 v191, v191
	s_nop 0
	v_pk_mul_f32 v[136:137], v[136:137], v[184:185]
	v_pk_mul_f32 v[138:139], v[138:139], v[186:187]
	v_pk_mul_f32 v[140:141], v[140:141], v[188:189]
	v_pk_mul_f32 v[142:143], v[142:143], v[190:191]
	v_pk_mul_f32 v[136:137], v[136:137], v[196:197]
	v_pk_mul_f32 v[138:139], v[138:139], v[198:199]
	v_pk_mul_f32 v[140:141], v[140:141], v[200:201]
	v_pk_mul_f32 v[142:143], v[142:143], v[202:203]
	v_cvt_pk_bf16_f32 v12, v136, v137
	v_cvt_pk_bf16_f32 v13, v138, v139
	v_cvt_pk_bf16_f32 v14, v140, v141
	v_cvt_pk_bf16_f32 v15, v142, v143
	global_store_dwordx4 v6, v[12:15], s[36:37]
	v_add_u32_e32 v6, 5632, v6
	s_waitcnt vmcnt(25)
	v_lshlrev_b32_e32 v32, 16, v96
	v_and_b32_e32 v33, s99, v96
	v_lshlrev_b32_e32 v34, 16, v97
	v_and_b32_e32 v35, s99, v97
	v_lshlrev_b32_e32 v36, 16, v98
	v_and_b32_e32 v37, s99, v98
	v_lshlrev_b32_e32 v38, 16, v99
	v_and_b32_e32 v39, s99, v99
	v_lshlrev_b32_e32 v40, 16, v100
	v_and_b32_e32 v41, s99, v100
	v_lshlrev_b32_e32 v42, 16, v101
	v_and_b32_e32 v43, s99, v101
	v_lshlrev_b32_e32 v44, 16, v102
	v_and_b32_e32 v45, s99, v102
	v_lshlrev_b32_e32 v46, 16, v103
	v_and_b32_e32 v47, s99, v103
	v_add_u32_e32 v10, 67096320, v5
	global_load_dwordx4 v[96:99], v10, s[2:3] offset:-2816 nt
	global_load_dwordx4 v[100:103], v10, s[2:3] offset:2816 nt
	v_pk_fma_f32 v[136:137], v[48:49], v[152:153], v[236:237]
	v_pk_fma_f32 v[196:197], v[56:57], v[212:213], v[244:245]
	v_pk_fma_f32 v[138:139], v[50:51], v[154:155], v[238:239]
	v_pk_fma_f32 v[198:199], v[58:59], v[214:215], v[246:247]
	v_pk_fma_f32 v[140:141], v[52:53], v[156:157], v[240:241]
	v_pk_fma_f32 v[200:201], v[60:61], v[216:217], v[248:249]
	v_pk_fma_f32 v[142:143], v[54:55], v[158:159], v[242:243]
	v_pk_fma_f32 v[202:203], v[62:63], v[218:219], v[250:251]
	v_pk_fma_f32 v[136:137], v[16:17], v[160:161], v[136:137]
	v_pk_fma_f32 v[196:197], v[24:25], v[220:221], v[196:197]
	v_pk_fma_f32 v[138:139], v[18:19], v[162:163], v[138:139]
	v_pk_fma_f32 v[198:199], v[26:27], v[222:223], v[198:199]
	v_pk_fma_f32 v[140:141], v[20:21], v[164:165], v[140:141]
	v_pk_fma_f32 v[200:201], v[28:29], v[224:225], v[200:201]
	v_pk_fma_f32 v[142:143], v[22:23], v[166:167], v[142:143]
	v_pk_fma_f32 v[202:203], v[30:31], v[226:227], v[202:203]
	v_pk_fma_f32 v[136:137], v[32:33], v[168:169], v[136:137]
	v_pk_fma_f32 v[196:197], v[40:41], v[228:229], v[196:197]
	v_pk_fma_f32 v[138:139], v[34:35], v[170:171], v[138:139]
	v_pk_fma_f32 v[198:199], v[42:43], v[230:231], v[198:199]
	v_pk_fma_f32 v[140:141], v[36:37], v[172:173], v[140:141]
	v_pk_fma_f32 v[200:201], v[44:45], v[232:233], v[200:201]
	v_pk_fma_f32 v[142:143], v[38:39], v[174:175], v[142:143]
	v_pk_fma_f32 v[202:203], v[46:47], v[234:235], v[202:203]
	v_pk_mul_f32 v[184:185], v[136:137], v[180:181]
	v_pk_mul_f32 v[186:187], v[138:139], v[180:181]
	v_pk_mul_f32 v[188:189], v[140:141], v[180:181]
	v_pk_mul_f32 v[190:191], v[142:143], v[180:181]
	v_exp_f32_e32 v184, v184
	v_exp_f32_e32 v185, v185
	v_exp_f32_e32 v186, v186
	v_exp_f32_e32 v187, v187
	v_exp_f32_e32 v188, v188
	v_exp_f32_e32 v189, v189
	v_exp_f32_e32 v190, v190
	v_exp_f32_e32 v191, v191
	s_nop 0
	v_pk_add_f32 v[184:185], v[184:185], v[144:145]
	v_pk_add_f32 v[186:187], v[186:187], v[144:145]
	v_pk_add_f32 v[188:189], v[188:189], v[144:145]
	v_pk_add_f32 v[190:191], v[190:191], v[144:145]
	v_rcp_f32_e32 v184, v184
	v_rcp_f32_e32 v185, v185
	v_rcp_f32_e32 v186, v186
	v_rcp_f32_e32 v187, v187
	v_rcp_f32_e32 v188, v188
	v_rcp_f32_e32 v189, v189
	v_rcp_f32_e32 v190, v190
	v_rcp_f32_e32 v191, v191
	s_nop 0
	v_pk_mul_f32 v[136:137], v[136:137], v[184:185]
	v_pk_mul_f32 v[138:139], v[138:139], v[186:187]
	v_pk_mul_f32 v[140:141], v[140:141], v[188:189]
	v_pk_mul_f32 v[142:143], v[142:143], v[190:191]
	v_pk_mul_f32 v[136:137], v[136:137], v[196:197]
	v_pk_mul_f32 v[138:139], v[138:139], v[198:199]
	v_pk_mul_f32 v[140:141], v[140:141], v[200:201]
	v_pk_mul_f32 v[142:143], v[142:143], v[202:203]
	v_cvt_pk_bf16_f32 v12, v136, v137
	v_cvt_pk_bf16_f32 v13, v138, v139
	v_cvt_pk_bf16_f32 v14, v140, v141
	v_cvt_pk_bf16_f32 v15, v142, v143
	global_store_dwordx4 v6, v[12:15], s[36:37]
	v_add_u32_e32 v6, 5632, v6
	s_waitcnt vmcnt(25)
; __device__ __forceinline__ unsigned cvt_pk_bf16(float lo, float hi) { unsigned r; asm volatile("v_cvt_pk_bf16_f32 %0, %1, %2" : "=v"(r) : "v"(lo), "v"(hi)); return r; }
; __device__ __forceinline__ float silu_f(float x) { return x * __builtin_amdgcn_rcpf(1.0f + __builtin_amdgcn_exp2f(-LOG2E * x)); }
; __device__ __forceinline__ float bflo(unsigned w) { return __uint_as_float(w << 16); }
; __device__ __forceinline__ float bfhi(unsigned w) { return __uint_as_float(w & 0xffff0000u); }
; __device__ __forceinline__ void conv_phase(const bf16_t* Z, bf16_t* UA, const float* cw, const float* cb, int nrows, int rowoff) {
;     ...
;         for (int rr = 0; rr < 16; ++rr) {
;             u32x4 na = zero, ng = zero; if (rr < 15 || has_right) { na = *(const u32x4*)(zp + (size_t)(rr + 1) * FFN2); ng = *(const u32x4*)(zp + (size_t)(rr + 1) * FFN2 + FFN); }
;             u32x4 o;
; #pragma unroll
;             for (int e2 = 0; e2 < 4; ++e2) {
;                 const float a0 = bflo(pa[e2]) * wa[0][2 * e2] + bflo(ca[e2]) * wa[1][2 * e2] + bflo(na[e2]) * wa[2][2 * e2] + ba[2 * e2];
;                 const float a1 = bfhi(pa[e2]) * wa[0][2 * e2 + 1] + bfhi(ca[e2]) * wa[1][2 * e2 + 1] + bfhi(na[e2]) * wa[2][2 * e2 + 1] + ba[2 * e2 + 1];
;                 const float g0 = bflo(pg[e2]) * wg[0][2 * e2] + bflo(cgv[e2]) * wg[1][2 * e2] + bflo(ng[e2]) * wg[2][2 * e2] + bg[2 * e2];
;                 const float g1 = bfhi(pg[e2]) * wg[0][2 * e2 + 1] + bfhi(cgv[e2]) * wg[1][2 * e2 + 1] + bfhi(ng[e2]) * wg[2][2 * e2 + 1] + bg[2 * e2 + 1];
;                 o[e2] = cvt_pk_bf16(silu_f(a0) * g0, silu_f(a1) * g1); }
;             *(u32x4*)(UA + (size_t)(r0 + rr) * FFN + c0) = o;
;             pa = ca; pg = cgv; ca = na; cgv = ng;
	v_lshlrev_b32_e32 v48, 16, v104
	v_and_b32_e32 v49, s99, v104
	v_lshlrev_b32_e32 v50, 16, v105
	v_and_b32_e32 v51, s99, v105
	v_lshlrev_b32_e32 v52, 16, v106
	v_and_b32_e32 v53, s99, v106
	v_lshlrev_b32_e32 v54, 16, v107
	v_and_b32_e32 v55, s99, v107
	v_lshlrev_b32_e32 v56, 16, v108
	v_and_b32_e32 v57, s99, v108
	v_lshlrev_b32_e32 v58, 16, v109
	v_and_b32_e32 v59, s99, v109
	v_lshlrev_b32_e32 v60, 16, v110
	v_and_b32_e32 v61, s99, v110
	v_lshlrev_b32_e32 v62, 16, v111
	v_and_b32_e32 v63, s99, v111
	v_add_u32_e32 v11, 67107584, v5
	global_load_dwordx4 v[104:107], v11, s[2:3] offset:-2816 nt
	global_load_dwordx4 v[108:111], v11, s[2:3] offset:2816 nt
	v_pk_fma_f32 v[136:137], v[16:17], v[152:153], v[236:237]
	v_pk_fma_f32 v[196:197], v[24:25], v[212:213], v[244:245]
	v_pk_fma_f32 v[138:139], v[18:19], v[154:155], v[238:239]
	v_pk_fma_f32 v[198:199], v[26:27], v[214:215], v[246:247]
	v_pk_fma_f32 v[140:141], v[20:21], v[156:157], v[240:241]
	v_pk_fma_f32 v[200:201], v[28:29], v[216:217], v[248:249]
	v_pk_fma_f32 v[142:143], v[22:23], v[158:159], v[242:243]
	v_pk_fma_f32 v[202:203], v[30:31], v[218:219], v[250:251]
	v_pk_fma_f32 v[136:137], v[32:33], v[160:161], v[136:137]
	v_pk_fma_f32 v[196:197], v[40:41], v[220:221], v[196:197]
	v_pk_fma_f32 v[138:139], v[34:35], v[162:163], v[138:139]
	v_pk_fma_f32 v[198:199], v[42:43], v[222:223], v[198:199]
	v_pk_fma_f32 v[140:141], v[36:37], v[164:165], v[140:141]
	v_pk_fma_f32 v[200:201], v[44:45], v[224:225], v[200:201]
	v_pk_fma_f32 v[142:143], v[38:39], v[166:167], v[142:143]
	v_pk_fma_f32 v[202:203], v[46:47], v[226:227], v[202:203]
	v_pk_fma_f32 v[136:137], v[48:49], v[168:169], v[136:137]
	v_pk_fma_f32 v[196:197], v[56:57], v[228:229], v[196:197]
	v_pk_fma_f32 v[138:139], v[50:51], v[170:171], v[138:139]
	v_pk_fma_f32 v[198:199], v[58:59], v[230:231], v[198:199]
	v_pk_fma_f32 v[140:141], v[52:53], v[172:173], v[140:141]
	v_pk_fma_f32 v[200:201], v[60:61], v[232:233], v[200:201]
	v_pk_fma_f32 v[142:143], v[54:55], v[174:175], v[142:143]
	v_pk_fma_f32 v[202:203], v[62:63], v[234:235], v[202:203]
	v_pk_mul_f32 v[184:185], v[136:137], v[180:181]
	v_pk_mul_f32 v[186:187], v[138:139], v[180:181]
	v_pk_mul_f32 v[188:189], v[140:141], v[180:181]
	v_pk_mul_f32 v[190:191], v[142:143], v[180:181]
	v_exp_f32_e32 v184, v184
	v_exp_f32_e32 v185, v185
	v_exp_f32_e32 v186, v186
	v_exp_f32_e32 v187, v187
	v_exp_f32_e32 v188, v188
	v_exp_f32_e32 v189, v189
	v_exp_f32_e32 v190, v190
	v_exp_f32_e32 v191, v191
	s_nop 0
	v_pk_add_f32 v[184:185], v[184:185], v[144:145]
	v_pk_add_f32 v[186:187], v[186:187], v[144:145]
	v_pk_add_f32 v[188:189], v[188:189], v[144:145]
	v_pk_add_f32 v[190:191], v[190:191], v[144:145]
	v_rcp_f32_e32 v184, v184
	v_rcp_f32_e32 v185, v185
	v_rcp_f32_e32 v186, v186
	v_rcp_f32_e32 v187, v187
	v_rcp_f32_e32 v188, v188
	v_rcp_f32_e32 v189, v189
	v_rcp_f32_e32 v190, v190
	v_rcp_f32_e32 v191, v191
	s_nop 0
	v_pk_mul_f32 v[136:137], v[136:137], v[184:185]
	v_pk_mul_f32 v[138:139], v[138:139], v[186:187]
	v_pk_mul_f32 v[140:141], v[140:141], v[188:189]
	v_pk_mul_f32 v[142:143], v[142:143], v[190:191]
	v_pk_mul_f32 v[136:137], v[136:137], v[196:197]
	v_pk_mul_f32 v[138:139], v[138:139], v[198:199]
	v_pk_mul_f32 v[140:141], v[140:141], v[200:201]
	v_pk_mul_f32 v[142:143], v[142:143], v[202:203]
	v_cvt_pk_bf16_f32 v12, v136, v137
	v_cvt_pk_bf16_f32 v13, v138, v139
	v_cvt_pk_bf16_f32 v14, v140, v141
	v_cvt_pk_bf16_f32 v15, v142, v143
	global_store_dwordx4 v6, v[12:15], s[36:37]
	v_add_u32_e32 v6, 5632, v6
	s_waitcnt vmcnt(25)
	v_lshlrev_b32_e32 v16, 16, v112
	v_and_b32_e32 v17, s99, v112
	v_lshlrev_b32_e32 v18, 16, v113
	v_and_b32_e32 v19, s99, v113
	v_lshlrev_b32_e32 v20, 16, v114
	v_and_b32_e32 v21, s99, v114
	v_lshlrev_b32_e32 v22, 16, v115
	v_and_b32_e32 v23, s99, v115
	v_lshlrev_b32_e32 v24, 16, v116
	v_and_b32_e32 v25, s99, v116
	v_lshlrev_b32_e32 v26, 16, v117
	v_and_b32_e32 v27, s99, v117
	v_lshlrev_b32_e32 v28, 16, v118
	v_and_b32_e32 v29, s99, v118
	v_lshlrev_b32_e32 v30, 16, v119
	v_and_b32_e32 v31, s99, v119
	v_add_u32_e32 v10, 67118848, v5
	global_load_dwordx4 v[112:115], v10, s[2:3] offset:-2816 nt
	global_load_dwordx4 v[116:119], v10, s[2:3] offset:2816 nt
	v_pk_fma_f32 v[136:137], v[32:33], v[152:153], v[236:237]
	v_pk_fma_f32 v[196:197], v[40:41], v[212:213], v[244:245]
	v_pk_fma_f32 v[138:139], v[34:35], v[154:155], v[238:239]
	v_pk_fma_f32 v[198:199], v[42:43], v[214:215], v[246:247]
	v_pk_fma_f32 v[140:141], v[36:37], v[156:157], v[240:241]
	v_pk_fma_f32 v[200:201], v[44:45], v[216:217], v[248:249]
	v_pk_fma_f32 v[142:143], v[38:39], v[158:159], v[242:243]
	v_pk_fma_f32 v[202:203], v[46:47], v[218:219], v[250:251]
	v_pk_fma_f32 v[136:137], v[48:49], v[160:161], v[136:137]
	v_pk_fma_f32 v[196:197], v[56:57], v[220:221], v[196:197]
	v_pk_fma_f32 v[138:139], v[50:51], v[162:163], v[138:139]
	v_pk_fma_f32 v[198:199], v[58:59], v[222:223], v[198:199]
	v_pk_fma_f32 v[140:141], v[52:53], v[164:165], v[140:141]
	v_pk_fma_f32 v[200:201], v[60:61], v[224:225], v[200:201]
	v_pk_fma_f32 v[142:143], v[54:55], v[166:167], v[142:143]
	v_pk_fma_f32 v[202:203], v[62:63], v[226:227], v[202:203]
	v_pk_fma_f32 v[136:137], v[16:17], v[168:169], v[136:137]
	v_pk_fma_f32 v[196:197], v[24:25], v[228:229], v[196:197]
	v_pk_fma_f32 v[138:139], v[18:19], v[170:171], v[138:139]
	v_pk_fma_f32 v[198:199], v[26:27], v[230:231], v[198:199]
	v_pk_fma_f32 v[140:141], v[20:21], v[172:173], v[140:141]
	v_pk_fma_f32 v[200:201], v[28:29], v[232:233], v[200:201]
	v_pk_fma_f32 v[142:143], v[22:23], v[174:175], v[142:143]
	v_pk_fma_f32 v[202:203], v[30:31], v[234:235], v[202:203]
	v_pk_mul_f32 v[184:185], v[136:137], v[180:181]
; __device__ __forceinline__ unsigned cvt_pk_bf16(float lo, float hi) { unsigned r; asm volatile("v_cvt_pk_bf16_f32 %0, %1, %2" : "=v"(r) : "v"(lo), "v"(hi)); return r; }
; __device__ __forceinline__ float silu_f(float x) { return x * __builtin_amdgcn_rcpf(1.0f + __builtin_amdgcn_exp2f(-LOG2E * x)); }
; __device__ __forceinline__ float bflo(unsigned w) { return __uint_as_float(w << 16); }
; __device__ __forceinline__ float bfhi(unsigned w) { return __uint_as_float(w & 0xffff0000u); }
; __device__ __forceinline__ void conv_phase(const bf16_t* Z, bf16_t* UA, const float* cw, const float* cb, int nrows, int rowoff) {
;     ...
;         for (int rr = 0; rr < 16; ++rr) {
;             u32x4 na = zero, ng = zero; if (rr < 15 || has_right) { na = *(const u32x4*)(zp + (size_t)(rr + 1) * FFN2); ng = *(const u32x4*)(zp + (size_t)(rr + 1) * FFN2 + FFN); }
;             u32x4 o;
; #pragma unroll
;             for (int e2 = 0; e2 < 4; ++e2) {
;                 const float a0 = bflo(pa[e2]) * wa[0][2 * e2] + bflo(ca[e2]) * wa[1][2 * e2] + bflo(na[e2]) * wa[2][2 * e2] + ba[2 * e2];
;                 const float a1 = bfhi(pa[e2]) * wa[0][2 * e2 + 1] + bfhi(ca[e2]) * wa[1][2 * e2 + 1] + bfhi(na[e2]) * wa[2][2 * e2 + 1] + ba[2 * e2 + 1];
;                 const float g0 = bflo(pg[e2]) * wg[0][2 * e2] + bflo(cgv[e2]) * wg[1][2 * e2] + bflo(ng[e2]) * wg[2][2 * e2] + bg[2 * e2];
;                 const float g1 = bfhi(pg[e2]) * wg[0][2 * e2 + 1] + bfhi(cgv[e2]) * wg[1][2 * e2 + 1] + bfhi(ng[e2]) * wg[2][2 * e2 + 1] + bg[2 * e2 + 1];
;                 o[e2] = cvt_pk_bf16(silu_f(a0) * g0, silu_f(a1) * g1); }
;             *(u32x4*)(UA + (size_t)(r0 + rr) * FFN + c0) = o;
;             pa = ca; pg = cgv; ca = na; cgv = ng;
	v_pk_mul_f32 v[186:187], v[138:139], v[180:181]
	v_pk_mul_f32 v[188:189], v[140:141], v[180:181]
	v_pk_mul_f32 v[190:191], v[142:143], v[180:181]
	v_exp_f32_e32 v184, v184
	v_exp_f32_e32 v185, v185
	v_exp_f32_e32 v186, v186
	v_exp_f32_e32 v187, v187
	v_exp_f32_e32 v188, v188
	v_exp_f32_e32 v189, v189
	v_exp_f32_e32 v190, v190
	v_exp_f32_e32 v191, v191
	s_nop 0
	v_pk_add_f32 v[184:185], v[184:185], v[144:145]
	v_pk_add_f32 v[186:187], v[186:187], v[144:145]
	v_pk_add_f32 v[188:189], v[188:189], v[144:145]
	v_pk_add_f32 v[190:191], v[190:191], v[144:145]
	v_rcp_f32_e32 v184, v184
	v_rcp_f32_e32 v185, v185
	v_rcp_f32_e32 v186, v186
	v_rcp_f32_e32 v187, v187
	v_rcp_f32_e32 v188, v188
	v_rcp_f32_e32 v189, v189
	v_rcp_f32_e32 v190, v190
	v_rcp_f32_e32 v191, v191
	s_nop 0
	v_pk_mul_f32 v[136:137], v[136:137], v[184:185]
	v_pk_mul_f32 v[138:139], v[138:139], v[186:187]
	v_pk_mul_f32 v[140:141], v[140:141], v[188:189]
	v_pk_mul_f32 v[142:143], v[142:143], v[190:191]
	v_pk_mul_f32 v[136:137], v[136:137], v[196:197]
	v_pk_mul_f32 v[138:139], v[138:139], v[198:199]
	v_pk_mul_f32 v[140:141], v[140:141], v[200:201]
	v_pk_mul_f32 v[142:143], v[142:143], v[202:203]
	v_cvt_pk_bf16_f32 v12, v136, v137
	v_cvt_pk_bf16_f32 v13, v138, v139
	v_cvt_pk_bf16_f32 v14, v140, v141
	v_cvt_pk_bf16_f32 v15, v142, v143
	global_store_dwordx4 v6, v[12:15], s[36:37]
	v_add_u32_e32 v6, 5632, v6
	s_waitcnt vmcnt(25)
	v_lshlrev_b32_e32 v32, 16, v120
	v_and_b32_e32 v33, s99, v120
	v_lshlrev_b32_e32 v34, 16, v121
	v_and_b32_e32 v35, s99, v121
	v_lshlrev_b32_e32 v36, 16, v122
	v_and_b32_e32 v37, s99, v122
	v_lshlrev_b32_e32 v38, 16, v123
	v_and_b32_e32 v39, s99, v123
	v_lshlrev_b32_e32 v40, 16, v124
	v_and_b32_e32 v41, s99, v124
	v_lshlrev_b32_e32 v42, 16, v125
	v_and_b32_e32 v43, s99, v125
	v_lshlrev_b32_e32 v44, 16, v126
	v_and_b32_e32 v45, s99, v126
	v_lshlrev_b32_e32 v46, 16, v127
	v_and_b32_e32 v47, s99, v127
	v_add_u32_e32 v11, 67130112, v5
	global_load_dwordx4 v[120:123], v11, s[2:3] offset:-2816 nt
	global_load_dwordx4 v[124:127], v11, s[2:3] offset:2816 nt
	v_pk_fma_f32 v[136:137], v[48:49], v[152:153], v[236:237]
	v_pk_fma_f32 v[196:197], v[56:57], v[212:213], v[244:245]
	v_pk_fma_f32 v[138:139], v[50:51], v[154:155], v[238:239]
	v_pk_fma_f32 v[198:199], v[58:59], v[214:215], v[246:247]
	v_pk_fma_f32 v[140:141], v[52:53], v[156:157], v[240:241]
	v_pk_fma_f32 v[200:201], v[60:61], v[216:217], v[248:249]
	v_pk_fma_f32 v[142:143], v[54:55], v[158:159], v[242:243]
	v_pk_fma_f32 v[202:203], v[62:63], v[218:219], v[250:251]
	v_pk_fma_f32 v[136:137], v[16:17], v[160:161], v[136:137]
	v_pk_fma_f32 v[196:197], v[24:25], v[220:221], v[196:197]
	v_pk_fma_f32 v[138:139], v[18:19], v[162:163], v[138:139]
	v_pk_fma_f32 v[198:199], v[26:27], v[222:223], v[198:199]
	v_pk_fma_f32 v[140:141], v[20:21], v[164:165], v[140:141]
	v_pk_fma_f32 v[200:201], v[28:29], v[224:225], v[200:201]
	v_pk_fma_f32 v[142:143], v[22:23], v[166:167], v[142:143]
	v_pk_fma_f32 v[202:203], v[30:31], v[226:227], v[202:203]
	v_pk_fma_f32 v[136:137], v[32:33], v[168:169], v[136:137]
	v_pk_fma_f32 v[196:197], v[40:41], v[228:229], v[196:197]
	v_pk_fma_f32 v[138:139], v[34:35], v[170:171], v[138:139]
	v_pk_fma_f32 v[198:199], v[42:43], v[230:231], v[198:199]
	v_pk_fma_f32 v[140:141], v[36:37], v[172:173], v[140:141]
	v_pk_fma_f32 v[200:201], v[44:45], v[232:233], v[200:201]
	v_pk_fma_f32 v[142:143], v[38:39], v[174:175], v[142:143]
	v_pk_fma_f32 v[202:203], v[46:47], v[234:235], v[202:203]
	v_pk_mul_f32 v[184:185], v[136:137], v[180:181]
	v_pk_mul_f32 v[186:187], v[138:139], v[180:181]
	v_pk_mul_f32 v[188:189], v[140:141], v[180:181]
	v_pk_mul_f32 v[190:191], v[142:143], v[180:181]
	v_exp_f32_e32 v184, v184
	v_exp_f32_e32 v185, v185
	v_exp_f32_e32 v186, v186
	v_exp_f32_e32 v187, v187
	v_exp_f32_e32 v188, v188
	v_exp_f32_e32 v189, v189
	v_exp_f32_e32 v190, v190
	v_exp_f32_e32 v191, v191
	s_nop 0
	v_pk_add_f32 v[184:185], v[184:185], v[144:145]
	v_pk_add_f32 v[186:187], v[186:187], v[144:145]
	v_pk_add_f32 v[188:189], v[188:189], v[144:145]
	v_pk_add_f32 v[190:191], v[190:191], v[144:145]
	v_rcp_f32_e32 v184, v184
	v_rcp_f32_e32 v185, v185
	v_rcp_f32_e32 v186, v186
	v_rcp_f32_e32 v187, v187
	v_rcp_f32_e32 v188, v188
	v_rcp_f32_e32 v189, v189
	v_rcp_f32_e32 v190, v190
	v_rcp_f32_e32 v191, v191
	s_nop 0
	v_pk_mul_f32 v[136:137], v[136:137], v[184:185]
	v_pk_mul_f32 v[138:139], v[138:139], v[186:187]
	v_pk_mul_f32 v[140:141], v[140:141], v[188:189]
	v_pk_mul_f32 v[142:143], v[142:143], v[190:191]
	v_pk_mul_f32 v[136:137], v[136:137], v[196:197]
	v_pk_mul_f32 v[138:139], v[138:139], v[198:199]
	v_pk_mul_f32 v[140:141], v[140:141], v[200:201]
	v_pk_mul_f32 v[142:143], v[142:143], v[202:203]
	v_cvt_pk_bf16_f32 v12, v136, v137
	v_cvt_pk_bf16_f32 v13, v138, v139
	v_cvt_pk_bf16_f32 v14, v140, v141
	v_cvt_pk_bf16_f32 v15, v142, v143
	global_store_dwordx4 v6, v[12:15], s[36:37]
	v_add_u32_e32 v6, 5632, v6
	s_waitcnt vmcnt(25)
; __device__ __forceinline__ unsigned cvt_pk_bf16(float lo, float hi) { unsigned r; asm volatile("v_cvt_pk_bf16_f32 %0, %1, %2" : "=v"(r) : "v"(lo), "v"(hi)); return r; }
; __device__ __forceinline__ float silu_f(float x) { return x * __builtin_amdgcn_rcpf(1.0f + __builtin_amdgcn_exp2f(-LOG2E * x)); }
; __device__ __forceinline__ float bflo(unsigned w) { return __uint_as_float(w << 16); }
; __device__ __forceinline__ float bfhi(unsigned w) { return __uint_as_float(w & 0xffff0000u); }
; __device__ __forceinline__ void conv_phase(const bf16_t* Z, bf16_t* UA, const float* cw, const float* cb, int nrows, int rowoff) {
;     ...
;         for (int rr = 0; rr < 16; ++rr) {
;             u32x4 na = zero, ng = zero; if (rr < 15 || has_right) { na = *(const u32x4*)(zp + (size_t)(rr + 1) * FFN2); ng = *(const u32x4*)(zp + (size_t)(rr + 1) * FFN2 + FFN); }
;             u32x4 o;
; #pragma unroll
;             for (int e2 = 0; e2 < 4; ++e2) {
;                 const float a0 = bflo(pa[e2]) * wa[0][2 * e2] + bflo(ca[e2]) * wa[1][2 * e2] + bflo(na[e2]) * wa[2][2 * e2] + ba[2 * e2];
;                 const float a1 = bfhi(pa[e2]) * wa[0][2 * e2 + 1] + bfhi(ca[e2]) * wa[1][2 * e2 + 1] + bfhi(na[e2]) * wa[2][2 * e2 + 1] + ba[2 * e2 + 1];
;                 const float g0 = bflo(pg[e2]) * wg[0][2 * e2] + bflo(cgv[e2]) * wg[1][2 * e2] + bflo(ng[e2]) * wg[2][2 * e2] + bg[2 * e2];
;                 const float g1 = bfhi(pg[e2]) * wg[0][2 * e2 + 1] + bfhi(cgv[e2]) * wg[1][2 * e2 + 1] + bfhi(ng[e2]) * wg[2][2 * e2 + 1] + bg[2 * e2 + 1];
;                 o[e2] = cvt_pk_bf16(silu_f(a0) * g0, silu_f(a1) * g1); }
;             *(u32x4*)(UA + (size_t)(r0 + rr) * FFN + c0) = o;
;             pa = ca; pg = cgv; ca = na; cgv = ng;
;         }
	v_cndmask_b32_e64 v128, 0, v128, s[100:101]
	v_cndmask_b32_e64 v129, 0, v129, s[100:101]
	v_cndmask_b32_e64 v130, 0, v130, s[100:101]
	v_cndmask_b32_e64 v131, 0, v131, s[100:101]
	v_cndmask_b32_e64 v132, 0, v132, s[100:101]
	v_cndmask_b32_e64 v133, 0, v133, s[100:101]
	v_cndmask_b32_e64 v134, 0, v134, s[100:101]
	v_cndmask_b32_e64 v135, 0, v135, s[100:101]
	v_lshlrev_b32_e32 v48, 16, v128
	v_and_b32_e32 v49, s99, v128
	v_lshlrev_b32_e32 v50, 16, v129
	v_and_b32_e32 v51, s99, v129
	v_lshlrev_b32_e32 v52, 16, v130
	v_and_b32_e32 v53, s99, v130
	v_lshlrev_b32_e32 v54, 16, v131
	v_and_b32_e32 v55, s99, v131
	v_lshlrev_b32_e32 v56, 16, v132
	v_and_b32_e32 v57, s99, v132
	v_lshlrev_b32_e32 v58, 16, v133
	v_and_b32_e32 v59, s99, v133
	v_lshlrev_b32_e32 v60, 16, v134
	v_and_b32_e32 v61, s99, v134
	v_lshlrev_b32_e32 v62, 16, v135
	v_and_b32_e32 v63, s99, v135
	v_add_u32_e32 v10, 67141376, v5
	global_load_dwordx4 v[128:131], v10, s[2:3] offset:-2816 nt
	global_load_dwordx4 v[132:135], v10, s[2:3] offset:2816 nt
	v_pk_fma_f32 v[136:137], v[16:17], v[152:153], v[236:237]
	v_pk_fma_f32 v[196:197], v[24:25], v[212:213], v[244:245]
	v_pk_fma_f32 v[138:139], v[18:19], v[154:155], v[238:239]
	v_pk_fma_f32 v[198:199], v[26:27], v[214:215], v[246:247]
	v_pk_fma_f32 v[140:141], v[20:21], v[156:157], v[240:241]
	v_pk_fma_f32 v[200:201], v[28:29], v[216:217], v[248:249]
	v_pk_fma_f32 v[142:143], v[22:23], v[158:159], v[242:243]
	v_pk_fma_f32 v[202:203], v[30:31], v[218:219], v[250:251]
	v_pk_fma_f32 v[136:137], v[32:33], v[160:161], v[136:137]
	v_pk_fma_f32 v[196:197], v[40:41], v[220:221], v[196:197]
	v_pk_fma_f32 v[138:139], v[34:35], v[162:163], v[138:139]
	v_pk_fma_f32 v[198:199], v[42:43], v[222:223], v[198:199]
	v_pk_fma_f32 v[140:141], v[36:37], v[164:165], v[140:141]
	v_pk_fma_f32 v[200:201], v[44:45], v[224:225], v[200:201]
	v_pk_fma_f32 v[142:143], v[38:39], v[166:167], v[142:143]
	v_pk_fma_f32 v[202:203], v[46:47], v[226:227], v[202:203]
	v_pk_fma_f32 v[136:137], v[48:49], v[168:169], v[136:137]
	v_pk_fma_f32 v[196:197], v[56:57], v[228:229], v[196:197]
	v_pk_fma_f32 v[138:139], v[50:51], v[170:171], v[138:139]
	v_pk_fma_f32 v[198:199], v[58:59], v[230:231], v[198:199]
	v_pk_fma_f32 v[140:141], v[52:53], v[172:173], v[140:141]
	v_pk_fma_f32 v[200:201], v[60:61], v[232:233], v[200:201]
	v_pk_fma_f32 v[142:143], v[54:55], v[174:175], v[142:143]
	v_pk_fma_f32 v[202:203], v[62:63], v[234:235], v[202:203]
	v_pk_mul_f32 v[184:185], v[136:137], v[180:181]
	v_pk_mul_f32 v[186:187], v[138:139], v[180:181]
	v_pk_mul_f32 v[188:189], v[140:141], v[180:181]
	v_pk_mul_f32 v[190:191], v[142:143], v[180:181]
	v_exp_f32_e32 v184, v184
	v_exp_f32_e32 v185, v185
	v_exp_f32_e32 v186, v186
	v_exp_f32_e32 v187, v187
	v_exp_f32_e32 v188, v188
	v_exp_f32_e32 v189, v189
	v_exp_f32_e32 v190, v190
	v_exp_f32_e32 v191, v191
	s_nop 0
	v_pk_add_f32 v[184:185], v[184:185], v[144:145]
	v_pk_add_f32 v[186:187], v[186:187], v[144:145]
	v_pk_add_f32 v[188:189], v[188:189], v[144:145]
	v_pk_add_f32 v[190:191], v[190:191], v[144:145]
	v_rcp_f32_e32 v184, v184
	v_rcp_f32_e32 v185, v185
	v_rcp_f32_e32 v186, v186
	v_rcp_f32_e32 v187, v187
	v_rcp_f32_e32 v188, v188
	v_rcp_f32_e32 v189, v189
	v_rcp_f32_e32 v190, v190
	v_rcp_f32_e32 v191, v191
	s_nop 0
	v_pk_mul_f32 v[136:137], v[136:137], v[184:185]
	v_pk_mul_f32 v[138:139], v[138:139], v[186:187]
	v_pk_mul_f32 v[140:141], v[140:141], v[188:189]
	v_pk_mul_f32 v[142:143], v[142:143], v[190:191]
	v_pk_mul_f32 v[136:137], v[136:137], v[196:197]
	v_pk_mul_f32 v[138:139], v[138:139], v[198:199]
	v_pk_mul_f32 v[140:141], v[140:141], v[200:201]
	v_pk_mul_f32 v[142:143], v[142:143], v[202:203]
	v_cvt_pk_bf16_f32 v12, v136, v137
	v_cvt_pk_bf16_f32 v13, v138, v139
	v_cvt_pk_bf16_f32 v14, v140, v141
	v_cvt_pk_bf16_f32 v15, v142, v143
	global_store_dwordx4 v6, v[12:15], s[36:37]
	v_add_u32_e32 v5, 67043328, v5
	v_add_u32_e32 v6, 33437184, v6
	v_add_u32_e32 v7, 372, v7
	v_add_u32_e32 v2, 372, v2
	s_add_u32 s98, s98, 1
	s_cmp_lt_u32 s98, 6
	s_cbranch_scc1 .Lconv_item_l0

; __device__ __forceinline__ int tid_fresh() { int t = (int)threadIdx.x; asm volatile("" : "+v"(t)); return t; }
; __device__ __forceinline__ void conv_phase(const bf16_t* Z, bf16_t* UA, const float* cw, const float* cb, int nrows, int rowoff) {
;     const int gtid = blockIdx.x * 512 + tid_fresh(), NT = gridDim.x * 512; const int total = (nrows / 16) * 352;
;     for (int idx = gtid; idx < total; idx += NT) {
;         const int cgp = idx % 352, rb = idx / 352, c0 = cgp * 8, r0 = rb * 16, grow0 = rowoff + r0;
;         const int seg = grow0 < MLAT ? SEQ : CTXL; const bool has_left = (grow0 & (seg - 1)) != 0, has_right = ((grow0 + 16) & (seg - 1)) != 0;
;         float wa[3][8], wg[3][8], ba[8], bg[8];
; #pragma unroll
;         for (int j = 0; j < 3; ++j)
; #pragma unroll
;             for (int h = 0; h < 2; ++h) { const f32x4 x = *(const f32x4*)(cw + j * FFN2 + c0 + 4 * h), y = *(const f32x4*)(cw + j * FFN2 + FFN + c0 + 4 * h);
; #pragma unroll
;                 for (int e = 0; e < 4; ++e) { wa[j][4 * h + e] = x[e]; wg[j][4 * h + e] = y[e]; } }
; #pragma unroll
;         for (int h = 0; h < 2; ++h) { const f32x4 x = *(const f32x4*)(cb + c0 + 4 * h), y = *(const f32x4*)(cb + FFN + c0 + 4 * h);
; #pragma unroll
;             for (int e = 0; e < 4; ++e) { ba[4 * h + e] = x[e]; bg[4 * h + e] = y[e]; } }
;         const bf16_t* zp = Z + (size_t)r0 * FFN2 + c0; const u32x4 zero = (u32x4){0u, 0u, 0u, 0u};
;         u32x4 pa = zero, pg = zero; if (has_left) { pa = *(const u32x4*)(zp - FFN2); pg = *(const u32x4*)(zp - FFN2 + FFN); }
;         u32x4 ca = *(const u32x4*)(zp), cgv = *(const u32x4*)(zp + FFN);
; #pragma unroll 4
;         for (int rr = 0; rr < 16; ++rr) {
;             u32x4 na = zero, ng = zero; if (rr < 15 || has_right) { na = *(const u32x4*)(zp + (size_t)(rr + 1) * FFN2); ng = *(const u32x4*)(zp + (size_t)(rr + 1) * FFN2 + FFN); }
.LBB0_1101:
	s_or_b64 exec, exec, s[2:3]
	v_mov_b32_e32 v1, v204
	v_readlane_b32 s2, v255, 17
	s_waitcnt lgkmcnt(0)
	s_barrier
	s_xor_b64 s[88:89], s[40:41], -1
	v_readlane_b32 s2, v254, 21
	v_readlane_b32 s3, v254, 22
	v_readlane_b32 s98, v255, 17
	s_load_dwordx2 s[38:39], s[2:3], 0x98
	s_load_dwordx2 s[40:41], s[2:3], 0xa0
	s_add_u32 s30, s54, 0x23a00000
	s_addc_u32 s31, s55, 0
	v_mov_b32_e32 v180, 0xbfb8aa3b
	v_mov_b32_e32 v181, 0xbfb8aa3b
	v_mov_b32_e32 v144, 1.0
	v_mov_b32_e32 v145, 1.0
	v_add_u32_e32 v1, s98, v204
	s_mov_b32 s99, 0x2e8ba2e9
	v_mul_hi_u32 v2, v1, s99
	v_lshrrev_b32_e32 v2, 6, v2
	v_mul_u32_u24_e32 v3, 0x160, v2
	v_sub_u32_e32 v3, v1, v3
	v_lshlrev_b32_e32 v4, 5, v3
	v_mul_u32_u24_e32 v5, 180224, v2
	v_lshl_add_u32 v5, v3, 4, v5
	v_mul_u32_u24_e32 v6, 90112, v2
	v_lshl_add_u32 v6, v3, 4, v6
	s_lshr_b32 s99, s43, 4
	v_add_u32_e32 v7, s99, v2
	s_waitcnt lgkmcnt(0)
	s_sub_u32 s2, s64, 0x4000
	s_subb_u32 s3, s65, 0
	s_add_u32 s38, s38, 67584
	s_addc_u32 s39, s39, 0
	s_add_u32 s40, s40, 22528
	s_addc_u32 s41, s41, 0
	s_mov_b32 s98, 0
	s_mov_b32 s99, 0xffff0000
	global_load_dwordx4 v[152:155], v4, s[38:39]
	global_load_dwordx4 v[156:159], v4, s[38:39] offset:16
	v_add_u32_e32 v10, 11264, v4
	global_load_dwordx4 v[212:215], v10, s[38:39]
	global_load_dwordx4 v[216:219], v10, s[38:39] offset:16
	v_add_u32_e32 v11, 22528, v4
	global_load_dwordx4 v[160:163], v11, s[38:39]
	global_load_dwordx4 v[164:167], v11, s[38:39] offset:16
	v_add_u32_e32 v10, 33792, v4
	global_load_dwordx4 v[220:223], v10, s[38:39]
	global_load_dwordx4 v[224:227], v10, s[38:39] offset:16
	v_add_u32_e32 v11, 45056, v4
	global_load_dwordx4 v[168:171], v11, s[38:39]
	global_load_dwordx4 v[172:175], v11, s[38:39] offset:16
	v_add_u32_e32 v10, 56320, v4
	global_load_dwordx4 v[228:231], v10, s[38:39]
	global_load_dwordx4 v[232:235], v10, s[38:39] offset:16
	global_load_dwordx4 v[236:239], v4, s[40:41]
	global_load_dwordx4 v[240:243], v4, s[40:41] offset:16
	v_add_u32_e32 v11, 11264, v4
	global_load_dwordx4 v[244:247], v11, s[40:41]
	global_load_dwordx4 v[248:251], v11, s[40:41] offset:16
	v_add_u32_e32 v10, 7936, v5
	global_load_dwordx4 v[64:67], v10, s[2:3] offset:-2816 nt
	global_load_dwordx4 v[68:71], v10, s[2:3] offset:2816 nt
	global_load_dword v252, v4, s[40:41]
	v_add_u32_e32 v11, 19200, v5
	global_load_dwordx4 v[72:75], v11, s[2:3] offset:-2816 nt
	global_load_dwordx4 v[76:79], v11, s[2:3] offset:2816 nt
	global_load_dword v252, v4, s[40:41]
	v_add_u32_e32 v10, 30464, v5
	global_load_dwordx4 v[80:83], v10, s[2:3] offset:-2816 nt
	global_load_dwordx4 v[84:87], v10, s[2:3] offset:2816 nt
	global_load_dword v252, v4, s[40:41]
	v_add_u32_e32 v11, 41728, v5
	global_load_dwordx4 v[88:91], v11, s[2:3] offset:-2816 nt
	global_load_dwordx4 v[92:95], v11, s[2:3] offset:2816 nt
	global_load_dword v252, v4, s[40:41]
	v_add_u32_e32 v10, 52992, v5
	global_load_dwordx4 v[96:99], v10, s[2:3] offset:-2816 nt
	global_load_dwordx4 v[100:103], v10, s[2:3] offset:2816 nt
	global_load_dword v252, v4, s[40:41]
	v_add_u32_e32 v11, 64256, v5
	global_load_dwordx4 v[104:107], v11, s[2:3] offset:-2816 nt
	global_load_dwordx4 v[108:111], v11, s[2:3] offset:2816 nt
	global_load_dword v252, v4, s[40:41]
	v_add_u32_e32 v10, 75520, v5
	global_load_dwordx4 v[112:115], v10, s[2:3] offset:-2816 nt
	global_load_dwordx4 v[116:119], v10, s[2:3] offset:2816 nt
	global_load_dword v252, v4, s[40:41]
	v_add_u32_e32 v11, 86784, v5
	global_load_dwordx4 v[120:123], v11, s[2:3] offset:-2816 nt
	global_load_dwordx4 v[124:127], v11, s[2:3] offset:2816 nt
	global_load_dword v252, v4, s[40:41]
	v_add_u32_e32 v10, 98048, v5
	global_load_dwordx4 v[128:131], v10, s[2:3] offset:-2816 nt
	global_load_dwordx4 v[132:135], v10, s[2:3] offset:2816 nt
	global_load_dword v252, v4, s[40:41]
.Lconv_item_l1:
	v_cmp_gt_u32_e32 vcc, 0x800, v2
	s_nop 4
	s_cbranch_vccz .Lconv_done_l1
	v_mov_b32_e32 v9, 0x1ff
	v_cmp_gt_u32_e32 vcc, 0x1000, v7
	s_nop 1
	v_cndmask_b32_e32 v8, 15, v9, vcc
	v_and_b32_e32 v9, v7, v8
	v_cmp_ne_u32_e64 s[34:35], 0, v9
	v_add_u32_e32 v9, 1, v7
	v_and_b32_e32 v9, v9, v8
	v_cmp_ne_u32_e64 s[100:101], 0, v9
	s_waitcnt vmcnt(25)
	v_cndmask_b32_e64 v64, 0, v64, s[34:35]
	v_cndmask_b32_e64 v65, 0, v65, s[34:35]
	v_cndmask_b32_e64 v66, 0, v66, s[34:35]
	v_cndmask_b32_e64 v67, 0, v67, s[34:35]
	v_cndmask_b32_e64 v68, 0, v68, s[34:35]
	v_cndmask_b32_e64 v69, 0, v69, s[34:35]
	v_cndmask_b32_e64 v70, 0, v70, s[34:35]
	v_cndmask_b32_e64 v71, 0, v71, s[34:35]
	v_lshlrev_b32_e32 v16, 16, v64
	v_and_b32_e32 v17, s99, v64
	v_lshlrev_b32_e32 v18, 16, v65
	v_and_b32_e32 v19, s99, v65
	v_lshlrev_b32_e32 v20, 16, v66
	v_and_b32_e32 v21, s99, v66
	v_lshlrev_b32_e32 v22, 16, v67
	v_and_b32_e32 v23, s99, v67
	v_lshlrev_b32_e32 v24, 16, v68
	v_and_b32_e32 v25, s99, v68
	v_lshlrev_b32_e32 v26, 16, v69
	v_and_b32_e32 v27, s99, v69
	v_lshlrev_b32_e32 v28, 16, v70
	v_and_b32_e32 v29, s99, v70
	v_lshlrev_b32_e32 v30, 16, v71
	v_and_b32_e32 v31, s99, v71
	v_add_u32_e32 v11, 109312, v5
	global_load_dwordx4 v[64:67], v11, s[2:3] offset:-2816 nt
	global_load_dwordx4 v[68:71], v11, s[2:3] offset:2816 nt
	s_waitcnt vmcnt(24)
	v_lshlrev_b32_e32 v32, 16, v72
	v_and_b32_e32 v33, s99, v72
	v_lshlrev_b32_e32 v34, 16, v73
	v_and_b32_e32 v35, s99, v73
	v_lshlrev_b32_e32 v36, 16, v74
	v_and_b32_e32 v37, s99, v74
	v_lshlrev_b32_e32 v38, 16, v75
	v_and_b32_e32 v39, s99, v75
	v_lshlrev_b32_e32 v40, 16, v76
	v_and_b32_e32 v41, s99, v76
	v_lshlrev_b32_e32 v42, 16, v77
	v_and_b32_e32 v43, s99, v77
	v_lshlrev_b32_e32 v44, 16, v78
	v_and_b32_e32 v45, s99, v78
	v_lshlrev_b32_e32 v46, 16, v79
	v_and_b32_e32 v47, s99, v79
	v_add_u32_e32 v10, 120576, v5
	global_load_dwordx4 v[72:75], v10, s[2:3] offset:-2816 nt
	global_load_dwordx4 v[76:79], v10, s[2:3] offset:2816 nt
	s_waitcnt vmcnt(23)
; __device__ __forceinline__ unsigned cvt_pk_bf16(float lo, float hi) { unsigned r; asm volatile("v_cvt_pk_bf16_f32 %0, %1, %2" : "=v"(r) : "v"(lo), "v"(hi)); return r; }
; __device__ __forceinline__ float silu_f(float x) { return x * __builtin_amdgcn_rcpf(1.0f + __builtin_amdgcn_exp2f(-LOG2E * x)); }
; __device__ __forceinline__ float bflo(unsigned w) { return __uint_as_float(w << 16); }
; __device__ __forceinline__ float bfhi(unsigned w) { return __uint_as_float(w & 0xffff0000u); }
; __device__ __forceinline__ void conv_phase(const bf16_t* Z, bf16_t* UA, const float* cw, const float* cb, int nrows, int rowoff) {
;     ...
;         for (int rr = 0; rr < 16; ++rr) {
;             u32x4 na = zero, ng = zero; if (rr < 15 || has_right) { na = *(const u32x4*)(zp + (size_t)(rr + 1) * FFN2); ng = *(const u32x4*)(zp + (size_t)(rr + 1) * FFN2 + FFN); }
;             u32x4 o;
; #pragma unroll
;             for (int e2 = 0; e2 < 4; ++e2) {
;                 const float a0 = bflo(pa[e2]) * wa[0][2 * e2] + bflo(ca[e2]) * wa[1][2 * e2] + bflo(na[e2]) * wa[2][2 * e2] + ba[2 * e2];
;                 const float a1 = bfhi(pa[e2]) * wa[0][2 * e2 + 1] + bfhi(ca[e2]) * wa[1][2 * e2 + 1] + bfhi(na[e2]) * wa[2][2 * e2 + 1] + ba[2 * e2 + 1];
;                 const float g0 = bflo(pg[e2]) * wg[0][2 * e2] + bflo(cgv[e2]) * wg[1][2 * e2] + bflo(ng[e2]) * wg[2][2 * e2] + bg[2 * e2];
;                 const float g1 = bfhi(pg[e2]) * wg[0][2 * e2 + 1] + bfhi(cgv[e2]) * wg[1][2 * e2 + 1] + bfhi(ng[e2]) * wg[2][2 * e2 + 1] + bg[2 * e2 + 1];
;                 o[e2] = cvt_pk_bf16(silu_f(a0) * g0, silu_f(a1) * g1); }
;             *(u32x4*)(UA + (size_t)(r0 + rr) * FFN + c0) = o;
;             pa = ca; pg = cgv; ca = na; cgv = ng;
	v_lshlrev_b32_e32 v48, 16, v80
	v_and_b32_e32 v49, s99, v80
	v_lshlrev_b32_e32 v50, 16, v81
	v_and_b32_e32 v51, s99, v81
	v_lshlrev_b32_e32 v52, 16, v82
	v_and_b32_e32 v53, s99, v82
	v_lshlrev_b32_e32 v54, 16, v83
	v_and_b32_e32 v55, s99, v83
	v_lshlrev_b32_e32 v56, 16, v84
	v_and_b32_e32 v57, s99, v84
	v_lshlrev_b32_e32 v58, 16, v85
	v_and_b32_e32 v59, s99, v85
	v_lshlrev_b32_e32 v60, 16, v86
	v_and_b32_e32 v61, s99, v86
	v_lshlrev_b32_e32 v62, 16, v87
	v_and_b32_e32 v63, s99, v87
	v_add_u32_e32 v11, 131840, v5
	global_load_dwordx4 v[80:83], v11, s[2:3] offset:-2816 nt
	global_load_dwordx4 v[84:87], v11, s[2:3] offset:2816 nt
	v_pk_fma_f32 v[136:137], v[16:17], v[152:153], v[236:237]
	v_pk_fma_f32 v[196:197], v[24:25], v[212:213], v[244:245]
	v_pk_fma_f32 v[138:139], v[18:19], v[154:155], v[238:239]
	v_pk_fma_f32 v[198:199], v[26:27], v[214:215], v[246:247]
	v_pk_fma_f32 v[140:141], v[20:21], v[156:157], v[240:241]
	v_pk_fma_f32 v[200:201], v[28:29], v[216:217], v[248:249]
	v_pk_fma_f32 v[142:143], v[22:23], v[158:159], v[242:243]
	v_pk_fma_f32 v[202:203], v[30:31], v[218:219], v[250:251]
	v_pk_fma_f32 v[136:137], v[32:33], v[160:161], v[136:137]
	v_pk_fma_f32 v[196:197], v[40:41], v[220:221], v[196:197]
	v_pk_fma_f32 v[138:139], v[34:35], v[162:163], v[138:139]
	v_pk_fma_f32 v[198:199], v[42:43], v[222:223], v[198:199]
	v_pk_fma_f32 v[140:141], v[36:37], v[164:165], v[140:141]
	v_pk_fma_f32 v[200:201], v[44:45], v[224:225], v[200:201]
	v_pk_fma_f32 v[142:143], v[38:39], v[166:167], v[142:143]
	v_pk_fma_f32 v[202:203], v[46:47], v[226:227], v[202:203]
	v_pk_fma_f32 v[136:137], v[48:49], v[168:169], v[136:137]
	v_pk_fma_f32 v[196:197], v[56:57], v[228:229], v[196:197]
	v_pk_fma_f32 v[138:139], v[50:51], v[170:171], v[138:139]
	v_pk_fma_f32 v[198:199], v[58:59], v[230:231], v[198:199]
	v_pk_fma_f32 v[140:141], v[52:53], v[172:173], v[140:141]
	v_pk_fma_f32 v[200:201], v[60:61], v[232:233], v[200:201]
	v_pk_fma_f32 v[142:143], v[54:55], v[174:175], v[142:143]
	v_pk_fma_f32 v[202:203], v[62:63], v[234:235], v[202:203]
	v_pk_mul_f32 v[184:185], v[136:137], v[180:181]
	v_pk_mul_f32 v[186:187], v[138:139], v[180:181]
	v_pk_mul_f32 v[188:189], v[140:141], v[180:181]
	v_pk_mul_f32 v[190:191], v[142:143], v[180:181]
	v_exp_f32_e32 v184, v184
	v_exp_f32_e32 v185, v185
	v_exp_f32_e32 v186, v186
	v_exp_f32_e32 v187, v187
	v_exp_f32_e32 v188, v188
	v_exp_f32_e32 v189, v189
	v_exp_f32_e32 v190, v190
	v_exp_f32_e32 v191, v191
	s_nop 0
	v_pk_add_f32 v[184:185], v[184:185], v[144:145]
	v_pk_add_f32 v[186:187], v[186:187], v[144:145]
	v_pk_add_f32 v[188:189], v[188:189], v[144:145]
	v_pk_add_f32 v[190:191], v[190:191], v[144:145]
	v_rcp_f32_e32 v184, v184
	v_rcp_f32_e32 v185, v185
	v_rcp_f32_e32 v186, v186
	v_rcp_f32_e32 v187, v187
	v_rcp_f32_e32 v188, v188
	v_rcp_f32_e32 v189, v189
	v_rcp_f32_e32 v190, v190
	v_rcp_f32_e32 v191, v191
	s_nop 0
	v_pk_mul_f32 v[136:137], v[136:137], v[184:185]
	v_pk_mul_f32 v[138:139], v[138:139], v[186:187]
	v_pk_mul_f32 v[140:141], v[140:141], v[188:189]
	v_pk_mul_f32 v[142:143], v[142:143], v[190:191]
	v_pk_mul_f32 v[136:137], v[136:137], v[196:197]
	v_pk_mul_f32 v[138:139], v[138:139], v[198:199]
	v_pk_mul_f32 v[140:141], v[140:141], v[200:201]
	v_pk_mul_f32 v[142:143], v[142:143], v[202:203]
	v_cvt_pk_bf16_f32 v12, v136, v137
	v_cvt_pk_bf16_f32 v13, v138, v139
	v_cvt_pk_bf16_f32 v14, v140, v141
	v_cvt_pk_bf16_f32 v15, v142, v143
	global_store_dwordx4 v6, v[12:15], s[30:31]
	v_add_u32_e32 v6, 5632, v6
	s_waitcnt vmcnt(23)
	v_lshlrev_b32_e32 v16, 16, v88
	v_and_b32_e32 v17, s99, v88
	v_lshlrev_b32_e32 v18, 16, v89
	v_and_b32_e32 v19, s99, v89
	v_lshlrev_b32_e32 v20, 16, v90
	v_and_b32_e32 v21, s99, v90
	v_lshlrev_b32_e32 v22, 16, v91
	v_and_b32_e32 v23, s99, v91
	v_lshlrev_b32_e32 v24, 16, v92
	v_and_b32_e32 v25, s99, v92
	v_lshlrev_b32_e32 v26, 16, v93
	v_and_b32_e32 v27, s99, v93
	v_lshlrev_b32_e32 v28, 16, v94
	v_and_b32_e32 v29, s99, v94
	v_lshlrev_b32_e32 v30, 16, v95
	v_and_b32_e32 v31, s99, v95
	v_add_u32_e32 v10, 143104, v5
	global_load_dwordx4 v[88:91], v10, s[2:3] offset:-2816 nt
	global_load_dwordx4 v[92:95], v10, s[2:3] offset:2816 nt
	v_pk_fma_f32 v[136:137], v[32:33], v[152:153], v[236:237]
	v_pk_fma_f32 v[196:197], v[40:41], v[212:213], v[244:245]
	v_pk_fma_f32 v[138:139], v[34:35], v[154:155], v[238:239]
	v_pk_fma_f32 v[198:199], v[42:43], v[214:215], v[246:247]
	v_pk_fma_f32 v[140:141], v[36:37], v[156:157], v[240:241]
	v_pk_fma_f32 v[200:201], v[44:45], v[216:217], v[248:249]
	v_pk_fma_f32 v[142:143], v[38:39], v[158:159], v[242:243]
	v_pk_fma_f32 v[202:203], v[46:47], v[218:219], v[250:251]
	v_pk_fma_f32 v[136:137], v[48:49], v[160:161], v[136:137]
	v_pk_fma_f32 v[196:197], v[56:57], v[220:221], v[196:197]
	v_pk_fma_f32 v[138:139], v[50:51], v[162:163], v[138:139]
	v_pk_fma_f32 v[198:199], v[58:59], v[222:223], v[198:199]
	v_pk_fma_f32 v[140:141], v[52:53], v[164:165], v[140:141]
	v_pk_fma_f32 v[200:201], v[60:61], v[224:225], v[200:201]
	v_pk_fma_f32 v[142:143], v[54:55], v[166:167], v[142:143]
	v_pk_fma_f32 v[202:203], v[62:63], v[226:227], v[202:203]
	v_pk_fma_f32 v[136:137], v[16:17], v[168:169], v[136:137]
	v_pk_fma_f32 v[196:197], v[24:25], v[228:229], v[196:197]
	v_pk_fma_f32 v[138:139], v[18:19], v[170:171], v[138:139]
	v_pk_fma_f32 v[198:199], v[26:27], v[230:231], v[198:199]
	v_pk_fma_f32 v[140:141], v[20:21], v[172:173], v[140:141]
	v_pk_fma_f32 v[200:201], v[28:29], v[232:233], v[200:201]
	v_pk_fma_f32 v[142:143], v[22:23], v[174:175], v[142:143]
	v_pk_fma_f32 v[202:203], v[30:31], v[234:235], v[202:203]
	v_pk_mul_f32 v[184:185], v[136:137], v[180:181]
	v_pk_mul_f32 v[186:187], v[138:139], v[180:181]
	v_pk_mul_f32 v[188:189], v[140:141], v[180:181]
	v_pk_mul_f32 v[190:191], v[142:143], v[180:181]
	v_exp_f32_e32 v184, v184
	v_exp_f32_e32 v185, v185
	v_exp_f32_e32 v186, v186
	v_exp_f32_e32 v187, v187
	v_exp_f32_e32 v188, v188
	v_exp_f32_e32 v189, v189
	v_exp_f32_e32 v190, v190
	v_exp_f32_e32 v191, v191
	s_nop 0
	v_pk_add_f32 v[184:185], v[184:185], v[144:145]
	v_pk_add_f32 v[186:187], v[186:187], v[144:145]
	v_pk_add_f32 v[188:189], v[188:189], v[144:145]
	v_pk_add_f32 v[190:191], v[190:191], v[144:145]
	v_rcp_f32_e32 v184, v184
	v_rcp_f32_e32 v185, v185
	v_rcp_f32_e32 v186, v186
	v_rcp_f32_e32 v187, v187
	v_rcp_f32_e32 v188, v188
	v_rcp_f32_e32 v189, v189
	v_rcp_f32_e32 v190, v190
	v_rcp_f32_e32 v191, v191
	s_nop 0
	v_pk_mul_f32 v[136:137], v[136:137], v[184:185]
	v_pk_mul_f32 v[138:139], v[138:139], v[186:187]
	v_pk_mul_f32 v[140:141], v[140:141], v[188:189]
	v_pk_mul_f32 v[142:143], v[142:143], v[190:191]
	v_pk_mul_f32 v[136:137], v[136:137], v[196:197]
	v_pk_mul_f32 v[138:139], v[138:139], v[198:199]
	v_pk_mul_f32 v[140:141], v[140:141], v[200:201]
	v_pk_mul_f32 v[142:143], v[142:143], v[202:203]
	v_cvt_pk_bf16_f32 v12, v136, v137
	v_cvt_pk_bf16_f32 v13, v138, v139
	v_cvt_pk_bf16_f32 v14, v140, v141
	v_cvt_pk_bf16_f32 v15, v142, v143
	global_store_dwordx4 v6, v[12:15], s[30:31]
	v_add_u32_e32 v6, 5632, v6
	s_waitcnt vmcnt(23)
; __device__ __forceinline__ unsigned cvt_pk_bf16(float lo, float hi) { unsigned r; asm volatile("v_cvt_pk_bf16_f32 %0, %1, %2" : "=v"(r) : "v"(lo), "v"(hi)); return r; }
; __device__ __forceinline__ float silu_f(float x) { return x * __builtin_amdgcn_rcpf(1.0f + __builtin_amdgcn_exp2f(-LOG2E * x)); }
; __device__ __forceinline__ float bflo(unsigned w) { return __uint_as_float(w << 16); }
; __device__ __forceinline__ float bfhi(unsigned w) { return __uint_as_float(w & 0xffff0000u); }
; __device__ __forceinline__ void conv_phase(const bf16_t* Z, bf16_t* UA, const float* cw, const float* cb, int nrows, int rowoff) {
;     ...
;         for (int rr = 0; rr < 16; ++rr) {
;             u32x4 na = zero, ng = zero; if (rr < 15 || has_right) { na = *(const u32x4*)(zp + (size_t)(rr + 1) * FFN2); ng = *(const u32x4*)(zp + (size_t)(rr + 1) * FFN2 + FFN); }
;             u32x4 o;
; #pragma unroll
;             for (int e2 = 0; e2 < 4; ++e2) {
;                 const float a0 = bflo(pa[e2]) * wa[0][2 * e2] + bflo(ca[e2]) * wa[1][2 * e2] + bflo(na[e2]) * wa[2][2 * e2] + ba[2 * e2];
;                 const float a1 = bfhi(pa[e2]) * wa[0][2 * e2 + 1] + bfhi(ca[e2]) * wa[1][2 * e2 + 1] + bfhi(na[e2]) * wa[2][2 * e2 + 1] + ba[2 * e2 + 1];
;                 const float g0 = bflo(pg[e2]) * wg[0][2 * e2] + bflo(cgv[e2]) * wg[1][2 * e2] + bflo(ng[e2]) * wg[2][2 * e2] + bg[2 * e2];
;                 const float g1 = bfhi(pg[e2]) * wg[0][2 * e2 + 1] + bfhi(cgv[e2]) * wg[1][2 * e2 + 1] + bfhi(ng[e2]) * wg[2][2 * e2 + 1] + bg[2 * e2 + 1];
;                 o[e2] = cvt_pk_bf16(silu_f(a0) * g0, silu_f(a1) * g1); }
;             *(u32x4*)(UA + (size_t)(r0 + rr) * FFN + c0) = o;
;             pa = ca; pg = cgv; ca = na; cgv = ng;
	v_lshlrev_b32_e32 v32, 16, v96
	v_and_b32_e32 v33, s99, v96
	v_lshlrev_b32_e32 v34, 16, v97
	v_and_b32_e32 v35, s99, v97
	v_lshlrev_b32_e32 v36, 16, v98
	v_and_b32_e32 v37, s99, v98
	v_lshlrev_b32_e32 v38, 16, v99
	v_and_b32_e32 v39, s99, v99
	v_lshlrev_b32_e32 v40, 16, v100
	v_and_b32_e32 v41, s99, v100
	v_lshlrev_b32_e32 v42, 16, v101
	v_and_b32_e32 v43, s99, v101
	v_lshlrev_b32_e32 v44, 16, v102
	v_and_b32_e32 v45, s99, v102
	v_lshlrev_b32_e32 v46, 16, v103
	v_and_b32_e32 v47, s99, v103
	v_add_u32_e32 v11, 154368, v5
	global_load_dwordx4 v[96:99], v11, s[2:3] offset:-2816 nt
	global_load_dwordx4 v[100:103], v11, s[2:3] offset:2816 nt
	v_pk_fma_f32 v[136:137], v[48:49], v[152:153], v[236:237]
	v_pk_fma_f32 v[196:197], v[56:57], v[212:213], v[244:245]
	v_pk_fma_f32 v[138:139], v[50:51], v[154:155], v[238:239]
	v_pk_fma_f32 v[198:199], v[58:59], v[214:215], v[246:247]
	v_pk_fma_f32 v[140:141], v[52:53], v[156:157], v[240:241]
	v_pk_fma_f32 v[200:201], v[60:61], v[216:217], v[248:249]
	v_pk_fma_f32 v[142:143], v[54:55], v[158:159], v[242:243]
	v_pk_fma_f32 v[202:203], v[62:63], v[218:219], v[250:251]
	v_pk_fma_f32 v[136:137], v[16:17], v[160:161], v[136:137]
	v_pk_fma_f32 v[196:197], v[24:25], v[220:221], v[196:197]
	v_pk_fma_f32 v[138:139], v[18:19], v[162:163], v[138:139]
	v_pk_fma_f32 v[198:199], v[26:27], v[222:223], v[198:199]
	v_pk_fma_f32 v[140:141], v[20:21], v[164:165], v[140:141]
	v_pk_fma_f32 v[200:201], v[28:29], v[224:225], v[200:201]
	v_pk_fma_f32 v[142:143], v[22:23], v[166:167], v[142:143]
	v_pk_fma_f32 v[202:203], v[30:31], v[226:227], v[202:203]
	v_pk_fma_f32 v[136:137], v[32:33], v[168:169], v[136:137]
	v_pk_fma_f32 v[196:197], v[40:41], v[228:229], v[196:197]
	v_pk_fma_f32 v[138:139], v[34:35], v[170:171], v[138:139]
	v_pk_fma_f32 v[198:199], v[42:43], v[230:231], v[198:199]
	v_pk_fma_f32 v[140:141], v[36:37], v[172:173], v[140:141]
	v_pk_fma_f32 v[200:201], v[44:45], v[232:233], v[200:201]
	v_pk_fma_f32 v[142:143], v[38:39], v[174:175], v[142:143]
	v_pk_fma_f32 v[202:203], v[46:47], v[234:235], v[202:203]
	v_pk_mul_f32 v[184:185], v[136:137], v[180:181]
	v_pk_mul_f32 v[186:187], v[138:139], v[180:181]
	v_pk_mul_f32 v[188:189], v[140:141], v[180:181]
	v_pk_mul_f32 v[190:191], v[142:143], v[180:181]
	v_exp_f32_e32 v184, v184
	v_exp_f32_e32 v185, v185
	v_exp_f32_e32 v186, v186
	v_exp_f32_e32 v187, v187
	v_exp_f32_e32 v188, v188
	v_exp_f32_e32 v189, v189
	v_exp_f32_e32 v190, v190
	v_exp_f32_e32 v191, v191
	s_nop 0
	v_pk_add_f32 v[184:185], v[184:185], v[144:145]
	v_pk_add_f32 v[186:187], v[186:187], v[144:145]
	v_pk_add_f32 v[188:189], v[188:189], v[144:145]
	v_pk_add_f32 v[190:191], v[190:191], v[144:145]
	v_rcp_f32_e32 v184, v184
	v_rcp_f32_e32 v185, v185
	v_rcp_f32_e32 v186, v186
	v_rcp_f32_e32 v187, v187
	v_rcp_f32_e32 v188, v188
	v_rcp_f32_e32 v189, v189
	v_rcp_f32_e32 v190, v190
	v_rcp_f32_e32 v191, v191
	s_nop 0
	v_pk_mul_f32 v[136:137], v[136:137], v[184:185]
	v_pk_mul_f32 v[138:139], v[138:139], v[186:187]
	v_pk_mul_f32 v[140:141], v[140:141], v[188:189]
	v_pk_mul_f32 v[142:143], v[142:143], v[190:191]
	v_pk_mul_f32 v[136:137], v[136:137], v[196:197]
	v_pk_mul_f32 v[138:139], v[138:139], v[198:199]
	v_pk_mul_f32 v[140:141], v[140:141], v[200:201]
	v_pk_mul_f32 v[142:143], v[142:143], v[202:203]
	v_cvt_pk_bf16_f32 v12, v136, v137
	v_cvt_pk_bf16_f32 v13, v138, v139
	v_cvt_pk_bf16_f32 v14, v140, v141
	v_cvt_pk_bf16_f32 v15, v142, v143
	global_store_dwordx4 v6, v[12:15], s[30:31]
	v_add_u32_e32 v6, 5632, v6
	s_waitcnt vmcnt(23)
	v_lshlrev_b32_e32 v48, 16, v104
	v_and_b32_e32 v49, s99, v104
	v_lshlrev_b32_e32 v50, 16, v105
	v_and_b32_e32 v51, s99, v105
	v_lshlrev_b32_e32 v52, 16, v106
	v_and_b32_e32 v53, s99, v106
	v_lshlrev_b32_e32 v54, 16, v107
	v_and_b32_e32 v55, s99, v107
	v_lshlrev_b32_e32 v56, 16, v108
	v_and_b32_e32 v57, s99, v108
	v_lshlrev_b32_e32 v58, 16, v109
	v_and_b32_e32 v59, s99, v109
	v_lshlrev_b32_e32 v60, 16, v110
	v_and_b32_e32 v61, s99, v110
	v_lshlrev_b32_e32 v62, 16, v111
	v_and_b32_e32 v63, s99, v111
	v_add_u32_e32 v10, 165632, v5
	global_load_dwordx4 v[104:107], v10, s[2:3] offset:-2816 nt
	global_load_dwordx4 v[108:111], v10, s[2:3] offset:2816 nt
	v_pk_fma_f32 v[136:137], v[16:17], v[152:153], v[236:237]
	v_pk_fma_f32 v[196:197], v[24:25], v[212:213], v[244:245]
	v_pk_fma_f32 v[138:139], v[18:19], v[154:155], v[238:239]
	v_pk_fma_f32 v[198:199], v[26:27], v[214:215], v[246:247]
	v_pk_fma_f32 v[140:141], v[20:21], v[156:157], v[240:241]
	v_pk_fma_f32 v[200:201], v[28:29], v[216:217], v[248:249]
	v_pk_fma_f32 v[142:143], v[22:23], v[158:159], v[242:243]
	v_pk_fma_f32 v[202:203], v[30:31], v[218:219], v[250:251]
	v_pk_fma_f32 v[136:137], v[32:33], v[160:161], v[136:137]
	v_pk_fma_f32 v[196:197], v[40:41], v[220:221], v[196:197]
	v_pk_fma_f32 v[138:139], v[34:35], v[162:163], v[138:139]
	v_pk_fma_f32 v[198:199], v[42:43], v[222:223], v[198:199]
	v_pk_fma_f32 v[140:141], v[36:37], v[164:165], v[140:141]
	v_pk_fma_f32 v[200:201], v[44:45], v[224:225], v[200:201]
	v_pk_fma_f32 v[142:143], v[38:39], v[166:167], v[142:143]
	v_pk_fma_f32 v[202:203], v[46:47], v[226:227], v[202:203]
	v_pk_fma_f32 v[136:137], v[48:49], v[168:169], v[136:137]
	v_pk_fma_f32 v[196:197], v[56:57], v[228:229], v[196:197]
	v_pk_fma_f32 v[138:139], v[50:51], v[170:171], v[138:139]
	v_pk_fma_f32 v[198:199], v[58:59], v[230:231], v[198:199]
	v_pk_fma_f32 v[140:141], v[52:53], v[172:173], v[140:141]
	v_pk_fma_f32 v[200:201], v[60:61], v[232:233], v[200:201]
	v_pk_fma_f32 v[142:143], v[54:55], v[174:175], v[142:143]
	v_pk_fma_f32 v[202:203], v[62:63], v[234:235], v[202:203]
	v_pk_mul_f32 v[184:185], v[136:137], v[180:181]
	v_pk_mul_f32 v[186:187], v[138:139], v[180:181]
	v_pk_mul_f32 v[188:189], v[140:141], v[180:181]
	v_pk_mul_f32 v[190:191], v[142:143], v[180:181]
	v_exp_f32_e32 v184, v184
	v_exp_f32_e32 v185, v185
	v_exp_f32_e32 v186, v186
	v_exp_f32_e32 v187, v187
	v_exp_f32_e32 v188, v188
	v_exp_f32_e32 v189, v189
	v_exp_f32_e32 v190, v190
	v_exp_f32_e32 v191, v191
	s_nop 0
	v_pk_add_f32 v[184:185], v[184:185], v[144:145]
	v_pk_add_f32 v[186:187], v[186:187], v[144:145]
	v_pk_add_f32 v[188:189], v[188:189], v[144:145]
	v_pk_add_f32 v[190:191], v[190:191], v[144:145]
	v_rcp_f32_e32 v184, v184
	v_rcp_f32_e32 v185, v185
	v_rcp_f32_e32 v186, v186
	v_rcp_f32_e32 v187, v187
	v_rcp_f32_e32 v188, v188
	v_rcp_f32_e32 v189, v189
	v_rcp_f32_e32 v190, v190
	v_rcp_f32_e32 v191, v191
	s_nop 0
	v_pk_mul_f32 v[136:137], v[136:137], v[184:185]
	v_pk_mul_f32 v[138:139], v[138:139], v[186:187]
	v_pk_mul_f32 v[140:141], v[140:141], v[188:189]
	v_pk_mul_f32 v[142:143], v[142:143], v[190:191]
	v_pk_mul_f32 v[136:137], v[136:137], v[196:197]
	v_pk_mul_f32 v[138:139], v[138:139], v[198:199]
	v_pk_mul_f32 v[140:141], v[140:141], v[200:201]
	v_pk_mul_f32 v[142:143], v[142:143], v[202:203]
	v_cvt_pk_bf16_f32 v12, v136, v137
	v_cvt_pk_bf16_f32 v13, v138, v139
	v_cvt_pk_bf16_f32 v14, v140, v141
	v_cvt_pk_bf16_f32 v15, v142, v143
	global_store_dwordx4 v6, v[12:15], s[30:31]
	v_add_u32_e32 v6, 5632, v6
	s_waitcnt vmcnt(23)
; __device__ __forceinline__ unsigned cvt_pk_bf16(float lo, float hi) { unsigned r; asm volatile("v_cvt_pk_bf16_f32 %0, %1, %2" : "=v"(r) : "v"(lo), "v"(hi)); return r; }
; __device__ __forceinline__ float silu_f(float x) { return x * __builtin_amdgcn_rcpf(1.0f + __builtin_amdgcn_exp2f(-LOG2E * x)); }
; __device__ __forceinline__ float bflo(unsigned w) { return __uint_as_float(w << 16); }
; __device__ __forceinline__ float bfhi(unsigned w) { return __uint_as_float(w & 0xffff0000u); }
; __device__ __forceinline__ void conv_phase(const bf16_t* Z, bf16_t* UA, const float* cw, const float* cb, int nrows, int rowoff) {
;     ...
;         for (int rr = 0; rr < 16; ++rr) {
;             u32x4 na = zero, ng = zero; if (rr < 15 || has_right) { na = *(const u32x4*)(zp + (size_t)(rr + 1) * FFN2); ng = *(const u32x4*)(zp + (size_t)(rr + 1) * FFN2 + FFN); }
;             u32x4 o;
; #pragma unroll
;             for (int e2 = 0; e2 < 4; ++e2) {
;                 const float a0 = bflo(pa[e2]) * wa[0][2 * e2] + bflo(ca[e2]) * wa[1][2 * e2] + bflo(na[e2]) * wa[2][2 * e2] + ba[2 * e2];
;                 const float a1 = bfhi(pa[e2]) * wa[0][2 * e2 + 1] + bfhi(ca[e2]) * wa[1][2 * e2 + 1] + bfhi(na[e2]) * wa[2][2 * e2 + 1] + ba[2 * e2 + 1];
;                 const float g0 = bflo(pg[e2]) * wg[0][2 * e2] + bflo(cgv[e2]) * wg[1][2 * e2] + bflo(ng[e2]) * wg[2][2 * e2] + bg[2 * e2];
;                 const float g1 = bfhi(pg[e2]) * wg[0][2 * e2 + 1] + bfhi(cgv[e2]) * wg[1][2 * e2 + 1] + bfhi(ng[e2]) * wg[2][2 * e2 + 1] + bg[2 * e2 + 1];
;                 o[e2] = cvt_pk_bf16(silu_f(a0) * g0, silu_f(a1) * g1); }
;             *(u32x4*)(UA + (size_t)(r0 + rr) * FFN + c0) = o;
;             pa = ca; pg = cgv; ca = na; cgv = ng;
	v_lshlrev_b32_e32 v16, 16, v112
	v_and_b32_e32 v17, s99, v112
	v_lshlrev_b32_e32 v18, 16, v113
	v_and_b32_e32 v19, s99, v113
	v_lshlrev_b32_e32 v20, 16, v114
	v_and_b32_e32 v21, s99, v114
	v_lshlrev_b32_e32 v22, 16, v115
	v_and_b32_e32 v23, s99, v115
	v_lshlrev_b32_e32 v24, 16, v116
	v_and_b32_e32 v25, s99, v116
	v_lshlrev_b32_e32 v26, 16, v117
	v_and_b32_e32 v27, s99, v117
	v_lshlrev_b32_e32 v28, 16, v118
	v_and_b32_e32 v29, s99, v118
	v_lshlrev_b32_e32 v30, 16, v119
	v_and_b32_e32 v31, s99, v119
	v_add_u32_e32 v11, 176896, v5
	global_load_dwordx4 v[112:115], v11, s[2:3] offset:-2816 nt
	global_load_dwordx4 v[116:119], v11, s[2:3] offset:2816 nt
	v_pk_fma_f32 v[136:137], v[32:33], v[152:153], v[236:237]
	v_pk_fma_f32 v[196:197], v[40:41], v[212:213], v[244:245]
	v_pk_fma_f32 v[138:139], v[34:35], v[154:155], v[238:239]
	v_pk_fma_f32 v[198:199], v[42:43], v[214:215], v[246:247]
	v_pk_fma_f32 v[140:141], v[36:37], v[156:157], v[240:241]
	v_pk_fma_f32 v[200:201], v[44:45], v[216:217], v[248:249]
	v_pk_fma_f32 v[142:143], v[38:39], v[158:159], v[242:243]
	v_pk_fma_f32 v[202:203], v[46:47], v[218:219], v[250:251]
	v_pk_fma_f32 v[136:137], v[48:49], v[160:161], v[136:137]
	v_pk_fma_f32 v[196:197], v[56:57], v[220:221], v[196:197]
	v_pk_fma_f32 v[138:139], v[50:51], v[162:163], v[138:139]
	v_pk_fma_f32 v[198:199], v[58:59], v[222:223], v[198:199]
	v_pk_fma_f32 v[140:141], v[52:53], v[164:165], v[140:141]
	v_pk_fma_f32 v[200:201], v[60:61], v[224:225], v[200:201]
	v_pk_fma_f32 v[142:143], v[54:55], v[166:167], v[142:143]
	v_pk_fma_f32 v[202:203], v[62:63], v[226:227], v[202:203]
	v_pk_fma_f32 v[136:137], v[16:17], v[168:169], v[136:137]
	v_pk_fma_f32 v[196:197], v[24:25], v[228:229], v[196:197]
	v_pk_fma_f32 v[138:139], v[18:19], v[170:171], v[138:139]
	v_pk_fma_f32 v[198:199], v[26:27], v[230:231], v[198:199]
	v_pk_fma_f32 v[140:141], v[20:21], v[172:173], v[140:141]
	v_pk_fma_f32 v[200:201], v[28:29], v[232:233], v[200:201]
	v_pk_fma_f32 v[142:143], v[22:23], v[174:175], v[142:143]
	v_pk_fma_f32 v[202:203], v[30:31], v[234:235], v[202:203]
	v_pk_mul_f32 v[184:185], v[136:137], v[180:181]
	v_pk_mul_f32 v[186:187], v[138:139], v[180:181]
	v_pk_mul_f32 v[188:189], v[140:141], v[180:181]
	v_pk_mul_f32 v[190:191], v[142:143], v[180:181]
	v_exp_f32_e32 v184, v184
	v_exp_f32_e32 v185, v185
	v_exp_f32_e32 v186, v186
	v_exp_f32_e32 v187, v187
	v_exp_f32_e32 v188, v188
	v_exp_f32_e32 v189, v189
	v_exp_f32_e32 v190, v190
	v_exp_f32_e32 v191, v191
	s_nop 0
	v_pk_add_f32 v[184:185], v[184:185], v[144:145]
	v_pk_add_f32 v[186:187], v[186:187], v[144:145]
	v_pk_add_f32 v[188:189], v[188:189], v[144:145]
	v_pk_add_f32 v[190:191], v[190:191], v[144:145]
	v_rcp_f32_e32 v184, v184
	v_rcp_f32_e32 v185, v185
	v_rcp_f32_e32 v186, v186
	v_rcp_f32_e32 v187, v187
	v_rcp_f32_e32 v188, v188
	v_rcp_f32_e32 v189, v189
	v_rcp_f32_e32 v190, v190
	v_rcp_f32_e32 v191, v191
	s_nop 0
	v_pk_mul_f32 v[136:137], v[136:137], v[184:185]
	v_pk_mul_f32 v[138:139], v[138:139], v[186:187]
	v_pk_mul_f32 v[140:141], v[140:141], v[188:189]
	v_pk_mul_f32 v[142:143], v[142:143], v[190:191]
	v_pk_mul_f32 v[136:137], v[136:137], v[196:197]
	v_pk_mul_f32 v[138:139], v[138:139], v[198:199]
	v_pk_mul_f32 v[140:141], v[140:141], v[200:201]
	v_pk_mul_f32 v[142:143], v[142:143], v[202:203]
	v_cvt_pk_bf16_f32 v12, v136, v137
	v_cvt_pk_bf16_f32 v13, v138, v139
	v_cvt_pk_bf16_f32 v14, v140, v141
	v_cvt_pk_bf16_f32 v15, v142, v143
	global_store_dwordx4 v6, v[12:15], s[30:31]
	v_add_u32_e32 v6, 5632, v6
	s_waitcnt vmcnt(23)
	v_lshlrev_b32_e32 v32, 16, v120
	v_and_b32_e32 v33, s99, v120
	v_lshlrev_b32_e32 v34, 16, v121
	v_and_b32_e32 v35, s99, v121
	v_lshlrev_b32_e32 v36, 16, v122
	v_and_b32_e32 v37, s99, v122
	v_lshlrev_b32_e32 v38, 16, v123
	v_and_b32_e32 v39, s99, v123
	v_lshlrev_b32_e32 v40, 16, v124
	v_and_b32_e32 v41, s99, v124
	v_lshlrev_b32_e32 v42, 16, v125
	v_and_b32_e32 v43, s99, v125
	v_lshlrev_b32_e32 v44, 16, v126
	v_and_b32_e32 v45, s99, v126
	v_lshlrev_b32_e32 v46, 16, v127
	v_and_b32_e32 v47, s99, v127
	v_add_u32_e32 v10, 188160, v5
	global_load_dwordx4 v[120:123], v10, s[2:3] offset:-2816 nt
	global_load_dwordx4 v[124:127], v10, s[2:3] offset:2816 nt
	v_pk_fma_f32 v[136:137], v[48:49], v[152:153], v[236:237]
	v_pk_fma_f32 v[196:197], v[56:57], v[212:213], v[244:245]
	v_pk_fma_f32 v[138:139], v[50:51], v[154:155], v[238:239]
	v_pk_fma_f32 v[198:199], v[58:59], v[214:215], v[246:247]
	v_pk_fma_f32 v[140:141], v[52:53], v[156:157], v[240:241]
	v_pk_fma_f32 v[200:201], v[60:61], v[216:217], v[248:249]
	v_pk_fma_f32 v[142:143], v[54:55], v[158:159], v[242:243]
	v_pk_fma_f32 v[202:203], v[62:63], v[218:219], v[250:251]
	v_pk_fma_f32 v[136:137], v[16:17], v[160:161], v[136:137]
	v_pk_fma_f32 v[196:197], v[24:25], v[220:221], v[196:197]
	v_pk_fma_f32 v[138:139], v[18:19], v[162:163], v[138:139]
	v_pk_fma_f32 v[198:199], v[26:27], v[222:223], v[198:199]
	v_pk_fma_f32 v[140:141], v[20:21], v[164:165], v[140:141]
	v_pk_fma_f32 v[200:201], v[28:29], v[224:225], v[200:201]
	v_pk_fma_f32 v[142:143], v[22:23], v[166:167], v[142:143]
	v_pk_fma_f32 v[202:203], v[30:31], v[226:227], v[202:203]
	v_pk_fma_f32 v[136:137], v[32:33], v[168:169], v[136:137]
	v_pk_fma_f32 v[196:197], v[40:41], v[228:229], v[196:197]
	v_pk_fma_f32 v[138:139], v[34:35], v[170:171], v[138:139]
	v_pk_fma_f32 v[198:199], v[42:43], v[230:231], v[198:199]
	v_pk_fma_f32 v[140:141], v[36:37], v[172:173], v[140:141]
	v_pk_fma_f32 v[200:201], v[44:45], v[232:233], v[200:201]
	v_pk_fma_f32 v[142:143], v[38:39], v[174:175], v[142:143]
	v_pk_fma_f32 v[202:203], v[46:47], v[234:235], v[202:203]
	v_pk_mul_f32 v[184:185], v[136:137], v[180:181]
	v_pk_mul_f32 v[186:187], v[138:139], v[180:181]
	v_pk_mul_f32 v[188:189], v[140:141], v[180:181]
	v_pk_mul_f32 v[190:191], v[142:143], v[180:181]
	v_exp_f32_e32 v184, v184
	v_exp_f32_e32 v185, v185
	v_exp_f32_e32 v186, v186
	v_exp_f32_e32 v187, v187
	v_exp_f32_e32 v188, v188
	v_exp_f32_e32 v189, v189
	v_exp_f32_e32 v190, v190
	v_exp_f32_e32 v191, v191
	s_nop 0
	v_pk_add_f32 v[184:185], v[184:185], v[144:145]
	v_pk_add_f32 v[186:187], v[186:187], v[144:145]
	v_pk_add_f32 v[188:189], v[188:189], v[144:145]
	v_pk_add_f32 v[190:191], v[190:191], v[144:145]
	v_rcp_f32_e32 v184, v184
	v_rcp_f32_e32 v185, v185
	v_rcp_f32_e32 v186, v186
	v_rcp_f32_e32 v187, v187
	v_rcp_f32_e32 v188, v188
	v_rcp_f32_e32 v189, v189
	v_rcp_f32_e32 v190, v190
	v_rcp_f32_e32 v191, v191
	s_nop 0
	v_pk_mul_f32 v[136:137], v[136:137], v[184:185]
	v_pk_mul_f32 v[138:139], v[138:139], v[186:187]
	v_pk_mul_f32 v[140:141], v[140:141], v[188:189]
	v_pk_mul_f32 v[142:143], v[142:143], v[190:191]
	v_pk_mul_f32 v[136:137], v[136:137], v[196:197]
	v_pk_mul_f32 v[138:139], v[138:139], v[198:199]
	v_pk_mul_f32 v[140:141], v[140:141], v[200:201]
	v_pk_mul_f32 v[142:143], v[142:143], v[202:203]
	v_cvt_pk_bf16_f32 v12, v136, v137
	v_cvt_pk_bf16_f32 v13, v138, v139
	v_cvt_pk_bf16_f32 v14, v140, v141
	v_cvt_pk_bf16_f32 v15, v142, v143
	global_store_dwordx4 v6, v[12:15], s[30:31]
	v_add_u32_e32 v6, 5632, v6
	s_waitcnt vmcnt(23)
; __device__ __forceinline__ unsigned cvt_pk_bf16(float lo, float hi) { unsigned r; asm volatile("v_cvt_pk_bf16_f32 %0, %1, %2" : "=v"(r) : "v"(lo), "v"(hi)); return r; }
; __device__ __forceinline__ float silu_f(float x) { return x * __builtin_amdgcn_rcpf(1.0f + __builtin_amdgcn_exp2f(-LOG2E * x)); }
; __device__ __forceinline__ float bflo(unsigned w) { return __uint_as_float(w << 16); }
; __device__ __forceinline__ float bfhi(unsigned w) { return __uint_as_float(w & 0xffff0000u); }
; __device__ __forceinline__ void conv_phase(const bf16_t* Z, bf16_t* UA, const float* cw, const float* cb, int nrows, int rowoff) {
;     ...
;         for (int rr = 0; rr < 16; ++rr) {
;             u32x4 na = zero, ng = zero; if (rr < 15 || has_right) { na = *(const u32x4*)(zp + (size_t)(rr + 1) * FFN2); ng = *(const u32x4*)(zp + (size_t)(rr + 1) * FFN2 + FFN); }
;             u32x4 o;
; #pragma unroll
;             for (int e2 = 0; e2 < 4; ++e2) {
;                 const float a0 = bflo(pa[e2]) * wa[0][2 * e2] + bflo(ca[e2]) * wa[1][2 * e2] + bflo(na[e2]) * wa[2][2 * e2] + ba[2 * e2];
;                 const float a1 = bfhi(pa[e2]) * wa[0][2 * e2 + 1] + bfhi(ca[e2]) * wa[1][2 * e2 + 1] + bfhi(na[e2]) * wa[2][2 * e2 + 1] + ba[2 * e2 + 1];
;                 const float g0 = bflo(pg[e2]) * wg[0][2 * e2] + bflo(cgv[e2]) * wg[1][2 * e2] + bflo(ng[e2]) * wg[2][2 * e2] + bg[2 * e2];
;                 const float g1 = bfhi(pg[e2]) * wg[0][2 * e2 + 1] + bfhi(cgv[e2]) * wg[1][2 * e2 + 1] + bfhi(ng[e2]) * wg[2][2 * e2 + 1] + bg[2 * e2 + 1];
;                 o[e2] = cvt_pk_bf16(silu_f(a0) * g0, silu_f(a1) * g1); }
;             *(u32x4*)(UA + (size_t)(r0 + rr) * FFN + c0) = o;
;             pa = ca; pg = cgv; ca = na; cgv = ng;
;         }
	v_lshlrev_b32_e32 v48, 16, v128
	v_and_b32_e32 v49, s99, v128
	v_lshlrev_b32_e32 v50, 16, v129
	v_and_b32_e32 v51, s99, v129
	v_lshlrev_b32_e32 v52, 16, v130
	v_and_b32_e32 v53, s99, v130
	v_lshlrev_b32_e32 v54, 16, v131
	v_and_b32_e32 v55, s99, v131
	v_lshlrev_b32_e32 v56, 16, v132
	v_and_b32_e32 v57, s99, v132
	v_lshlrev_b32_e32 v58, 16, v133
	v_and_b32_e32 v59, s99, v133
	v_lshlrev_b32_e32 v60, 16, v134
	v_and_b32_e32 v61, s99, v134
	v_lshlrev_b32_e32 v62, 16, v135
	v_and_b32_e32 v63, s99, v135
	v_add_u32_e32 v11, 199424, v5
	global_load_dwordx4 v[128:131], v11, s[2:3] offset:-2816 nt
	global_load_dwordx4 v[132:135], v11, s[2:3] offset:2816 nt
	v_pk_fma_f32 v[136:137], v[16:17], v[152:153], v[236:237]
	v_pk_fma_f32 v[196:197], v[24:25], v[212:213], v[244:245]
	v_pk_fma_f32 v[138:139], v[18:19], v[154:155], v[238:239]
	v_pk_fma_f32 v[198:199], v[26:27], v[214:215], v[246:247]
	v_pk_fma_f32 v[140:141], v[20:21], v[156:157], v[240:241]
	v_pk_fma_f32 v[200:201], v[28:29], v[216:217], v[248:249]
	v_pk_fma_f32 v[142:143], v[22:23], v[158:159], v[242:243]
	v_pk_fma_f32 v[202:203], v[30:31], v[218:219], v[250:251]
	v_pk_fma_f32 v[136:137], v[32:33], v[160:161], v[136:137]
	v_pk_fma_f32 v[196:197], v[40:41], v[220:221], v[196:197]
	v_pk_fma_f32 v[138:139], v[34:35], v[162:163], v[138:139]
	v_pk_fma_f32 v[198:199], v[42:43], v[222:223], v[198:199]
	v_pk_fma_f32 v[140:141], v[36:37], v[164:165], v[140:141]
	v_pk_fma_f32 v[200:201], v[44:45], v[224:225], v[200:201]
	v_pk_fma_f32 v[142:143], v[38:39], v[166:167], v[142:143]
	v_pk_fma_f32 v[202:203], v[46:47], v[226:227], v[202:203]
	v_pk_fma_f32 v[136:137], v[48:49], v[168:169], v[136:137]
	v_pk_fma_f32 v[196:197], v[56:57], v[228:229], v[196:197]
	v_pk_fma_f32 v[138:139], v[50:51], v[170:171], v[138:139]
	v_pk_fma_f32 v[198:199], v[58:59], v[230:231], v[198:199]
	v_pk_fma_f32 v[140:141], v[52:53], v[172:173], v[140:141]
	v_pk_fma_f32 v[200:201], v[60:61], v[232:233], v[200:201]
	v_pk_fma_f32 v[142:143], v[54:55], v[174:175], v[142:143]
	v_pk_fma_f32 v[202:203], v[62:63], v[234:235], v[202:203]
	v_pk_mul_f32 v[184:185], v[136:137], v[180:181]
	v_pk_mul_f32 v[186:187], v[138:139], v[180:181]
	v_pk_mul_f32 v[188:189], v[140:141], v[180:181]
	v_pk_mul_f32 v[190:191], v[142:143], v[180:181]
	v_exp_f32_e32 v184, v184
	v_exp_f32_e32 v185, v185
	v_exp_f32_e32 v186, v186
	v_exp_f32_e32 v187, v187
	v_exp_f32_e32 v188, v188
	v_exp_f32_e32 v189, v189
	v_exp_f32_e32 v190, v190
	v_exp_f32_e32 v191, v191
	s_nop 0
	v_pk_add_f32 v[184:185], v[184:185], v[144:145]
	v_pk_add_f32 v[186:187], v[186:187], v[144:145]
	v_pk_add_f32 v[188:189], v[188:189], v[144:145]
	v_pk_add_f32 v[190:191], v[190:191], v[144:145]
	v_rcp_f32_e32 v184, v184
	v_rcp_f32_e32 v185, v185
	v_rcp_f32_e32 v186, v186
	v_rcp_f32_e32 v187, v187
	v_rcp_f32_e32 v188, v188
	v_rcp_f32_e32 v189, v189
	v_rcp_f32_e32 v190, v190
	v_rcp_f32_e32 v191, v191
	s_nop 0
	v_pk_mul_f32 v[136:137], v[136:137], v[184:185]
	v_pk_mul_f32 v[138:139], v[138:139], v[186:187]
	v_pk_mul_f32 v[140:141], v[140:141], v[188:189]
	v_pk_mul_f32 v[142:143], v[142:143], v[190:191]
	v_pk_mul_f32 v[136:137], v[136:137], v[196:197]
	v_pk_mul_f32 v[138:139], v[138:139], v[198:199]
	v_pk_mul_f32 v[140:141], v[140:141], v[200:201]
	v_pk_mul_f32 v[142:143], v[142:143], v[202:203]
	v_cvt_pk_bf16_f32 v12, v136, v137
	v_cvt_pk_bf16_f32 v13, v138, v139
	v_cvt_pk_bf16_f32 v14, v140, v141
	v_cvt_pk_bf16_f32 v15, v142, v143
	global_store_dwordx4 v6, v[12:15], s[30:31]
	v_add_u32_e32 v6, 5632, v6
	s_waitcnt vmcnt(23)
	v_lshlrev_b32_e32 v16, 16, v64
	v_and_b32_e32 v17, s99, v64
	v_lshlrev_b32_e32 v18, 16, v65
	v_and_b32_e32 v19, s99, v65
	v_lshlrev_b32_e32 v20, 16, v66
	v_and_b32_e32 v21, s99, v66
	v_lshlrev_b32_e32 v22, 16, v67
	v_and_b32_e32 v23, s99, v67
	v_lshlrev_b32_e32 v24, 16, v68
	v_and_b32_e32 v25, s99, v68
	v_lshlrev_b32_e32 v26, 16, v69
	v_and_b32_e32 v27, s99, v69
	v_lshlrev_b32_e32 v28, 16, v70
	v_and_b32_e32 v29, s99, v70
	v_lshlrev_b32_e32 v30, 16, v71
	v_and_b32_e32 v31, s99, v71
	v_add_u32_e32 v10, 67051264, v5
	global_load_dwordx4 v[64:67], v10, s[2:3] offset:-2816 nt
	global_load_dwordx4 v[68:71], v10, s[2:3] offset:2816 nt
	v_pk_fma_f32 v[136:137], v[32:33], v[152:153], v[236:237]
	v_pk_fma_f32 v[196:197], v[40:41], v[212:213], v[244:245]
	v_pk_fma_f32 v[138:139], v[34:35], v[154:155], v[238:239]
	v_pk_fma_f32 v[198:199], v[42:43], v[214:215], v[246:247]
	v_pk_fma_f32 v[140:141], v[36:37], v[156:157], v[240:241]
	v_pk_fma_f32 v[200:201], v[44:45], v[216:217], v[248:249]
	v_pk_fma_f32 v[142:143], v[38:39], v[158:159], v[242:243]
	v_pk_fma_f32 v[202:203], v[46:47], v[218:219], v[250:251]
	v_pk_fma_f32 v[136:137], v[48:49], v[160:161], v[136:137]
	v_pk_fma_f32 v[196:197], v[56:57], v[220:221], v[196:197]
	v_pk_fma_f32 v[138:139], v[50:51], v[162:163], v[138:139]
	v_pk_fma_f32 v[198:199], v[58:59], v[222:223], v[198:199]
	v_pk_fma_f32 v[140:141], v[52:53], v[164:165], v[140:141]
	v_pk_fma_f32 v[200:201], v[60:61], v[224:225], v[200:201]
	v_pk_fma_f32 v[142:143], v[54:55], v[166:167], v[142:143]
	v_pk_fma_f32 v[202:203], v[62:63], v[226:227], v[202:203]
	v_pk_fma_f32 v[136:137], v[16:17], v[168:169], v[136:137]
	v_pk_fma_f32 v[196:197], v[24:25], v[228:229], v[196:197]
	v_pk_fma_f32 v[138:139], v[18:19], v[170:171], v[138:139]
	v_pk_fma_f32 v[198:199], v[26:27], v[230:231], v[198:199]
	v_pk_fma_f32 v[140:141], v[20:21], v[172:173], v[140:141]
	v_pk_fma_f32 v[200:201], v[28:29], v[232:233], v[200:201]
	v_pk_fma_f32 v[142:143], v[22:23], v[174:175], v[142:143]
	v_pk_fma_f32 v[202:203], v[30:31], v[234:235], v[202:203]
	v_pk_mul_f32 v[184:185], v[136:137], v[180:181]
	v_pk_mul_f32 v[186:187], v[138:139], v[180:181]
	v_pk_mul_f32 v[188:189], v[140:141], v[180:181]
	v_pk_mul_f32 v[190:191], v[142:143], v[180:181]
	v_exp_f32_e32 v184, v184
	v_exp_f32_e32 v185, v185
	v_exp_f32_e32 v186, v186
	v_exp_f32_e32 v187, v187
	v_exp_f32_e32 v188, v188
	v_exp_f32_e32 v189, v189
	v_exp_f32_e32 v190, v190
	v_exp_f32_e32 v191, v191
	s_nop 0
	v_pk_add_f32 v[184:185], v[184:185], v[144:145]
	v_pk_add_f32 v[186:187], v[186:187], v[144:145]
	v_pk_add_f32 v[188:189], v[188:189], v[144:145]
	v_pk_add_f32 v[190:191], v[190:191], v[144:145]
	v_rcp_f32_e32 v184, v184
	v_rcp_f32_e32 v185, v185
	v_rcp_f32_e32 v186, v186
	v_rcp_f32_e32 v187, v187
	v_rcp_f32_e32 v188, v188
	v_rcp_f32_e32 v189, v189
	v_rcp_f32_e32 v190, v190
	v_rcp_f32_e32 v191, v191
	s_nop 0
	v_pk_mul_f32 v[136:137], v[136:137], v[184:185]
	v_pk_mul_f32 v[138:139], v[138:139], v[186:187]
	v_pk_mul_f32 v[140:141], v[140:141], v[188:189]
	v_pk_mul_f32 v[142:143], v[142:143], v[190:191]
	v_pk_mul_f32 v[136:137], v[136:137], v[196:197]
	v_pk_mul_f32 v[138:139], v[138:139], v[198:199]
	v_pk_mul_f32 v[140:141], v[140:141], v[200:201]
	v_pk_mul_f32 v[142:143], v[142:143], v[202:203]
	v_cvt_pk_bf16_f32 v12, v136, v137
	v_cvt_pk_bf16_f32 v13, v138, v139
	v_cvt_pk_bf16_f32 v14, v140, v141
	v_cvt_pk_bf16_f32 v15, v142, v143
	global_store_dwordx4 v6, v[12:15], s[30:31]
	v_add_u32_e32 v6, 5632, v6
	s_waitcnt vmcnt(24)
; __device__ __forceinline__ unsigned cvt_pk_bf16(float lo, float hi) { unsigned r; asm volatile("v_cvt_pk_bf16_f32 %0, %1, %2" : "=v"(r) : "v"(lo), "v"(hi)); return r; }
; __device__ __forceinline__ float silu_f(float x) { return x * __builtin_amdgcn_rcpf(1.0f + __builtin_amdgcn_exp2f(-LOG2E * x)); }
; __device__ __forceinline__ float bflo(unsigned w) { return __uint_as_float(w << 16); }
; __device__ __forceinline__ float bfhi(unsigned w) { return __uint_as_float(w & 0xffff0000u); }
; __device__ __forceinline__ void conv_phase(const bf16_t* Z, bf16_t* UA, const float* cw, const float* cb, int nrows, int rowoff) {
;     ...
;         for (int rr = 0; rr < 16; ++rr) {
;             u32x4 na = zero, ng = zero; if (rr < 15 || has_right) { na = *(const u32x4*)(zp + (size_t)(rr + 1) * FFN2); ng = *(const u32x4*)(zp + (size_t)(rr + 1) * FFN2 + FFN); }
;             u32x4 o;
; #pragma unroll
;             for (int e2 = 0; e2 < 4; ++e2) {
;                 const float a0 = bflo(pa[e2]) * wa[0][2 * e2] + bflo(ca[e2]) * wa[1][2 * e2] + bflo(na[e2]) * wa[2][2 * e2] + ba[2 * e2];
;                 const float a1 = bfhi(pa[e2]) * wa[0][2 * e2 + 1] + bfhi(ca[e2]) * wa[1][2 * e2 + 1] + bfhi(na[e2]) * wa[2][2 * e2 + 1] + ba[2 * e2 + 1];
;                 const float g0 = bflo(pg[e2]) * wg[0][2 * e2] + bflo(cgv[e2]) * wg[1][2 * e2] + bflo(ng[e2]) * wg[2][2 * e2] + bg[2 * e2];
;                 const float g1 = bfhi(pg[e2]) * wg[0][2 * e2 + 1] + bfhi(cgv[e2]) * wg[1][2 * e2 + 1] + bfhi(ng[e2]) * wg[2][2 * e2 + 1] + bg[2 * e2 + 1];
;                 o[e2] = cvt_pk_bf16(silu_f(a0) * g0, silu_f(a1) * g1); }
;             *(u32x4*)(UA + (size_t)(r0 + rr) * FFN + c0) = o;
;             pa = ca; pg = cgv; ca = na; cgv = ng;
;         }
	v_lshlrev_b32_e32 v32, 16, v72
	v_and_b32_e32 v33, s99, v72
	v_lshlrev_b32_e32 v34, 16, v73
	v_and_b32_e32 v35, s99, v73
	v_lshlrev_b32_e32 v36, 16, v74
	v_and_b32_e32 v37, s99, v74
	v_lshlrev_b32_e32 v38, 16, v75
	v_and_b32_e32 v39, s99, v75
	v_lshlrev_b32_e32 v40, 16, v76
	v_and_b32_e32 v41, s99, v76
	v_lshlrev_b32_e32 v42, 16, v77
	v_and_b32_e32 v43, s99, v77
	v_lshlrev_b32_e32 v44, 16, v78
	v_and_b32_e32 v45, s99, v78
	v_lshlrev_b32_e32 v46, 16, v79
	v_and_b32_e32 v47, s99, v79
	v_add_u32_e32 v11, 67062528, v5
	global_load_dwordx4 v[72:75], v11, s[2:3] offset:-2816 nt
	global_load_dwordx4 v[76:79], v11, s[2:3] offset:2816 nt
	v_pk_fma_f32 v[136:137], v[48:49], v[152:153], v[236:237]
	v_pk_fma_f32 v[196:197], v[56:57], v[212:213], v[244:245]
	v_pk_fma_f32 v[138:139], v[50:51], v[154:155], v[238:239]
	v_pk_fma_f32 v[198:199], v[58:59], v[214:215], v[246:247]
	v_pk_fma_f32 v[140:141], v[52:53], v[156:157], v[240:241]
	v_pk_fma_f32 v[200:201], v[60:61], v[216:217], v[248:249]
	v_pk_fma_f32 v[142:143], v[54:55], v[158:159], v[242:243]
	v_pk_fma_f32 v[202:203], v[62:63], v[218:219], v[250:251]
	v_pk_fma_f32 v[136:137], v[16:17], v[160:161], v[136:137]
	v_pk_fma_f32 v[196:197], v[24:25], v[220:221], v[196:197]
	v_pk_fma_f32 v[138:139], v[18:19], v[162:163], v[138:139]
	v_pk_fma_f32 v[198:199], v[26:27], v[222:223], v[198:199]
	v_pk_fma_f32 v[140:141], v[20:21], v[164:165], v[140:141]
	v_pk_fma_f32 v[200:201], v[28:29], v[224:225], v[200:201]
	v_pk_fma_f32 v[142:143], v[22:23], v[166:167], v[142:143]
	v_pk_fma_f32 v[202:203], v[30:31], v[226:227], v[202:203]
	v_pk_fma_f32 v[136:137], v[32:33], v[168:169], v[136:137]
	v_pk_fma_f32 v[196:197], v[40:41], v[228:229], v[196:197]
	v_pk_fma_f32 v[138:139], v[34:35], v[170:171], v[138:139]
	v_pk_fma_f32 v[198:199], v[42:43], v[230:231], v[198:199]
	v_pk_fma_f32 v[140:141], v[36:37], v[172:173], v[140:141]
	v_pk_fma_f32 v[200:201], v[44:45], v[232:233], v[200:201]
	v_pk_fma_f32 v[142:143], v[38:39], v[174:175], v[142:143]
	v_pk_fma_f32 v[202:203], v[46:47], v[234:235], v[202:203]
	v_pk_mul_f32 v[184:185], v[136:137], v[180:181]
	v_pk_mul_f32 v[186:187], v[138:139], v[180:181]
	v_pk_mul_f32 v[188:189], v[140:141], v[180:181]
	v_pk_mul_f32 v[190:191], v[142:143], v[180:181]
	v_exp_f32_e32 v184, v184
	v_exp_f32_e32 v185, v185
	v_exp_f32_e32 v186, v186
	v_exp_f32_e32 v187, v187
	v_exp_f32_e32 v188, v188
	v_exp_f32_e32 v189, v189
	v_exp_f32_e32 v190, v190
	v_exp_f32_e32 v191, v191
	s_nop 0
	v_pk_add_f32 v[184:185], v[184:185], v[144:145]
	v_pk_add_f32 v[186:187], v[186:187], v[144:145]
	v_pk_add_f32 v[188:189], v[188:189], v[144:145]
	v_pk_add_f32 v[190:191], v[190:191], v[144:145]
	v_rcp_f32_e32 v184, v184
	v_rcp_f32_e32 v185, v185
	v_rcp_f32_e32 v186, v186
	v_rcp_f32_e32 v187, v187
	v_rcp_f32_e32 v188, v188
	v_rcp_f32_e32 v189, v189
	v_rcp_f32_e32 v190, v190
	v_rcp_f32_e32 v191, v191
	s_nop 0
	v_pk_mul_f32 v[136:137], v[136:137], v[184:185]
	v_pk_mul_f32 v[138:139], v[138:139], v[186:187]
	v_pk_mul_f32 v[140:141], v[140:141], v[188:189]
	v_pk_mul_f32 v[142:143], v[142:143], v[190:191]
	v_pk_mul_f32 v[136:137], v[136:137], v[196:197]
	v_pk_mul_f32 v[138:139], v[138:139], v[198:199]
	v_pk_mul_f32 v[140:141], v[140:141], v[200:201]
	v_pk_mul_f32 v[142:143], v[142:143], v[202:203]
	v_cvt_pk_bf16_f32 v12, v136, v137
	v_cvt_pk_bf16_f32 v13, v138, v139
	v_cvt_pk_bf16_f32 v14, v140, v141
	v_cvt_pk_bf16_f32 v15, v142, v143
	global_store_dwordx4 v6, v[12:15], s[30:31]
	v_add_u32_e32 v6, 5632, v6
	s_waitcnt vmcnt(25)
	v_lshlrev_b32_e32 v48, 16, v80
	v_and_b32_e32 v49, s99, v80
	v_lshlrev_b32_e32 v50, 16, v81
	v_and_b32_e32 v51, s99, v81
	v_lshlrev_b32_e32 v52, 16, v82
	v_and_b32_e32 v53, s99, v82
	v_lshlrev_b32_e32 v54, 16, v83
	v_and_b32_e32 v55, s99, v83
	v_lshlrev_b32_e32 v56, 16, v84
	v_and_b32_e32 v57, s99, v84
	v_lshlrev_b32_e32 v58, 16, v85
	v_and_b32_e32 v59, s99, v85
	v_lshlrev_b32_e32 v60, 16, v86
	v_and_b32_e32 v61, s99, v86
	v_lshlrev_b32_e32 v62, 16, v87
	v_and_b32_e32 v63, s99, v87
	v_add_u32_e32 v10, 67073792, v5
	global_load_dwordx4 v[80:83], v10, s[2:3] offset:-2816 nt
	global_load_dwordx4 v[84:87], v10, s[2:3] offset:2816 nt
	v_pk_fma_f32 v[136:137], v[16:17], v[152:153], v[236:237]
	v_pk_fma_f32 v[196:197], v[24:25], v[212:213], v[244:245]
	v_pk_fma_f32 v[138:139], v[18:19], v[154:155], v[238:239]
	v_pk_fma_f32 v[198:199], v[26:27], v[214:215], v[246:247]
	v_pk_fma_f32 v[140:141], v[20:21], v[156:157], v[240:241]
	v_pk_fma_f32 v[200:201], v[28:29], v[216:217], v[248:249]
	v_pk_fma_f32 v[142:143], v[22:23], v[158:159], v[242:243]
	v_pk_fma_f32 v[202:203], v[30:31], v[218:219], v[250:251]
	v_pk_fma_f32 v[136:137], v[32:33], v[160:161], v[136:137]
	v_pk_fma_f32 v[196:197], v[40:41], v[220:221], v[196:197]
	v_pk_fma_f32 v[138:139], v[34:35], v[162:163], v[138:139]
	v_pk_fma_f32 v[198:199], v[42:43], v[222:223], v[198:199]
	v_pk_fma_f32 v[140:141], v[36:37], v[164:165], v[140:141]
	v_pk_fma_f32 v[200:201], v[44:45], v[224:225], v[200:201]
	v_pk_fma_f32 v[142:143], v[38:39], v[166:167], v[142:143]
	v_pk_fma_f32 v[202:203], v[46:47], v[226:227], v[202:203]
	v_pk_fma_f32 v[136:137], v[48:49], v[168:169], v[136:137]
	v_pk_fma_f32 v[196:197], v[56:57], v[228:229], v[196:197]
	v_pk_fma_f32 v[138:139], v[50:51], v[170:171], v[138:139]
	v_pk_fma_f32 v[198:199], v[58:59], v[230:231], v[198:199]
	v_pk_fma_f32 v[140:141], v[52:53], v[172:173], v[140:141]
	v_pk_fma_f32 v[200:201], v[60:61], v[232:233], v[200:201]
	v_pk_fma_f32 v[142:143], v[54:55], v[174:175], v[142:143]
	v_pk_fma_f32 v[202:203], v[62:63], v[234:235], v[202:203]
	v_pk_mul_f32 v[184:185], v[136:137], v[180:181]
	v_pk_mul_f32 v[186:187], v[138:139], v[180:181]
	v_pk_mul_f32 v[188:189], v[140:141], v[180:181]
	v_pk_mul_f32 v[190:191], v[142:143], v[180:181]
	v_exp_f32_e32 v184, v184
	v_exp_f32_e32 v185, v185
	v_exp_f32_e32 v186, v186
	v_exp_f32_e32 v187, v187
	v_exp_f32_e32 v188, v188
	v_exp_f32_e32 v189, v189
	v_exp_f32_e32 v190, v190
	v_exp_f32_e32 v191, v191
	s_nop 0
	v_pk_add_f32 v[184:185], v[184:185], v[144:145]
	v_pk_add_f32 v[186:187], v[186:187], v[144:145]
	v_pk_add_f32 v[188:189], v[188:189], v[144:145]
	v_pk_add_f32 v[190:191], v[190:191], v[144:145]
	v_rcp_f32_e32 v184, v184
	v_rcp_f32_e32 v185, v185
	v_rcp_f32_e32 v186, v186
	v_rcp_f32_e32 v187, v187
	v_rcp_f32_e32 v188, v188
	v_rcp_f32_e32 v189, v189
	v_rcp_f32_e32 v190, v190
	v_rcp_f32_e32 v191, v191
	s_nop 0
	v_pk_mul_f32 v[136:137], v[136:137], v[184:185]
	v_pk_mul_f32 v[138:139], v[138:139], v[186:187]
	v_pk_mul_f32 v[140:141], v[140:141], v[188:189]
	v_pk_mul_f32 v[142:143], v[142:143], v[190:191]
	v_pk_mul_f32 v[136:137], v[136:137], v[196:197]
	v_pk_mul_f32 v[138:139], v[138:139], v[198:199]
	v_pk_mul_f32 v[140:141], v[140:141], v[200:201]
	v_pk_mul_f32 v[142:143], v[142:143], v[202:203]
	v_cvt_pk_bf16_f32 v12, v136, v137
	v_cvt_pk_bf16_f32 v13, v138, v139
	v_cvt_pk_bf16_f32 v14, v140, v141
	v_cvt_pk_bf16_f32 v15, v142, v143
	global_store_dwordx4 v6, v[12:15], s[30:31]
	v_add_u32_e32 v6, 5632, v6
	s_waitcnt vmcnt(25)
; __device__ __forceinline__ unsigned cvt_pk_bf16(float lo, float hi) { unsigned r; asm volatile("v_cvt_pk_bf16_f32 %0, %1, %2" : "=v"(r) : "v"(lo), "v"(hi)); return r; }
; __device__ __forceinline__ float silu_f(float x) { return x * __builtin_amdgcn_rcpf(1.0f + __builtin_amdgcn_exp2f(-LOG2E * x)); }
; __device__ __forceinline__ float bflo(unsigned w) { return __uint_as_float(w << 16); }
; __device__ __forceinline__ float bfhi(unsigned w) { return __uint_as_float(w & 0xffff0000u); }
; __device__ __forceinline__ void conv_phase(const bf16_t* Z, bf16_t* UA, const float* cw, const float* cb, int nrows, int rowoff) {
;     ...
;         for (int rr = 0; rr < 16; ++rr) {
;             u32x4 na = zero, ng = zero; if (rr < 15 || has_right) { na = *(const u32x4*)(zp + (size_t)(rr + 1) * FFN2); ng = *(const u32x4*)(zp + (size_t)(rr + 1) * FFN2 + FFN); }
;             u32x4 o;
; #pragma unroll
;             for (int e2 = 0; e2 < 4; ++e2) {
;                 const float a0 = bflo(pa[e2]) * wa[0][2 * e2] + bflo(ca[e2]) * wa[1][2 * e2] + bflo(na[e2]) * wa[2][2 * e2] + ba[2 * e2];
;                 const float a1 = bfhi(pa[e2]) * wa[0][2 * e2 + 1] + bfhi(ca[e2]) * wa[1][2 * e2 + 1] + bfhi(na[e2]) * wa[2][2 * e2 + 1] + ba[2 * e2 + 1];
;                 const float g0 = bflo(pg[e2]) * wg[0][2 * e2] + bflo(cgv[e2]) * wg[1][2 * e2] + bflo(ng[e2]) * wg[2][2 * e2] + bg[2 * e2];
;                 const float g1 = bfhi(pg[e2]) * wg[0][2 * e2 + 1] + bfhi(cgv[e2]) * wg[1][2 * e2 + 1] + bfhi(ng[e2]) * wg[2][2 * e2 + 1] + bg[2 * e2 + 1];
;                 o[e2] = cvt_pk_bf16(silu_f(a0) * g0, silu_f(a1) * g1); }
;             *(u32x4*)(UA + (size_t)(r0 + rr) * FFN + c0) = o;
;             pa = ca; pg = cgv; ca = na; cgv = ng;
;         }
	v_lshlrev_b32_e32 v16, 16, v88
	v_and_b32_e32 v17, s99, v88
	v_lshlrev_b32_e32 v18, 16, v89
	v_and_b32_e32 v19, s99, v89
	v_lshlrev_b32_e32 v20, 16, v90
	v_and_b32_e32 v21, s99, v90
	v_lshlrev_b32_e32 v22, 16, v91
	v_and_b32_e32 v23, s99, v91
	v_lshlrev_b32_e32 v24, 16, v92
	v_and_b32_e32 v25, s99, v92
	v_lshlrev_b32_e32 v26, 16, v93
	v_and_b32_e32 v27, s99, v93
	v_lshlrev_b32_e32 v28, 16, v94
	v_and_b32_e32 v29, s99, v94
	v_lshlrev_b32_e32 v30, 16, v95
	v_and_b32_e32 v31, s99, v95
	v_add_u32_e32 v11, 67085056, v5
	global_load_dwordx4 v[88:91], v11, s[2:3] offset:-2816 nt
	global_load_dwordx4 v[92:95], v11, s[2:3] offset:2816 nt
	v_pk_fma_f32 v[136:137], v[32:33], v[152:153], v[236:237]
	v_pk_fma_f32 v[196:197], v[40:41], v[212:213], v[244:245]
	v_pk_fma_f32 v[138:139], v[34:35], v[154:155], v[238:239]
	v_pk_fma_f32 v[198:199], v[42:43], v[214:215], v[246:247]
	v_pk_fma_f32 v[140:141], v[36:37], v[156:157], v[240:241]
	v_pk_fma_f32 v[200:201], v[44:45], v[216:217], v[248:249]
	v_pk_fma_f32 v[142:143], v[38:39], v[158:159], v[242:243]
	v_pk_fma_f32 v[202:203], v[46:47], v[218:219], v[250:251]
	v_pk_fma_f32 v[136:137], v[48:49], v[160:161], v[136:137]
	v_pk_fma_f32 v[196:197], v[56:57], v[220:221], v[196:197]
	v_pk_fma_f32 v[138:139], v[50:51], v[162:163], v[138:139]
	v_pk_fma_f32 v[198:199], v[58:59], v[222:223], v[198:199]
	v_pk_fma_f32 v[140:141], v[52:53], v[164:165], v[140:141]
	v_pk_fma_f32 v[200:201], v[60:61], v[224:225], v[200:201]
	v_pk_fma_f32 v[142:143], v[54:55], v[166:167], v[142:143]
	v_pk_fma_f32 v[202:203], v[62:63], v[226:227], v[202:203]
	v_pk_fma_f32 v[136:137], v[16:17], v[168:169], v[136:137]
	v_pk_fma_f32 v[196:197], v[24:25], v[228:229], v[196:197]
	v_pk_fma_f32 v[138:139], v[18:19], v[170:171], v[138:139]
	v_pk_fma_f32 v[198:199], v[26:27], v[230:231], v[198:199]
	v_pk_fma_f32 v[140:141], v[20:21], v[172:173], v[140:141]
	v_pk_fma_f32 v[200:201], v[28:29], v[232:233], v[200:201]
	v_pk_fma_f32 v[142:143], v[22:23], v[174:175], v[142:143]
	v_pk_fma_f32 v[202:203], v[30:31], v[234:235], v[202:203]
	v_pk_mul_f32 v[184:185], v[136:137], v[180:181]
	v_pk_mul_f32 v[186:187], v[138:139], v[180:181]
	v_pk_mul_f32 v[188:189], v[140:141], v[180:181]
	v_pk_mul_f32 v[190:191], v[142:143], v[180:181]
	v_exp_f32_e32 v184, v184
	v_exp_f32_e32 v185, v185
	v_exp_f32_e32 v186, v186
	v_exp_f32_e32 v187, v187
	v_exp_f32_e32 v188, v188
	v_exp_f32_e32 v189, v189
	v_exp_f32_e32 v190, v190
	v_exp_f32_e32 v191, v191
	s_nop 0
	v_pk_add_f32 v[184:185], v[184:185], v[144:145]
	v_pk_add_f32 v[186:187], v[186:187], v[144:145]
	v_pk_add_f32 v[188:189], v[188:189], v[144:145]
	v_pk_add_f32 v[190:191], v[190:191], v[144:145]
	v_rcp_f32_e32 v184, v184
	v_rcp_f32_e32 v185, v185
	v_rcp_f32_e32 v186, v186
	v_rcp_f32_e32 v187, v187
	v_rcp_f32_e32 v188, v188
	v_rcp_f32_e32 v189, v189
	v_rcp_f32_e32 v190, v190
	v_rcp_f32_e32 v191, v191
	s_nop 0
	v_pk_mul_f32 v[136:137], v[136:137], v[184:185]
	v_pk_mul_f32 v[138:139], v[138:139], v[186:187]
	v_pk_mul_f32 v[140:141], v[140:141], v[188:189]
	v_pk_mul_f32 v[142:143], v[142:143], v[190:191]
	v_pk_mul_f32 v[136:137], v[136:137], v[196:197]
	v_pk_mul_f32 v[138:139], v[138:139], v[198:199]
	v_pk_mul_f32 v[140:141], v[140:141], v[200:201]
	v_pk_mul_f32 v[142:143], v[142:143], v[202:203]
	v_cvt_pk_bf16_f32 v12, v136, v137
	v_cvt_pk_bf16_f32 v13, v138, v139
	v_cvt_pk_bf16_f32 v14, v140, v141
	v_cvt_pk_bf16_f32 v15, v142, v143
	global_store_dwordx4 v6, v[12:15], s[30:31]
	v_add_u32_e32 v6, 5632, v6
	s_waitcnt vmcnt(25)
	v_lshlrev_b32_e32 v32, 16, v96
	v_and_b32_e32 v33, s99, v96
	v_lshlrev_b32_e32 v34, 16, v97
	v_and_b32_e32 v35, s99, v97
	v_lshlrev_b32_e32 v36, 16, v98
	v_and_b32_e32 v37, s99, v98
	v_lshlrev_b32_e32 v38, 16, v99
	v_and_b32_e32 v39, s99, v99
	v_lshlrev_b32_e32 v40, 16, v100
	v_and_b32_e32 v41, s99, v100
	v_lshlrev_b32_e32 v42, 16, v101
	v_and_b32_e32 v43, s99, v101
	v_lshlrev_b32_e32 v44, 16, v102
	v_and_b32_e32 v45, s99, v102
	v_lshlrev_b32_e32 v46, 16, v103
	v_and_b32_e32 v47, s99, v103
	v_add_u32_e32 v10, 67096320, v5
	global_load_dwordx4 v[96:99], v10, s[2:3] offset:-2816 nt
	global_load_dwordx4 v[100:103], v10, s[2:3] offset:2816 nt
	v_pk_fma_f32 v[136:137], v[48:49], v[152:153], v[236:237]
	v_pk_fma_f32 v[196:197], v[56:57], v[212:213], v[244:245]
	v_pk_fma_f32 v[138:139], v[50:51], v[154:155], v[238:239]
	v_pk_fma_f32 v[198:199], v[58:59], v[214:215], v[246:247]
	v_pk_fma_f32 v[140:141], v[52:53], v[156:157], v[240:241]
	v_pk_fma_f32 v[200:201], v[60:61], v[216:217], v[248:249]
	v_pk_fma_f32 v[142:143], v[54:55], v[158:159], v[242:243]
	v_pk_fma_f32 v[202:203], v[62:63], v[218:219], v[250:251]
	v_pk_fma_f32 v[136:137], v[16:17], v[160:161], v[136:137]
	v_pk_fma_f32 v[196:197], v[24:25], v[220:221], v[196:197]
	v_pk_fma_f32 v[138:139], v[18:19], v[162:163], v[138:139]
	v_pk_fma_f32 v[198:199], v[26:27], v[222:223], v[198:199]
	v_pk_fma_f32 v[140:141], v[20:21], v[164:165], v[140:141]
	v_pk_fma_f32 v[200:201], v[28:29], v[224:225], v[200:201]
	v_pk_fma_f32 v[142:143], v[22:23], v[166:167], v[142:143]
	v_pk_fma_f32 v[202:203], v[30:31], v[226:227], v[202:203]
	v_pk_fma_f32 v[136:137], v[32:33], v[168:169], v[136:137]
	v_pk_fma_f32 v[196:197], v[40:41], v[228:229], v[196:197]
	v_pk_fma_f32 v[138:139], v[34:35], v[170:171], v[138:139]
	v_pk_fma_f32 v[198:199], v[42:43], v[230:231], v[198:199]
	v_pk_fma_f32 v[140:141], v[36:37], v[172:173], v[140:141]
	v_pk_fma_f32 v[200:201], v[44:45], v[232:233], v[200:201]
	v_pk_fma_f32 v[142:143], v[38:39], v[174:175], v[142:143]
	v_pk_fma_f32 v[202:203], v[46:47], v[234:235], v[202:203]
	v_pk_mul_f32 v[184:185], v[136:137], v[180:181]
	v_pk_mul_f32 v[186:187], v[138:139], v[180:181]
	v_pk_mul_f32 v[188:189], v[140:141], v[180:181]
	v_pk_mul_f32 v[190:191], v[142:143], v[180:181]
	v_exp_f32_e32 v184, v184
	v_exp_f32_e32 v185, v185
	v_exp_f32_e32 v186, v186
	v_exp_f32_e32 v187, v187
	v_exp_f32_e32 v188, v188
	v_exp_f32_e32 v189, v189
	v_exp_f32_e32 v190, v190
	v_exp_f32_e32 v191, v191
	s_nop 0
	v_pk_add_f32 v[184:185], v[184:185], v[144:145]
	v_pk_add_f32 v[186:187], v[186:187], v[144:145]
	v_pk_add_f32 v[188:189], v[188:189], v[144:145]
	v_pk_add_f32 v[190:191], v[190:191], v[144:145]
	v_rcp_f32_e32 v184, v184
	v_rcp_f32_e32 v185, v185
	v_rcp_f32_e32 v186, v186
	v_rcp_f32_e32 v187, v187
	v_rcp_f32_e32 v188, v188
	v_rcp_f32_e32 v189, v189
	v_rcp_f32_e32 v190, v190
	v_rcp_f32_e32 v191, v191
	s_nop 0
	v_pk_mul_f32 v[136:137], v[136:137], v[184:185]
	v_pk_mul_f32 v[138:139], v[138:139], v[186:187]
	v_pk_mul_f32 v[140:141], v[140:141], v[188:189]
	v_pk_mul_f32 v[142:143], v[142:143], v[190:191]
	v_pk_mul_f32 v[136:137], v[136:137], v[196:197]
	v_pk_mul_f32 v[138:139], v[138:139], v[198:199]
	v_pk_mul_f32 v[140:141], v[140:141], v[200:201]
	v_pk_mul_f32 v[142:143], v[142:143], v[202:203]
	v_cvt_pk_bf16_f32 v12, v136, v137
	v_cvt_pk_bf16_f32 v13, v138, v139
	v_cvt_pk_bf16_f32 v14, v140, v141
	v_cvt_pk_bf16_f32 v15, v142, v143
	global_store_dwordx4 v6, v[12:15], s[30:31]
	v_add_u32_e32 v6, 5632, v6
	s_waitcnt vmcnt(25)
; __device__ __forceinline__ unsigned cvt_pk_bf16(float lo, float hi) { unsigned r; asm volatile("v_cvt_pk_bf16_f32 %0, %1, %2" : "=v"(r) : "v"(lo), "v"(hi)); return r; }
; __device__ __forceinline__ float silu_f(float x) { return x * __builtin_amdgcn_rcpf(1.0f + __builtin_amdgcn_exp2f(-LOG2E * x)); }
; __device__ __forceinline__ float bflo(unsigned w) { return __uint_as_float(w << 16); }
; __device__ __forceinline__ float bfhi(unsigned w) { return __uint_as_float(w & 0xffff0000u); }
; __device__ __forceinline__ void conv_phase(const bf16_t* Z, bf16_t* UA, const float* cw, const float* cb, int nrows, int rowoff) {
;     ...
;         for (int rr = 0; rr < 16; ++rr) {
;             u32x4 na = zero, ng = zero; if (rr < 15 || has_right) { na = *(const u32x4*)(zp + (size_t)(rr + 1) * FFN2); ng = *(const u32x4*)(zp + (size_t)(rr + 1) * FFN2 + FFN); }
;             u32x4 o;
; #pragma unroll
;             for (int e2 = 0; e2 < 4; ++e2) {
;                 const float a0 = bflo(pa[e2]) * wa[0][2 * e2] + bflo(ca[e2]) * wa[1][2 * e2] + bflo(na[e2]) * wa[2][2 * e2] + ba[2 * e2];
;                 const float a1 = bfhi(pa[e2]) * wa[0][2 * e2 + 1] + bfhi(ca[e2]) * wa[1][2 * e2 + 1] + bfhi(na[e2]) * wa[2][2 * e2 + 1] + ba[2 * e2 + 1];
;                 const float g0 = bflo(pg[e2]) * wg[0][2 * e2] + bflo(cgv[e2]) * wg[1][2 * e2] + bflo(ng[e2]) * wg[2][2 * e2] + bg[2 * e2];
;                 const float g1 = bfhi(pg[e2]) * wg[0][2 * e2 + 1] + bfhi(cgv[e2]) * wg[1][2 * e2 + 1] + bfhi(ng[e2]) * wg[2][2 * e2 + 1] + bg[2 * e2 + 1];
;                 o[e2] = cvt_pk_bf16(silu_f(a0) * g0, silu_f(a1) * g1); }
;             *(u32x4*)(UA + (size_t)(r0 + rr) * FFN + c0) = o;
;             pa = ca; pg = cgv; ca = na; cgv = ng;
;         }
	v_lshlrev_b32_e32 v48, 16, v104
	v_and_b32_e32 v49, s99, v104
	v_lshlrev_b32_e32 v50, 16, v105
	v_and_b32_e32 v51, s99, v105
	v_lshlrev_b32_e32 v52, 16, v106
	v_and_b32_e32 v53, s99, v106
	v_lshlrev_b32_e32 v54, 16, v107
	v_and_b32_e32 v55, s99, v107
	v_lshlrev_b32_e32 v56, 16, v108
	v_and_b32_e32 v57, s99, v108
	v_lshlrev_b32_e32 v58, 16, v109
	v_and_b32_e32 v59, s99, v109
	v_lshlrev_b32_e32 v60, 16, v110
	v_and_b32_e32 v61, s99, v110
	v_lshlrev_b32_e32 v62, 16, v111
	v_and_b32_e32 v63, s99, v111
	v_add_u32_e32 v11, 67107584, v5
	global_load_dwordx4 v[104:107], v11, s[2:3] offset:-2816 nt
	global_load_dwordx4 v[108:111], v11, s[2:3] offset:2816 nt
	v_pk_fma_f32 v[136:137], v[16:17], v[152:153], v[236:237]
	v_pk_fma_f32 v[196:197], v[24:25], v[212:213], v[244:245]
	v_pk_fma_f32 v[138:139], v[18:19], v[154:155], v[238:239]
	v_pk_fma_f32 v[198:199], v[26:27], v[214:215], v[246:247]
	v_pk_fma_f32 v[140:141], v[20:21], v[156:157], v[240:241]
	v_pk_fma_f32 v[200:201], v[28:29], v[216:217], v[248:249]
	v_pk_fma_f32 v[142:143], v[22:23], v[158:159], v[242:243]
	v_pk_fma_f32 v[202:203], v[30:31], v[218:219], v[250:251]
	v_pk_fma_f32 v[136:137], v[32:33], v[160:161], v[136:137]
	v_pk_fma_f32 v[196:197], v[40:41], v[220:221], v[196:197]
	v_pk_fma_f32 v[138:139], v[34:35], v[162:163], v[138:139]
	v_pk_fma_f32 v[198:199], v[42:43], v[222:223], v[198:199]
	v_pk_fma_f32 v[140:141], v[36:37], v[164:165], v[140:141]
	v_pk_fma_f32 v[200:201], v[44:45], v[224:225], v[200:201]
	v_pk_fma_f32 v[142:143], v[38:39], v[166:167], v[142:143]
	v_pk_fma_f32 v[202:203], v[46:47], v[226:227], v[202:203]
	v_pk_fma_f32 v[136:137], v[48:49], v[168:169], v[136:137]
	v_pk_fma_f32 v[196:197], v[56:57], v[228:229], v[196:197]
	v_pk_fma_f32 v[138:139], v[50:51], v[170:171], v[138:139]
	v_pk_fma_f32 v[198:199], v[58:59], v[230:231], v[198:199]
	v_pk_fma_f32 v[140:141], v[52:53], v[172:173], v[140:141]
	v_pk_fma_f32 v[200:201], v[60:61], v[232:233], v[200:201]
	v_pk_fma_f32 v[142:143], v[54:55], v[174:175], v[142:143]
	v_pk_fma_f32 v[202:203], v[62:63], v[234:235], v[202:203]
	v_pk_mul_f32 v[184:185], v[136:137], v[180:181]
	v_pk_mul_f32 v[186:187], v[138:139], v[180:181]
	v_pk_mul_f32 v[188:189], v[140:141], v[180:181]
	v_pk_mul_f32 v[190:191], v[142:143], v[180:181]
	v_exp_f32_e32 v184, v184
	v_exp_f32_e32 v185, v185
	v_exp_f32_e32 v186, v186
	v_exp_f32_e32 v187, v187
	v_exp_f32_e32 v188, v188
	v_exp_f32_e32 v189, v189
	v_exp_f32_e32 v190, v190
	v_exp_f32_e32 v191, v191
	s_nop 0
	v_pk_add_f32 v[184:185], v[184:185], v[144:145]
	v_pk_add_f32 v[186:187], v[186:187], v[144:145]
	v_pk_add_f32 v[188:189], v[188:189], v[144:145]
	v_pk_add_f32 v[190:191], v[190:191], v[144:145]
	v_rcp_f32_e32 v184, v184
	v_rcp_f32_e32 v185, v185
	v_rcp_f32_e32 v186, v186
	v_rcp_f32_e32 v187, v187
	v_rcp_f32_e32 v188, v188
	v_rcp_f32_e32 v189, v189
	v_rcp_f32_e32 v190, v190
	v_rcp_f32_e32 v191, v191
	s_nop 0
	v_pk_mul_f32 v[136:137], v[136:137], v[184:185]
	v_pk_mul_f32 v[138:139], v[138:139], v[186:187]
	v_pk_mul_f32 v[140:141], v[140:141], v[188:189]
	v_pk_mul_f32 v[142:143], v[142:143], v[190:191]
	v_pk_mul_f32 v[136:137], v[136:137], v[196:197]
	v_pk_mul_f32 v[138:139], v[138:139], v[198:199]
	v_pk_mul_f32 v[140:141], v[140:141], v[200:201]
	v_pk_mul_f32 v[142:143], v[142:143], v[202:203]
	v_cvt_pk_bf16_f32 v12, v136, v137
	v_cvt_pk_bf16_f32 v13, v138, v139
	v_cvt_pk_bf16_f32 v14, v140, v141
	v_cvt_pk_bf16_f32 v15, v142, v143
	global_store_dwordx4 v6, v[12:15], s[30:31]
	v_add_u32_e32 v6, 5632, v6
	s_waitcnt vmcnt(25)
	v_lshlrev_b32_e32 v16, 16, v112
	v_and_b32_e32 v17, s99, v112
	v_lshlrev_b32_e32 v18, 16, v113
	v_and_b32_e32 v19, s99, v113
	v_lshlrev_b32_e32 v20, 16, v114
	v_and_b32_e32 v21, s99, v114
	v_lshlrev_b32_e32 v22, 16, v115
	v_and_b32_e32 v23, s99, v115
	v_lshlrev_b32_e32 v24, 16, v116
	v_and_b32_e32 v25, s99, v116
	v_lshlrev_b32_e32 v26, 16, v117
	v_and_b32_e32 v27, s99, v117
	v_lshlrev_b32_e32 v28, 16, v118
	v_and_b32_e32 v29, s99, v118
	v_lshlrev_b32_e32 v30, 16, v119
	v_and_b32_e32 v31, s99, v119
	v_add_u32_e32 v10, 67118848, v5
	global_load_dwordx4 v[112:115], v10, s[2:3] offset:-2816 nt
	global_load_dwordx4 v[116:119], v10, s[2:3] offset:2816 nt
	v_pk_fma_f32 v[136:137], v[32:33], v[152:153], v[236:237]
	v_pk_fma_f32 v[196:197], v[40:41], v[212:213], v[244:245]
	v_pk_fma_f32 v[138:139], v[34:35], v[154:155], v[238:239]
	v_pk_fma_f32 v[198:199], v[42:43], v[214:215], v[246:247]
	v_pk_fma_f32 v[140:141], v[36:37], v[156:157], v[240:241]
	v_pk_fma_f32 v[200:201], v[44:45], v[216:217], v[248:249]
	v_pk_fma_f32 v[142:143], v[38:39], v[158:159], v[242:243]
	v_pk_fma_f32 v[202:203], v[46:47], v[218:219], v[250:251]
	v_pk_fma_f32 v[136:137], v[48:49], v[160:161], v[136:137]
	v_pk_fma_f32 v[196:197], v[56:57], v[220:221], v[196:197]
	v_pk_fma_f32 v[138:139], v[50:51], v[162:163], v[138:139]
	v_pk_fma_f32 v[198:199], v[58:59], v[222:223], v[198:199]
	v_pk_fma_f32 v[140:141], v[52:53], v[164:165], v[140:141]
	v_pk_fma_f32 v[200:201], v[60:61], v[224:225], v[200:201]
	v_pk_fma_f32 v[142:143], v[54:55], v[166:167], v[142:143]
	v_pk_fma_f32 v[202:203], v[62:63], v[226:227], v[202:203]
	v_pk_fma_f32 v[136:137], v[16:17], v[168:169], v[136:137]
	v_pk_fma_f32 v[196:197], v[24:25], v[228:229], v[196:197]
	v_pk_fma_f32 v[138:139], v[18:19], v[170:171], v[138:139]
	v_pk_fma_f32 v[198:199], v[26:27], v[230:231], v[198:199]
	v_pk_fma_f32 v[140:141], v[20:21], v[172:173], v[140:141]
	v_pk_fma_f32 v[200:201], v[28:29], v[232:233], v[200:201]
	v_pk_fma_f32 v[142:143], v[22:23], v[174:175], v[142:143]
	v_pk_fma_f32 v[202:203], v[30:31], v[234:235], v[202:203]
	v_pk_mul_f32 v[184:185], v[136:137], v[180:181]
; __device__ __forceinline__ unsigned cvt_pk_bf16(float lo, float hi) { unsigned r; asm volatile("v_cvt_pk_bf16_f32 %0, %1, %2" : "=v"(r) : "v"(lo), "v"(hi)); return r; }
; __device__ __forceinline__ float silu_f(float x) { return x * __builtin_amdgcn_rcpf(1.0f + __builtin_amdgcn_exp2f(-LOG2E * x)); }
; __device__ __forceinline__ float bflo(unsigned w) { return __uint_as_float(w << 16); }
; __device__ __forceinline__ float bfhi(unsigned w) { return __uint_as_float(w & 0xffff0000u); }
; __device__ __forceinline__ void conv_phase(const bf16_t* Z, bf16_t* UA, const float* cw, const float* cb, int nrows, int rowoff) {
;     ...
;         for (int rr = 0; rr < 16; ++rr) {
;             u32x4 na = zero, ng = zero; if (rr < 15 || has_right) { na = *(const u32x4*)(zp + (size_t)(rr + 1) * FFN2); ng = *(const u32x4*)(zp + (size_t)(rr + 1) * FFN2 + FFN); }
;             u32x4 o;
; #pragma unroll
;             for (int e2 = 0; e2 < 4; ++e2) {
;                 const float a0 = bflo(pa[e2]) * wa[0][2 * e2] + bflo(ca[e2]) * wa[1][2 * e2] + bflo(na[e2]) * wa[2][2 * e2] + ba[2 * e2];
;                 const float a1 = bfhi(pa[e2]) * wa[0][2 * e2 + 1] + bfhi(ca[e2]) * wa[1][2 * e2 + 1] + bfhi(na[e2]) * wa[2][2 * e2 + 1] + ba[2 * e2 + 1];
;                 const float g0 = bflo(pg[e2]) * wg[0][2 * e2] + bflo(cgv[e2]) * wg[1][2 * e2] + bflo(ng[e2]) * wg[2][2 * e2] + bg[2 * e2];
;                 const float g1 = bfhi(pg[e2]) * wg[0][2 * e2 + 1] + bfhi(cgv[e2]) * wg[1][2 * e2 + 1] + bfhi(ng[e2]) * wg[2][2 * e2 + 1] + bg[2 * e2 + 1];
;                 o[e2] = cvt_pk_bf16(silu_f(a0) * g0, silu_f(a1) * g1); }
;             *(u32x4*)(UA + (size_t)(r0 + rr) * FFN + c0) = o;
;             pa = ca; pg = cgv; ca = na; cgv = ng;
;         }
	v_pk_mul_f32 v[186:187], v[138:139], v[180:181]
	v_pk_mul_f32 v[188:189], v[140:141], v[180:181]
	v_pk_mul_f32 v[190:191], v[142:143], v[180:181]
	v_exp_f32_e32 v184, v184
	v_exp_f32_e32 v185, v185
	v_exp_f32_e32 v186, v186
	v_exp_f32_e32 v187, v187
	v_exp_f32_e32 v188, v188
	v_exp_f32_e32 v189, v189
	v_exp_f32_e32 v190, v190
	v_exp_f32_e32 v191, v191
	s_nop 0
	v_pk_add_f32 v[184:185], v[184:185], v[144:145]
	v_pk_add_f32 v[186:187], v[186:187], v[144:145]
	v_pk_add_f32 v[188:189], v[188:189], v[144:145]
	v_pk_add_f32 v[190:191], v[190:191], v[144:145]
	v_rcp_f32_e32 v184, v184
	v_rcp_f32_e32 v185, v185
	v_rcp_f32_e32 v186, v186
	v_rcp_f32_e32 v187, v187
	v_rcp_f32_e32 v188, v188
	v_rcp_f32_e32 v189, v189
	v_rcp_f32_e32 v190, v190
	v_rcp_f32_e32 v191, v191
	s_nop 0
	v_pk_mul_f32 v[136:137], v[136:137], v[184:185]
	v_pk_mul_f32 v[138:139], v[138:139], v[186:187]
	v_pk_mul_f32 v[140:141], v[140:141], v[188:189]
	v_pk_mul_f32 v[142:143], v[142:143], v[190:191]
	v_pk_mul_f32 v[136:137], v[136:137], v[196:197]
	v_pk_mul_f32 v[138:139], v[138:139], v[198:199]
	v_pk_mul_f32 v[140:141], v[140:141], v[200:201]
	v_pk_mul_f32 v[142:143], v[142:143], v[202:203]
	v_cvt_pk_bf16_f32 v12, v136, v137
	v_cvt_pk_bf16_f32 v13, v138, v139
	v_cvt_pk_bf16_f32 v14, v140, v141
	v_cvt_pk_bf16_f32 v15, v142, v143
	global_store_dwordx4 v6, v[12:15], s[30:31]
	v_add_u32_e32 v6, 5632, v6
	s_waitcnt vmcnt(25)
	v_lshlrev_b32_e32 v32, 16, v120
	v_and_b32_e32 v33, s99, v120
	v_lshlrev_b32_e32 v34, 16, v121
	v_and_b32_e32 v35, s99, v121
	v_lshlrev_b32_e32 v36, 16, v122
	v_and_b32_e32 v37, s99, v122
	v_lshlrev_b32_e32 v38, 16, v123
	v_and_b32_e32 v39, s99, v123
	v_lshlrev_b32_e32 v40, 16, v124
	v_and_b32_e32 v41, s99, v124
	v_lshlrev_b32_e32 v42, 16, v125
	v_and_b32_e32 v43, s99, v125
	v_lshlrev_b32_e32 v44, 16, v126
	v_and_b32_e32 v45, s99, v126
	v_lshlrev_b32_e32 v46, 16, v127
	v_and_b32_e32 v47, s99, v127
	v_add_u32_e32 v11, 67130112, v5
	global_load_dwordx4 v[120:123], v11, s[2:3] offset:-2816 nt
	global_load_dwordx4 v[124:127], v11, s[2:3] offset:2816 nt
	v_pk_fma_f32 v[136:137], v[48:49], v[152:153], v[236:237]
	v_pk_fma_f32 v[196:197], v[56:57], v[212:213], v[244:245]
	v_pk_fma_f32 v[138:139], v[50:51], v[154:155], v[238:239]
	v_pk_fma_f32 v[198:199], v[58:59], v[214:215], v[246:247]
	v_pk_fma_f32 v[140:141], v[52:53], v[156:157], v[240:241]
	v_pk_fma_f32 v[200:201], v[60:61], v[216:217], v[248:249]
	v_pk_fma_f32 v[142:143], v[54:55], v[158:159], v[242:243]
	v_pk_fma_f32 v[202:203], v[62:63], v[218:219], v[250:251]
	v_pk_fma_f32 v[136:137], v[16:17], v[160:161], v[136:137]
	v_pk_fma_f32 v[196:197], v[24:25], v[220:221], v[196:197]
	v_pk_fma_f32 v[138:139], v[18:19], v[162:163], v[138:139]
	v_pk_fma_f32 v[198:199], v[26:27], v[222:223], v[198:199]
	v_pk_fma_f32 v[140:141], v[20:21], v[164:165], v[140:141]
	v_pk_fma_f32 v[200:201], v[28:29], v[224:225], v[200:201]
	v_pk_fma_f32 v[142:143], v[22:23], v[166:167], v[142:143]
	v_pk_fma_f32 v[202:203], v[30:31], v[226:227], v[202:203]
	v_pk_fma_f32 v[136:137], v[32:33], v[168:169], v[136:137]
	v_pk_fma_f32 v[196:197], v[40:41], v[228:229], v[196:197]
	v_pk_fma_f32 v[138:139], v[34:35], v[170:171], v[138:139]
	v_pk_fma_f32 v[198:199], v[42:43], v[230:231], v[198:199]
	v_pk_fma_f32 v[140:141], v[36:37], v[172:173], v[140:141]
	v_pk_fma_f32 v[200:201], v[44:45], v[232:233], v[200:201]
	v_pk_fma_f32 v[142:143], v[38:39], v[174:175], v[142:143]
	v_pk_fma_f32 v[202:203], v[46:47], v[234:235], v[202:203]
	v_pk_mul_f32 v[184:185], v[136:137], v[180:181]
	v_pk_mul_f32 v[186:187], v[138:139], v[180:181]
	v_pk_mul_f32 v[188:189], v[140:141], v[180:181]
	v_pk_mul_f32 v[190:191], v[142:143], v[180:181]
	v_exp_f32_e32 v184, v184
	v_exp_f32_e32 v185, v185
	v_exp_f32_e32 v186, v186
	v_exp_f32_e32 v187, v187
	v_exp_f32_e32 v188, v188
	v_exp_f32_e32 v189, v189
	v_exp_f32_e32 v190, v190
	v_exp_f32_e32 v191, v191
	s_nop 0
	v_pk_add_f32 v[184:185], v[184:185], v[144:145]
	v_pk_add_f32 v[186:187], v[186:187], v[144:145]
	v_pk_add_f32 v[188:189], v[188:189], v[144:145]
	v_pk_add_f32 v[190:191], v[190:191], v[144:145]
	v_rcp_f32_e32 v184, v184
	v_rcp_f32_e32 v185, v185
	v_rcp_f32_e32 v186, v186
	v_rcp_f32_e32 v187, v187
	v_rcp_f32_e32 v188, v188
	v_rcp_f32_e32 v189, v189
	v_rcp_f32_e32 v190, v190
	v_rcp_f32_e32 v191, v191
	s_nop 0
	v_pk_mul_f32 v[136:137], v[136:137], v[184:185]
	v_pk_mul_f32 v[138:139], v[138:139], v[186:187]
	v_pk_mul_f32 v[140:141], v[140:141], v[188:189]
	v_pk_mul_f32 v[142:143], v[142:143], v[190:191]
	v_pk_mul_f32 v[136:137], v[136:137], v[196:197]
	v_pk_mul_f32 v[138:139], v[138:139], v[198:199]
	v_pk_mul_f32 v[140:141], v[140:141], v[200:201]
	v_pk_mul_f32 v[142:143], v[142:143], v[202:203]
	v_cvt_pk_bf16_f32 v12, v136, v137
	v_cvt_pk_bf16_f32 v13, v138, v139
	v_cvt_pk_bf16_f32 v14, v140, v141
	v_cvt_pk_bf16_f32 v15, v142, v143
	global_store_dwordx4 v6, v[12:15], s[30:31]
	v_add_u32_e32 v6, 5632, v6
	s_waitcnt vmcnt(25)
; __device__ __forceinline__ unsigned cvt_pk_bf16(float lo, float hi) { unsigned r; asm volatile("v_cvt_pk_bf16_f32 %0, %1, %2" : "=v"(r) : "v"(lo), "v"(hi)); return r; }
; __device__ __forceinline__ float silu_f(float x) { return x * __builtin_amdgcn_rcpf(1.0f + __builtin_amdgcn_exp2f(-LOG2E * x)); }
; __device__ __forceinline__ float bflo(unsigned w) { return __uint_as_float(w << 16); }
; __device__ __forceinline__ float bfhi(unsigned w) { return __uint_as_float(w & 0xffff0000u); }
; __device__ __forceinline__ void conv_phase(const bf16_t* Z, bf16_t* UA, const float* cw, const float* cb, int nrows, int rowoff) {
;     ...
;     for (int idx = gtid; idx < total; idx += NT) {
;         const int cgp = idx % 352, rb = idx / 352, c0 = cgp * 8, r0 = rb * 16, grow0 = rowoff + r0;
;     ...
;         for (int rr = 0; rr < 16; ++rr) {
;             u32x4 na = zero, ng = zero; if (rr < 15 || has_right) { na = *(const u32x4*)(zp + (size_t)(rr + 1) * FFN2); ng = *(const u32x4*)(zp + (size_t)(rr + 1) * FFN2 + FFN); }
;             u32x4 o;
; #pragma unroll
;             for (int e2 = 0; e2 < 4; ++e2) {
;                 const float a0 = bflo(pa[e2]) * wa[0][2 * e2] + bflo(ca[e2]) * wa[1][2 * e2] + bflo(na[e2]) * wa[2][2 * e2] + ba[2 * e2];
;                 const float a1 = bfhi(pa[e2]) * wa[0][2 * e2 + 1] + bfhi(ca[e2]) * wa[1][2 * e2 + 1] + bfhi(na[e2]) * wa[2][2 * e2 + 1] + ba[2 * e2 + 1];
;                 const float g0 = bflo(pg[e2]) * wg[0][2 * e2] + bflo(cgv[e2]) * wg[1][2 * e2] + bflo(ng[e2]) * wg[2][2 * e2] + bg[2 * e2];
;                 const float g1 = bfhi(pg[e2]) * wg[0][2 * e2 + 1] + bfhi(cgv[e2]) * wg[1][2 * e2 + 1] + bfhi(ng[e2]) * wg[2][2 * e2 + 1] + bg[2 * e2 + 1];
;                 o[e2] = cvt_pk_bf16(silu_f(a0) * g0, silu_f(a1) * g1); }
;             *(u32x4*)(UA + (size_t)(r0 + rr) * FFN + c0) = o;
;             pa = ca; pg = cgv; ca = na; cgv = ng;
;         }
	v_cndmask_b32_e64 v128, 0, v128, s[100:101]
	v_cndmask_b32_e64 v129, 0, v129, s[100:101]
	v_cndmask_b32_e64 v130, 0, v130, s[100:101]
	v_cndmask_b32_e64 v131, 0, v131, s[100:101]
	v_cndmask_b32_e64 v132, 0, v132, s[100:101]
	v_cndmask_b32_e64 v133, 0, v133, s[100:101]
	v_cndmask_b32_e64 v134, 0, v134, s[100:101]
	v_cndmask_b32_e64 v135, 0, v135, s[100:101]
	v_lshlrev_b32_e32 v48, 16, v128
	v_and_b32_e32 v49, s99, v128
	v_lshlrev_b32_e32 v50, 16, v129
	v_and_b32_e32 v51, s99, v129
	v_lshlrev_b32_e32 v52, 16, v130
	v_and_b32_e32 v53, s99, v130
	v_lshlrev_b32_e32 v54, 16, v131
	v_and_b32_e32 v55, s99, v131
	v_lshlrev_b32_e32 v56, 16, v132
	v_and_b32_e32 v57, s99, v132
	v_lshlrev_b32_e32 v58, 16, v133
	v_and_b32_e32 v59, s99, v133
	v_lshlrev_b32_e32 v60, 16, v134
	v_and_b32_e32 v61, s99, v134
	v_lshlrev_b32_e32 v62, 16, v135
	v_and_b32_e32 v63, s99, v135
	v_add_u32_e32 v10, 67141376, v5
	global_load_dwordx4 v[128:131], v10, s[2:3] offset:-2816 nt
	global_load_dwordx4 v[132:135], v10, s[2:3] offset:2816 nt
	v_pk_fma_f32 v[136:137], v[16:17], v[152:153], v[236:237]
	v_pk_fma_f32 v[196:197], v[24:25], v[212:213], v[244:245]
	v_pk_fma_f32 v[138:139], v[18:19], v[154:155], v[238:239]
	v_pk_fma_f32 v[198:199], v[26:27], v[214:215], v[246:247]
	v_pk_fma_f32 v[140:141], v[20:21], v[156:157], v[240:241]
	v_pk_fma_f32 v[200:201], v[28:29], v[216:217], v[248:249]
	v_pk_fma_f32 v[142:143], v[22:23], v[158:159], v[242:243]
	v_pk_fma_f32 v[202:203], v[30:31], v[218:219], v[250:251]
	v_pk_fma_f32 v[136:137], v[32:33], v[160:161], v[136:137]
	v_pk_fma_f32 v[196:197], v[40:41], v[220:221], v[196:197]
	v_pk_fma_f32 v[138:139], v[34:35], v[162:163], v[138:139]
	v_pk_fma_f32 v[198:199], v[42:43], v[222:223], v[198:199]
	v_pk_fma_f32 v[140:141], v[36:37], v[164:165], v[140:141]
	v_pk_fma_f32 v[200:201], v[44:45], v[224:225], v[200:201]
	v_pk_fma_f32 v[142:143], v[38:39], v[166:167], v[142:143]
	v_pk_fma_f32 v[202:203], v[46:47], v[226:227], v[202:203]
	v_pk_fma_f32 v[136:137], v[48:49], v[168:169], v[136:137]
	v_pk_fma_f32 v[196:197], v[56:57], v[228:229], v[196:197]
	v_pk_fma_f32 v[138:139], v[50:51], v[170:171], v[138:139]
	v_pk_fma_f32 v[198:199], v[58:59], v[230:231], v[198:199]
	v_pk_fma_f32 v[140:141], v[52:53], v[172:173], v[140:141]
	v_pk_fma_f32 v[200:201], v[60:61], v[232:233], v[200:201]
	v_pk_fma_f32 v[142:143], v[54:55], v[174:175], v[142:143]
	v_pk_fma_f32 v[202:203], v[62:63], v[234:235], v[202:203]
	v_pk_mul_f32 v[184:185], v[136:137], v[180:181]
	v_pk_mul_f32 v[186:187], v[138:139], v[180:181]
	v_pk_mul_f32 v[188:189], v[140:141], v[180:181]
	v_pk_mul_f32 v[190:191], v[142:143], v[180:181]
	v_exp_f32_e32 v184, v184
	v_exp_f32_e32 v185, v185
	v_exp_f32_e32 v186, v186
	v_exp_f32_e32 v187, v187
	v_exp_f32_e32 v188, v188
	v_exp_f32_e32 v189, v189
	v_exp_f32_e32 v190, v190
	v_exp_f32_e32 v191, v191
	s_nop 0
	v_pk_add_f32 v[184:185], v[184:185], v[144:145]
	v_pk_add_f32 v[186:187], v[186:187], v[144:145]
	v_pk_add_f32 v[188:189], v[188:189], v[144:145]
	v_pk_add_f32 v[190:191], v[190:191], v[144:145]
	v_rcp_f32_e32 v184, v184
	v_rcp_f32_e32 v185, v185
	v_rcp_f32_e32 v186, v186
	v_rcp_f32_e32 v187, v187
	v_rcp_f32_e32 v188, v188
	v_rcp_f32_e32 v189, v189
	v_rcp_f32_e32 v190, v190
	v_rcp_f32_e32 v191, v191
	s_nop 0
	v_pk_mul_f32 v[136:137], v[136:137], v[184:185]
	v_pk_mul_f32 v[138:139], v[138:139], v[186:187]
	v_pk_mul_f32 v[140:141], v[140:141], v[188:189]
	v_pk_mul_f32 v[142:143], v[142:143], v[190:191]
	v_pk_mul_f32 v[136:137], v[136:137], v[196:197]
	v_pk_mul_f32 v[138:139], v[138:139], v[198:199]
	v_pk_mul_f32 v[140:141], v[140:141], v[200:201]
	v_pk_mul_f32 v[142:143], v[142:143], v[202:203]
	v_cvt_pk_bf16_f32 v12, v136, v137
	v_cvt_pk_bf16_f32 v13, v138, v139
	v_cvt_pk_bf16_f32 v14, v140, v141
	v_cvt_pk_bf16_f32 v15, v142, v143
	global_store_dwordx4 v6, v[12:15], s[30:31]
	v_add_u32_e32 v5, 67043328, v5
	v_add_u32_e32 v6, 33437184, v6
	v_add_u32_e32 v7, 372, v7
	v_add_u32_e32 v2, 372, v2
	s_add_u32 s98, s98, 1
	s_cmp_lt_u32 s98, 6
	s_cbranch_scc1 .Lconv_item_l1
